# baseline (speedup 1.0000x reference)
; #define PG8_STAGE(bufoff, gbase, voff) do { _Pragma("unroll") for (int _i = 0; _i < 2; ++_i) \
;         __builtin_amdgcn_global_load_lds((const unsigned*)((const char*)(gbase) + (voff)[_i]), (PG8_LAS unsigned*)(lds + (bufoff) + ldsw + _i * 8192), 16, 0, 0); } while (0)
; #define PG8_LDA(dst, b, h) do { _Pragma("unroll") for (int m = 0; m < 4; ++m) _Pragma("unroll") for (int k = 0; k < 2; ++k) dst[m][k] = *(const PG8_LAS bf16x8*)(lds + PG8_SA(b, h) + aoff + m * 2048 + k * 1024); } while (0)
; #define PG8_LDB(dst, b, h) do { _Pragma("unroll") for (int n = 0; n < 2; ++n) _Pragma("unroll") for (int k = 0; k < 2; ++k) dst[n][k] = *(const PG8_LAS bf16x8*)(lds + PG8_SB(b, h) + boff + n * 2048 + k * 1024); } while (0)
; #define PG8_MMA(ai, bj, At, Bt) do { __builtin_amdgcn_s_setprio(1); _Pragma("unroll") for (int m = 0; m < 4; ++m) _Pragma("unroll") for (int n = 0; n < 2; ++n) _Pragma("unroll") for (int k = 0; k < 2; ++k) \
;         acc[ai][bj][m][n] = __builtin_amdgcn_mfma_f32_16x16x32_bf16(Bt[n][k], At[m][k], acc[ai][bj][m][n], 0, 0, 0); __builtin_amdgcn_s_setprio(0); } while (0)
; #define PG8_WAIT_V(n) asm volatile("s_waitcnt vmcnt(" #n ")" ::: "memory")
; #define PG8_WAIT_L(n) asm volatile("s_waitcnt lgkmcnt(" #n ")" ::: "memory")
; #define PG8_BAR __builtin_amdgcn_s_barrier()
; #define PG8_SCHED __builtin_amdgcn_sched_barrier(0)
; template <class Epi, class Sched, bool ALIGN_EPI = false, bool SP2 = false>
; __device__ __forceinline__ void gemm_phase(PG8_LAS unsigned char* lds, const Gemm g, const Sched& S, const Epi& E) {
;     ...
;             PG8_LDB(B0, 0, 0); PG8_LDB(B1, 0, 1); PG8_SCHED; PG8_LDA(At, 0, 0); PG8_STAGE(PG8_SA(1, 1), a1 + hstepA, voffA);
;             PG8_WAIT_V(8); PG8_WAIT_L(0); PG8_BAR; PG8_MMA(0, 0, At, B0); PG8_MMA(0, 1, At, B1); PG8_BAR; PG8_SCHED;
;             PG8_LDA(At, 0, 1); PG8_STAGE(PG8_SB(0, 0), b2, voffB); PG8_STAGE(PG8_SB(0, 1), b2 + hstepB, voffB); PG8_STAGE(PG8_SA(0, 0), a2, voffA);
;             PG8_WAIT_V(8); PG8_WAIT_L(0); PG8_BAR; PG8_MMA(1, 0, At, B0); PG8_MMA(1, 1, At, B1); PG8_BAR; PG8_SCHED;
.LBB0_278:
	ds_read_b128 v[128:131], v166
	ds_read_b128 v[132:135], v166 offset:1024
	ds_read_b128 v[156:159], v166 offset:2048
	ds_read_b128 v[170:173], v166 offset:3072
	ds_read_b128 v[174:177], v167
	ds_read_b128 v[178:181], v167 offset:1024
	ds_read_b128 v[182:185], v167 offset:2048
	ds_read_b128 v[186:189], v167 offset:3072
	s_add_u32 s6, s62, 0xfff80080
	s_addc_u32 s7, s63, -1
	s_cmp_eq_u32 s96, 28
	s_cselect_b32 s71, s41, s7
	s_cselect_b32 s70, s59, s6
	s_cselect_b32 s65, s39, s95
	s_cselect_b32 s64, s69, s94
	v_lshl_add_u64 v[160:161], s[62:63], 0, v[148:149]
	s_add_i32 m0, s75, 0xc000
	ds_read_b128 v[190:193], v168
	ds_read_b128 v[194:197], v168 offset:1024
	ds_read_b128 v[198:201], v168 offset:2048
	ds_read_b128 v[202:205], v168 offset:3072
	ds_read_b128 v[206:209], v168 offset:4096
	ds_read_b128 v[210:213], v168 offset:5120
	ds_read_b128 v[214:217], v168 offset:6144
	ds_read_b128 v[218:221], v168 offset:7168
	global_load_lds_dwordx4 v[160:161], off
	v_lshl_add_u64 v[160:161], s[62:63], 0, v[150:151]
	s_add_i32 m0, s75, 0xe000
	s_nop 0
	global_load_lds_dwordx4 v[160:161], off
	s_waitcnt vmcnt(8)
	s_waitcnt lgkmcnt(0)
	s_barrier
	s_waitcnt lgkmcnt(0)
	v_mfma_f32_16x16x32_bf16 v[124:127], v[128:131], v[190:193], v[124:127]
	v_mfma_f32_16x16x32_bf16 v[120:123], v[156:159], v[190:193], v[120:123]
	v_mfma_f32_16x16x32_bf16 v[108:111], v[128:131], v[198:201], v[108:111]
	v_mfma_f32_16x16x32_bf16 v[104:107], v[156:159], v[198:201], v[104:107]
	v_mfma_f32_16x16x32_bf16 v[92:95], v[128:131], v[206:209], v[92:95]
	v_mfma_f32_16x16x32_bf16 v[88:91], v[156:159], v[206:209], v[88:91]
	v_mfma_f32_16x16x32_bf16 v[76:79], v[128:131], v[214:217], v[76:79]
	v_mfma_f32_16x16x32_bf16 v[72:75], v[156:159], v[214:217], v[72:75]
	v_mfma_f32_16x16x32_bf16 v[124:127], v[132:135], v[194:197], v[124:127]
	v_mfma_f32_16x16x32_bf16 v[120:123], v[170:173], v[194:197], v[120:123]
	v_mfma_f32_16x16x32_bf16 v[108:111], v[132:135], v[202:205], v[108:111]
	v_mfma_f32_16x16x32_bf16 v[104:107], v[170:173], v[202:205], v[104:107]
	v_mfma_f32_16x16x32_bf16 v[92:95], v[132:135], v[210:213], v[92:95]
	v_mfma_f32_16x16x32_bf16 v[88:91], v[170:173], v[210:213], v[88:91]
	v_mfma_f32_16x16x32_bf16 v[76:79], v[132:135], v[218:221], v[76:79]
	v_mfma_f32_16x16x32_bf16 v[72:75], v[170:173], v[218:221], v[72:75]
	v_mfma_f32_16x16x32_bf16 v[116:119], v[174:177], v[190:193], v[116:119]
	v_mfma_f32_16x16x32_bf16 v[112:115], v[182:185], v[190:193], v[112:115]
	v_mfma_f32_16x16x32_bf16 v[100:103], v[174:177], v[198:201], v[100:103]
	v_mfma_f32_16x16x32_bf16 v[96:99], v[182:185], v[198:201], v[96:99]
	v_mfma_f32_16x16x32_bf16 v[84:87], v[174:177], v[206:209], v[84:87]
	v_mfma_f32_16x16x32_bf16 v[80:83], v[182:185], v[206:209], v[80:83]
	v_mfma_f32_16x16x32_bf16 v[68:71], v[174:177], v[214:217], v[68:71]
	v_mfma_f32_16x16x32_bf16 v[64:67], v[182:185], v[214:217], v[64:67]
	v_mfma_f32_16x16x32_bf16 v[116:119], v[178:181], v[194:197], v[116:119]
	v_mfma_f32_16x16x32_bf16 v[112:115], v[186:189], v[194:197], v[112:115]
	v_mfma_f32_16x16x32_bf16 v[100:103], v[178:181], v[202:205], v[100:103]
	v_mfma_f32_16x16x32_bf16 v[96:99], v[186:189], v[202:205], v[96:99]
	v_mfma_f32_16x16x32_bf16 v[84:87], v[178:181], v[210:213], v[84:87]
	v_mfma_f32_16x16x32_bf16 v[80:83], v[186:189], v[210:213], v[80:83]
	v_mfma_f32_16x16x32_bf16 v[68:71], v[178:181], v[218:221], v[68:71]
	v_mfma_f32_16x16x32_bf16 v[64:67], v[186:189], v[218:221], v[64:67]
	s_barrier
	s_add_i32 s6, s89, s74
	v_lshl_add_u64 v[160:161], s[64:65], 0, v[138:139]
	s_mov_b32 m0, s6
	ds_read_b128 v[190:193], v168 offset:16384
	ds_read_b128 v[194:197], v168 offset:17408
	ds_read_b128 v[198:201], v168 offset:18432
	ds_read_b128 v[202:205], v168 offset:19456
	ds_read_b128 v[206:209], v168 offset:20480
	ds_read_b128 v[210:213], v168 offset:21504
	ds_read_b128 v[214:217], v168 offset:22528
	ds_read_b128 v[218:221], v168 offset:23552
	global_load_lds_dwordx4 v[160:161], off
	s_add_i32 m0, s6, 0x2000
	s_add_u32 vcc_lo, s64, 0x80000
	v_lshl_add_u64 v[222:223], s[64:65], 0, v[142:143]
	s_addc_u32 vcc_hi, s65, 0
	s_add_i32 s6, s90, s74
	global_load_lds_dwordx4 v[222:223], off
	v_lshl_add_u64 v[224:225], vcc, 0, v[138:139]
	s_mov_b32 m0, s6
	v_lshl_add_u64 v[226:227], s[70:71], 0, v[140:141]
	global_load_lds_dwordx4 v[224:225], off
	v_lshl_add_u64 v[224:225], vcc, 0, v[142:143]
	s_add_i32 m0, s6, 0x2000
	s_nop 0
	global_load_lds_dwordx4 v[224:225], off
	v_lshl_add_u64 v[224:225], s[70:71], 0, v[136:137]
	s_mov_b32 m0, s75
	s_nop 0
	global_load_lds_dwordx4 v[224:225], off
	s_mov_b32 m0, s76
	s_nop 0
	global_load_lds_dwordx4 v[226:227], off
	s_waitcnt vmcnt(8)
	s_waitcnt lgkmcnt(0)
	s_barrier
; #define PG8_STAGE(bufoff, gbase, voff) do { _Pragma("unroll") for (int _i = 0; _i < 2; ++_i) \
;         __builtin_amdgcn_global_load_lds((const unsigned*)((const char*)(gbase) + (voff)[_i]), (PG8_LAS unsigned*)(lds + (bufoff) + ldsw + _i * 8192), 16, 0, 0); } while (0)
; #define PG8_LDA(dst, b, h) do { _Pragma("unroll") for (int m = 0; m < 4; ++m) _Pragma("unroll") for (int k = 0; k < 2; ++k) dst[m][k] = *(const PG8_LAS bf16x8*)(lds + PG8_SA(b, h) + aoff + m * 2048 + k * 1024); } while (0)
; #define PG8_LDB(dst, b, h) do { _Pragma("unroll") for (int n = 0; n < 2; ++n) _Pragma("unroll") for (int k = 0; k < 2; ++k) dst[n][k] = *(const PG8_LAS bf16x8*)(lds + PG8_SB(b, h) + boff + n * 2048 + k * 1024); } while (0)
; #define PG8_MMA(ai, bj, At, Bt) do { __builtin_amdgcn_s_setprio(1); _Pragma("unroll") for (int m = 0; m < 4; ++m) _Pragma("unroll") for (int n = 0; n < 2; ++n) _Pragma("unroll") for (int k = 0; k < 2; ++k) \
;         acc[ai][bj][m][n] = __builtin_amdgcn_mfma_f32_16x16x32_bf16(Bt[n][k], At[m][k], acc[ai][bj][m][n], 0, 0, 0); __builtin_amdgcn_s_setprio(0); } while (0)
; #define PG8_WAIT_V(n) asm volatile("s_waitcnt vmcnt(" #n ")" ::: "memory")
; #define PG8_WAIT_L(n) asm volatile("s_waitcnt lgkmcnt(" #n ")" ::: "memory")
; #define PG8_BAR __builtin_amdgcn_s_barrier()
; #define PG8_SCHED __builtin_amdgcn_sched_barrier(0)
; template <class Epi, class Sched, bool ALIGN_EPI = false, bool SP2 = false>
; __device__ __forceinline__ void gemm_phase(PG8_LAS unsigned char* lds, const Gemm g, const Sched& S, const Epi& E) {
;     ...
;             PG8_WAIT_V(8); PG8_WAIT_L(0); PG8_BAR; PG8_MMA(1, 0, At, B0); PG8_MMA(1, 1, At, B1); PG8_BAR; PG8_SCHED;
;             PG8_LDB(B0, 1, 0); PG8_LDB(B1, 1, 1); PG8_SCHED; PG8_LDA(At, 1, 0); PG8_STAGE(PG8_SA(0, 1), a2 + hstepA, voffA);
;             PG8_WAIT_V(8); PG8_WAIT_L(0); PG8_BAR; PG8_MMA(0, 0, At, B0); PG8_MMA(0, 1, At, B1); PG8_BAR; PG8_SCHED;
	s_waitcnt lgkmcnt(0)
	v_mfma_f32_16x16x32_bf16 v[60:63], v[128:131], v[190:193], v[60:63]
	v_mfma_f32_16x16x32_bf16 v[56:59], v[156:159], v[190:193], v[56:59]
	v_mfma_f32_16x16x32_bf16 v[44:47], v[128:131], v[198:201], v[44:47]
	v_mfma_f32_16x16x32_bf16 v[40:43], v[156:159], v[198:201], v[40:43]
	v_mfma_f32_16x16x32_bf16 v[28:31], v[128:131], v[206:209], v[28:31]
	v_mfma_f32_16x16x32_bf16 v[24:27], v[156:159], v[206:209], v[24:27]
	v_mfma_f32_16x16x32_bf16 v[12:15], v[128:131], v[214:217], v[12:15]
	v_mfma_f32_16x16x32_bf16 v[8:11], v[156:159], v[214:217], v[8:11]
	v_mfma_f32_16x16x32_bf16 v[60:63], v[132:135], v[194:197], v[60:63]
	v_mfma_f32_16x16x32_bf16 v[56:59], v[170:173], v[194:197], v[56:59]
	v_mfma_f32_16x16x32_bf16 v[44:47], v[132:135], v[202:205], v[44:47]
	v_mfma_f32_16x16x32_bf16 v[40:43], v[170:173], v[202:205], v[40:43]
	v_mfma_f32_16x16x32_bf16 v[28:31], v[132:135], v[210:213], v[28:31]
	v_mfma_f32_16x16x32_bf16 v[24:27], v[170:173], v[210:213], v[24:27]
	v_mfma_f32_16x16x32_bf16 v[12:15], v[132:135], v[218:221], v[12:15]
	v_mfma_f32_16x16x32_bf16 v[8:11], v[170:173], v[218:221], v[8:11]
	v_mfma_f32_16x16x32_bf16 v[52:55], v[174:177], v[190:193], v[52:55]
	v_mfma_f32_16x16x32_bf16 v[48:51], v[182:185], v[190:193], v[48:51]
	v_mfma_f32_16x16x32_bf16 v[36:39], v[174:177], v[198:201], v[36:39]
	v_mfma_f32_16x16x32_bf16 v[32:35], v[182:185], v[198:201], v[32:35]
	v_mfma_f32_16x16x32_bf16 v[20:23], v[174:177], v[206:209], v[20:23]
	v_mfma_f32_16x16x32_bf16 v[16:19], v[182:185], v[206:209], v[16:19]
	v_mfma_f32_16x16x32_bf16 v[4:7], v[174:177], v[214:217], v[4:7]
	v_mfma_f32_16x16x32_bf16 v[0:3], v[182:185], v[214:217], v[0:3]
	v_mfma_f32_16x16x32_bf16 v[52:55], v[178:181], v[194:197], v[52:55]
	v_mfma_f32_16x16x32_bf16 v[48:51], v[186:189], v[194:197], v[48:51]
	v_mfma_f32_16x16x32_bf16 v[36:39], v[178:181], v[202:205], v[36:39]
	v_mfma_f32_16x16x32_bf16 v[32:35], v[186:189], v[202:205], v[32:35]
	v_mfma_f32_16x16x32_bf16 v[20:23], v[178:181], v[210:213], v[20:23]
	v_mfma_f32_16x16x32_bf16 v[16:19], v[186:189], v[210:213], v[16:19]
	v_mfma_f32_16x16x32_bf16 v[4:7], v[178:181], v[218:221], v[4:7]
	v_mfma_f32_16x16x32_bf16 v[0:3], v[186:189], v[218:221], v[0:3]
	s_barrier
	s_add_i32 s6, 0, 0x18000
	v_add_u32_e32 v144, s6, v163
	s_add_i32 s7, 0, 0x1c000
	ds_read_b128 v[128:131], v144
	ds_read_b128 v[132:135], v144 offset:1024
	ds_read_b128 v[156:159], v144 offset:2048
	ds_read_b128 v[170:173], v144 offset:3072
	v_add_u32_e32 v144, s7, v163
	ds_read_b128 v[174:177], v144
	ds_read_b128 v[178:181], v144 offset:1024
	ds_read_b128 v[182:185], v144 offset:2048
	ds_read_b128 v[186:189], v144 offset:3072
	s_add_u32 s70, s70, 0x80000
	s_addc_u32 s71, s71, 0
	s_mov_b32 m0, s77
	v_lshl_add_u64 v[228:229], s[70:71], 0, v[136:137]
	ds_read_b128 v[190:193], v168 offset:32768
	ds_read_b128 v[194:197], v168 offset:33792
	ds_read_b128 v[198:201], v168 offset:34816
	ds_read_b128 v[202:205], v168 offset:35840
	ds_read_b128 v[206:209], v168 offset:36864
	ds_read_b128 v[210:213], v168 offset:37888
	ds_read_b128 v[214:217], v168 offset:38912
	ds_read_b128 v[218:221], v168 offset:39936
	global_load_lds_dwordx4 v[228:229], off
	v_lshl_add_u64 v[228:229], s[70:71], 0, v[140:141]
	s_mov_b32 m0, s78
	s_nop 0
	global_load_lds_dwordx4 v[228:229], off
	s_waitcnt vmcnt(8)
	s_waitcnt lgkmcnt(0)
	s_barrier
	s_waitcnt lgkmcnt(0)
	v_mfma_f32_16x16x32_bf16 v[124:127], v[128:131], v[190:193], v[124:127]
	v_mfma_f32_16x16x32_bf16 v[120:123], v[156:159], v[190:193], v[120:123]
	v_mfma_f32_16x16x32_bf16 v[108:111], v[128:131], v[198:201], v[108:111]
	v_mfma_f32_16x16x32_bf16 v[104:107], v[156:159], v[198:201], v[104:107]
	v_mfma_f32_16x16x32_bf16 v[92:95], v[128:131], v[206:209], v[92:95]
	v_mfma_f32_16x16x32_bf16 v[88:91], v[156:159], v[206:209], v[88:91]
	v_mfma_f32_16x16x32_bf16 v[76:79], v[128:131], v[214:217], v[76:79]
	v_mfma_f32_16x16x32_bf16 v[72:75], v[156:159], v[214:217], v[72:75]
	v_mfma_f32_16x16x32_bf16 v[124:127], v[132:135], v[194:197], v[124:127]
	v_mfma_f32_16x16x32_bf16 v[120:123], v[170:173], v[194:197], v[120:123]
	v_mfma_f32_16x16x32_bf16 v[108:111], v[132:135], v[202:205], v[108:111]
	v_mfma_f32_16x16x32_bf16 v[104:107], v[170:173], v[202:205], v[104:107]
	v_mfma_f32_16x16x32_bf16 v[92:95], v[132:135], v[210:213], v[92:95]
	v_mfma_f32_16x16x32_bf16 v[88:91], v[170:173], v[210:213], v[88:91]
	v_mfma_f32_16x16x32_bf16 v[76:79], v[132:135], v[218:221], v[76:79]
	v_mfma_f32_16x16x32_bf16 v[72:75], v[170:173], v[218:221], v[72:75]
	v_mfma_f32_16x16x32_bf16 v[116:119], v[174:177], v[190:193], v[116:119]
	v_mfma_f32_16x16x32_bf16 v[112:115], v[182:185], v[190:193], v[112:115]
	v_mfma_f32_16x16x32_bf16 v[100:103], v[174:177], v[198:201], v[100:103]
	v_mfma_f32_16x16x32_bf16 v[96:99], v[182:185], v[198:201], v[96:99]
	v_mfma_f32_16x16x32_bf16 v[84:87], v[174:177], v[206:209], v[84:87]
	v_mfma_f32_16x16x32_bf16 v[80:83], v[182:185], v[206:209], v[80:83]
	v_mfma_f32_16x16x32_bf16 v[68:71], v[174:177], v[214:217], v[68:71]
	v_mfma_f32_16x16x32_bf16 v[64:67], v[182:185], v[214:217], v[64:67]
	v_mfma_f32_16x16x32_bf16 v[116:119], v[178:181], v[194:197], v[116:119]
	v_mfma_f32_16x16x32_bf16 v[112:115], v[186:189], v[194:197], v[112:115]
	v_mfma_f32_16x16x32_bf16 v[100:103], v[178:181], v[202:205], v[100:103]
	v_mfma_f32_16x16x32_bf16 v[96:99], v[186:189], v[202:205], v[96:99]
	v_mfma_f32_16x16x32_bf16 v[84:87], v[178:181], v[210:213], v[84:87]
	v_mfma_f32_16x16x32_bf16 v[80:83], v[186:189], v[210:213], v[80:83]
	v_mfma_f32_16x16x32_bf16 v[68:71], v[178:181], v[218:221], v[68:71]
	v_mfma_f32_16x16x32_bf16 v[64:67], v[186:189], v[218:221], v[64:67]
	s_barrier
; #define PG8_STAGE(bufoff, gbase, voff) do { _Pragma("unroll") for (int _i = 0; _i < 2; ++_i) \
;         __builtin_amdgcn_global_load_lds((const unsigned*)((const char*)(gbase) + (voff)[_i]), (PG8_LAS unsigned*)(lds + (bufoff) + ldsw + _i * 8192), 16, 0, 0); } while (0)
; #define PG8_LDA(dst, b, h) do { _Pragma("unroll") for (int m = 0; m < 4; ++m) _Pragma("unroll") for (int k = 0; k < 2; ++k) dst[m][k] = *(const PG8_LAS bf16x8*)(lds + PG8_SA(b, h) + aoff + m * 2048 + k * 1024); } while (0)
; #define PG8_MMA(ai, bj, At, Bt) do { __builtin_amdgcn_s_setprio(1); _Pragma("unroll") for (int m = 0; m < 4; ++m) _Pragma("unroll") for (int n = 0; n < 2; ++n) _Pragma("unroll") for (int k = 0; k < 2; ++k) \
;         acc[ai][bj][m][n] = __builtin_amdgcn_mfma_f32_16x16x32_bf16(Bt[n][k], At[m][k], acc[ai][bj][m][n], 0, 0, 0); __builtin_amdgcn_s_setprio(0); } while (0)
; #define PG8_WAIT_V(n) asm volatile("s_waitcnt vmcnt(" #n ")" ::: "memory")
; #define PG8_WAIT_L(n) asm volatile("s_waitcnt lgkmcnt(" #n ")" ::: "memory")
; #define PG8_BAR __builtin_amdgcn_s_barrier()
; #define PG8_SCHED __builtin_amdgcn_sched_barrier(0)
; template <class Epi, class Sched, bool ALIGN_EPI = false, bool SP2 = false>
; __device__ __forceinline__ void gemm_phase(PG8_LAS unsigned char* lds, const Gemm g, const Sched& S, const Epi& E) {
;     ...
;             PG8_LDA(At, 1, 1); PG8_STAGE(PG8_SB(1, 0), b3, voffB); PG8_STAGE(PG8_SB(1, 1), b3 + hstepB, voffB); PG8_STAGE(PG8_SA(1, 0), a3, voffA);
;             PG8_WAIT_V(8); PG8_WAIT_L(0); PG8_BAR; PG8_MMA(1, 0, At, B0); PG8_MMA(1, 1, At, B1); PG8_BAR; PG8_SCHED;
	s_add_i32 s6, s6, s74
	v_lshl_add_u64 v[160:161], v[160:161], 0, s[16:17]
	s_mov_b32 m0, s6
	ds_read_b128 v[190:193], v168 offset:49152
	ds_read_b128 v[194:197], v168 offset:50176
	ds_read_b128 v[198:201], v168 offset:51200
	ds_read_b128 v[202:205], v168 offset:52224
	ds_read_b128 v[206:209], v168 offset:53248
	ds_read_b128 v[210:213], v168 offset:54272
	ds_read_b128 v[214:217], v168 offset:55296
	ds_read_b128 v[218:221], v168 offset:56320
	global_load_lds_dwordx4 v[160:161], off
	s_add_i32 m0, s6, 0x2000
	s_add_u32 s64, s64, 0x80080
	v_lshl_add_u64 v[160:161], v[222:223], 0, s[16:17]
	s_addc_u32 s65, s65, 0
	s_add_i32 s6, s7, s74
	global_load_lds_dwordx4 v[160:161], off
	v_lshl_add_u64 v[160:161], s[64:65], 0, v[138:139]
	s_mov_b32 m0, s6
	s_nop 0
	global_load_lds_dwordx4 v[160:161], off
	v_lshl_add_u64 v[160:161], s[64:65], 0, v[142:143]
	s_add_i32 m0, s6, 0x2000
	s_nop 0
	global_load_lds_dwordx4 v[160:161], off
	v_lshl_add_u64 v[160:161], v[224:225], 0, s[16:17]
	s_mov_b32 m0, s81
	s_nop 0
	global_load_lds_dwordx4 v[160:161], off
	v_lshl_add_u64 v[160:161], v[226:227], 0, s[16:17]
	s_mov_b32 m0, s82
	s_nop 0
	global_load_lds_dwordx4 v[160:161], off
	s_waitcnt vmcnt(8)
	s_waitcnt lgkmcnt(0)
	s_barrier
	s_waitcnt lgkmcnt(0)
	v_mfma_f32_16x16x32_bf16 v[60:63], v[128:131], v[190:193], v[60:63]
	v_mfma_f32_16x16x32_bf16 v[56:59], v[156:159], v[190:193], v[56:59]
	v_mfma_f32_16x16x32_bf16 v[44:47], v[128:131], v[198:201], v[44:47]
	v_mfma_f32_16x16x32_bf16 v[40:43], v[156:159], v[198:201], v[40:43]
	v_mfma_f32_16x16x32_bf16 v[28:31], v[128:131], v[206:209], v[28:31]
	v_mfma_f32_16x16x32_bf16 v[24:27], v[156:159], v[206:209], v[24:27]
	v_mfma_f32_16x16x32_bf16 v[12:15], v[128:131], v[214:217], v[12:15]
	v_mfma_f32_16x16x32_bf16 v[8:11], v[156:159], v[214:217], v[8:11]
	v_mfma_f32_16x16x32_bf16 v[60:63], v[132:135], v[194:197], v[60:63]
	v_mfma_f32_16x16x32_bf16 v[56:59], v[170:173], v[194:197], v[56:59]
	v_mfma_f32_16x16x32_bf16 v[44:47], v[132:135], v[202:205], v[44:47]
	v_mfma_f32_16x16x32_bf16 v[40:43], v[170:173], v[202:205], v[40:43]
	v_mfma_f32_16x16x32_bf16 v[28:31], v[132:135], v[210:213], v[28:31]
	v_mfma_f32_16x16x32_bf16 v[24:27], v[170:173], v[210:213], v[24:27]
	v_mfma_f32_16x16x32_bf16 v[12:15], v[132:135], v[218:221], v[12:15]
	v_mfma_f32_16x16x32_bf16 v[8:11], v[170:173], v[218:221], v[8:11]
	v_mfma_f32_16x16x32_bf16 v[52:55], v[174:177], v[190:193], v[52:55]
	v_mfma_f32_16x16x32_bf16 v[48:51], v[182:185], v[190:193], v[48:51]
	v_mfma_f32_16x16x32_bf16 v[36:39], v[174:177], v[198:201], v[36:39]
	v_mfma_f32_16x16x32_bf16 v[32:35], v[182:185], v[198:201], v[32:35]
	v_mfma_f32_16x16x32_bf16 v[20:23], v[174:177], v[206:209], v[20:23]
	v_mfma_f32_16x16x32_bf16 v[16:19], v[182:185], v[206:209], v[16:19]
	v_mfma_f32_16x16x32_bf16 v[4:7], v[174:177], v[214:217], v[4:7]
	v_mfma_f32_16x16x32_bf16 v[0:3], v[182:185], v[214:217], v[0:3]
	v_mfma_f32_16x16x32_bf16 v[52:55], v[178:181], v[194:197], v[52:55]
	v_mfma_f32_16x16x32_bf16 v[48:51], v[186:189], v[194:197], v[48:51]
	v_mfma_f32_16x16x32_bf16 v[36:39], v[178:181], v[202:205], v[36:39]
	v_mfma_f32_16x16x32_bf16 v[32:35], v[186:189], v[202:205], v[32:35]
	v_mfma_f32_16x16x32_bf16 v[20:23], v[178:181], v[210:213], v[20:23]
	v_mfma_f32_16x16x32_bf16 v[16:19], v[186:189], v[210:213], v[16:19]
	v_mfma_f32_16x16x32_bf16 v[4:7], v[178:181], v[218:221], v[4:7]
	v_mfma_f32_16x16x32_bf16 v[0:3], v[186:189], v[218:221], v[0:3]
	s_barrier
	s_add_i32 s96, s96, 2
	s_add_u32 s62, s62, 0x100
	s_addc_u32 s63, s63, 0
	s_add_u32 s94, s94, 0x100
	s_addc_u32 s95, s95, 0
	s_cmp_gt_u32 s96, 29
	s_cbranch_scc0 .LBB0_278
	s_and_b64 vcc, exec, s[24:25]
	s_cbranch_vccz .LBB0_281
	s_barrier

; #define PG8_STAGE(bufoff, gbase, voff) do { _Pragma("unroll") for (int _i = 0; _i < 2; ++_i) \
;         __builtin_amdgcn_global_load_lds((const unsigned*)((const char*)(gbase) + (voff)[_i]), (PG8_LAS unsigned*)(lds + (bufoff) + ldsw + _i * 8192), 16, 0, 0); } while (0)
; #define PG8_LDA(dst, b, h) do { _Pragma("unroll") for (int m = 0; m < 4; ++m) _Pragma("unroll") for (int k = 0; k < 2; ++k) dst[m][k] = *(const PG8_LAS bf16x8*)(lds + PG8_SA(b, h) + aoff + m * 2048 + k * 1024); } while (0)
; #define PG8_LDB(dst, b, h) do { _Pragma("unroll") for (int n = 0; n < 2; ++n) _Pragma("unroll") for (int k = 0; k < 2; ++k) dst[n][k] = *(const PG8_LAS bf16x8*)(lds + PG8_SB(b, h) + boff + n * 2048 + k * 1024); } while (0)
; #define PG8_MMA(ai, bj, At, Bt) do { __builtin_amdgcn_s_setprio(1); _Pragma("unroll") for (int m = 0; m < 4; ++m) _Pragma("unroll") for (int n = 0; n < 2; ++n) _Pragma("unroll") for (int k = 0; k < 2; ++k) \
;         acc[ai][bj][m][n] = __builtin_amdgcn_mfma_f32_16x16x32_bf16(Bt[n][k], At[m][k], acc[ai][bj][m][n], 0, 0, 0); __builtin_amdgcn_s_setprio(0); } while (0)
; #define PG8_WAIT_V(n) asm volatile("s_waitcnt vmcnt(" #n ")" ::: "memory")
; #define PG8_WAIT_L(n) asm volatile("s_waitcnt lgkmcnt(" #n ")" ::: "memory")
; #define PG8_BAR __builtin_amdgcn_s_barrier()
; #define PG8_SCHED __builtin_amdgcn_sched_barrier(0)
; template <class Epi, class Sched, bool ALIGN_EPI = false, bool SP2 = false>
; __device__ __forceinline__ void gemm_phase(PG8_LAS unsigned char* lds, const Gemm g, const Sched& S, const Epi& E) {
;     ...
;             PG8_LDB(B0, 0, 0); PG8_LDB(B1, 0, 1); PG8_SCHED; PG8_LDA(At, 0, 0); PG8_STAGE(PG8_SA(1, 1), a1 + hstepA, voffA);
;             PG8_WAIT_V(8); PG8_WAIT_L(0); PG8_BAR; PG8_MMA(0, 0, At, B0); PG8_MMA(0, 1, At, B1); PG8_BAR; PG8_SCHED;
;             PG8_LDA(At, 0, 1); PG8_STAGE(PG8_SB(0, 0), b2, voffB); PG8_STAGE(PG8_SB(0, 1), b2 + hstepB, voffB); PG8_STAGE(PG8_SA(0, 0), a2, voffA);
;             PG8_WAIT_V(8); PG8_WAIT_L(0); PG8_BAR; PG8_MMA(1, 0, At, B0); PG8_MMA(1, 1, At, B1); PG8_BAR; PG8_SCHED;
.LBB0_471:
	ds_read_b128 v[148:151], v188
	ds_read_b128 v[152:155], v188 offset:1024
	ds_read_b128 v[156:159], v188 offset:2048
	ds_read_b128 v[160:163], v188 offset:3072
	ds_read_b128 v[166:169], v189
	ds_read_b128 v[170:173], v189 offset:1024
	ds_read_b128 v[174:177], v189 offset:2048
	ds_read_b128 v[194:197], v189 offset:3072
	s_add_u32 s6, s0, 0xfff30080
	s_addc_u32 s7, s1, -1
	s_cmp_eq_u32 vcc_lo, 4
	s_cselect_b32 s73, s65, s7
	s_cselect_b32 s72, s64, s6
	s_cselect_b32 s71, s5, s97
	s_cselect_b32 s70, s63, s75
	v_lshl_add_u64 v[230:231], s[0:1], 0, v[140:141]
	s_add_i32 m0, s82, 0xc000
	ds_read_b128 v[198:201], v190
	ds_read_b128 v[202:205], v190 offset:1024
	ds_read_b128 v[206:209], v190 offset:2048
	ds_read_b128 v[210:213], v190 offset:3072
	ds_read_b128 v[214:217], v190 offset:4096
	ds_read_b128 v[218:221], v190 offset:5120
	ds_read_b128 v[222:225], v190 offset:6144
	ds_read_b128 v[226:229], v190 offset:7168
	global_load_lds_dwordx4 v[230:231], off
	v_lshl_add_u64 v[230:231], s[0:1], 0, v[142:143]
	s_add_i32 m0, s82, 0xe000
	s_nop 0
	global_load_lds_dwordx4 v[230:231], off
	s_waitcnt vmcnt(8)
	s_waitcnt lgkmcnt(0)
	s_barrier
	s_waitcnt lgkmcnt(0)
	v_mfma_f32_16x16x32_bf16 v[124:127], v[148:151], v[198:201], v[124:127]
	v_mfma_f32_16x16x32_bf16 v[120:123], v[156:159], v[198:201], v[120:123]
	v_mfma_f32_16x16x32_bf16 v[116:119], v[148:151], v[206:209], v[116:119]
	v_mfma_f32_16x16x32_bf16 v[112:115], v[156:159], v[206:209], v[112:115]
	v_mfma_f32_16x16x32_bf16 v[108:111], v[148:151], v[214:217], v[108:111]
	v_mfma_f32_16x16x32_bf16 v[104:107], v[156:159], v[214:217], v[104:107]
	v_mfma_f32_16x16x32_bf16 v[100:103], v[148:151], v[222:225], v[100:103]
	v_mfma_f32_16x16x32_bf16 v[96:99], v[156:159], v[222:225], v[96:99]
	v_mfma_f32_16x16x32_bf16 v[124:127], v[152:155], v[202:205], v[124:127]
	v_mfma_f32_16x16x32_bf16 v[120:123], v[160:163], v[202:205], v[120:123]
	v_mfma_f32_16x16x32_bf16 v[116:119], v[152:155], v[210:213], v[116:119]
	v_mfma_f32_16x16x32_bf16 v[112:115], v[160:163], v[210:213], v[112:115]
	v_mfma_f32_16x16x32_bf16 v[108:111], v[152:155], v[218:221], v[108:111]
	v_mfma_f32_16x16x32_bf16 v[104:107], v[160:163], v[218:221], v[104:107]
	v_mfma_f32_16x16x32_bf16 v[100:103], v[152:155], v[226:229], v[100:103]
	v_mfma_f32_16x16x32_bf16 v[96:99], v[160:163], v[226:229], v[96:99]
	v_mfma_f32_16x16x32_bf16 v[60:63], v[166:169], v[198:201], v[60:63]
	v_mfma_f32_16x16x32_bf16 v[56:59], v[174:177], v[198:201], v[56:59]
	v_mfma_f32_16x16x32_bf16 v[52:55], v[166:169], v[206:209], v[52:55]
	v_mfma_f32_16x16x32_bf16 v[48:51], v[174:177], v[206:209], v[48:51]
	v_mfma_f32_16x16x32_bf16 v[44:47], v[166:169], v[214:217], v[44:47]
	v_mfma_f32_16x16x32_bf16 v[40:43], v[174:177], v[214:217], v[40:43]
	v_mfma_f32_16x16x32_bf16 v[36:39], v[166:169], v[222:225], v[36:39]
	v_mfma_f32_16x16x32_bf16 v[32:35], v[174:177], v[222:225], v[32:35]
	v_mfma_f32_16x16x32_bf16 v[60:63], v[170:173], v[202:205], v[60:63]
	v_mfma_f32_16x16x32_bf16 v[56:59], v[194:197], v[202:205], v[56:59]
	v_mfma_f32_16x16x32_bf16 v[52:55], v[170:173], v[210:213], v[52:55]
	v_mfma_f32_16x16x32_bf16 v[48:51], v[194:197], v[210:213], v[48:51]
	v_mfma_f32_16x16x32_bf16 v[44:47], v[170:173], v[218:221], v[44:47]
	v_mfma_f32_16x16x32_bf16 v[40:43], v[194:197], v[218:221], v[40:43]
	v_mfma_f32_16x16x32_bf16 v[36:39], v[170:173], v[226:229], v[36:39]
	v_mfma_f32_16x16x32_bf16 v[32:35], v[194:197], v[226:229], v[32:35]
	s_barrier
	s_add_i32 s6, s92, s81
	v_lshl_add_u64 v[230:231], s[70:71], 0, v[130:131]
	s_mov_b32 m0, s6
	ds_read_b128 v[198:201], v190 offset:16384
	ds_read_b128 v[202:205], v190 offset:17408
	ds_read_b128 v[206:209], v190 offset:18432
	ds_read_b128 v[210:213], v190 offset:19456
	ds_read_b128 v[214:217], v190 offset:20480
	ds_read_b128 v[218:221], v190 offset:21504
	ds_read_b128 v[222:225], v190 offset:22528
	ds_read_b128 v[226:229], v190 offset:23552
	global_load_lds_dwordx4 v[230:231], off
	s_add_i32 m0, s6, 0x2000
	s_add_u32 s6, s70, 0x20000
	v_lshl_add_u64 v[232:233], s[70:71], 0, v[134:135]
	s_addc_u32 s7, s71, 0
	s_add_i32 s9, s93, s81
	global_load_lds_dwordx4 v[232:233], off
	v_lshl_add_u64 v[234:235], s[6:7], 0, v[130:131]
	s_mov_b32 m0, s9
	v_lshl_add_u64 v[236:237], s[72:73], 0, v[132:133]
	global_load_lds_dwordx4 v[234:235], off
	v_lshl_add_u64 v[234:235], s[6:7], 0, v[134:135]
	s_add_i32 m0, s9, 0x2000
	s_nop 0
	global_load_lds_dwordx4 v[234:235], off
	v_lshl_add_u64 v[234:235], s[72:73], 0, v[128:129]
	s_mov_b32 m0, s82
	s_nop 0
	global_load_lds_dwordx4 v[234:235], off
	s_mov_b32 m0, s83
	s_nop 0
	global_load_lds_dwordx4 v[236:237], off
	s_waitcnt vmcnt(8)
	s_waitcnt lgkmcnt(0)
	s_barrier
; #define PG8_STAGE(bufoff, gbase, voff) do { _Pragma("unroll") for (int _i = 0; _i < 2; ++_i) \
;         __builtin_amdgcn_global_load_lds((const unsigned*)((const char*)(gbase) + (voff)[_i]), (PG8_LAS unsigned*)(lds + (bufoff) + ldsw + _i * 8192), 16, 0, 0); } while (0)
; #define PG8_LDA(dst, b, h) do { _Pragma("unroll") for (int m = 0; m < 4; ++m) _Pragma("unroll") for (int k = 0; k < 2; ++k) dst[m][k] = *(const PG8_LAS bf16x8*)(lds + PG8_SA(b, h) + aoff + m * 2048 + k * 1024); } while (0)
; #define PG8_LDB(dst, b, h) do { _Pragma("unroll") for (int n = 0; n < 2; ++n) _Pragma("unroll") for (int k = 0; k < 2; ++k) dst[n][k] = *(const PG8_LAS bf16x8*)(lds + PG8_SB(b, h) + boff + n * 2048 + k * 1024); } while (0)
; #define PG8_MMA(ai, bj, At, Bt) do { __builtin_amdgcn_s_setprio(1); _Pragma("unroll") for (int m = 0; m < 4; ++m) _Pragma("unroll") for (int n = 0; n < 2; ++n) _Pragma("unroll") for (int k = 0; k < 2; ++k) \
;         acc[ai][bj][m][n] = __builtin_amdgcn_mfma_f32_16x16x32_bf16(Bt[n][k], At[m][k], acc[ai][bj][m][n], 0, 0, 0); __builtin_amdgcn_s_setprio(0); } while (0)
; #define PG8_WAIT_V(n) asm volatile("s_waitcnt vmcnt(" #n ")" ::: "memory")
; #define PG8_WAIT_L(n) asm volatile("s_waitcnt lgkmcnt(" #n ")" ::: "memory")
; #define PG8_BAR __builtin_amdgcn_s_barrier()
; #define PG8_SCHED __builtin_amdgcn_sched_barrier(0)
; template <class Epi, class Sched, bool ALIGN_EPI = false, bool SP2 = false>
; __device__ __forceinline__ void gemm_phase(PG8_LAS unsigned char* lds, const Gemm g, const Sched& S, const Epi& E) {
;     ...
;             PG8_WAIT_V(8); PG8_WAIT_L(0); PG8_BAR; PG8_MMA(1, 0, At, B0); PG8_MMA(1, 1, At, B1); PG8_BAR; PG8_SCHED;
;             PG8_LDB(B0, 1, 0); PG8_LDB(B1, 1, 1); PG8_SCHED; PG8_LDA(At, 1, 0); PG8_STAGE(PG8_SA(0, 1), a2 + hstepA, voffA);
;             PG8_WAIT_V(8); PG8_WAIT_L(0); PG8_BAR; PG8_MMA(0, 0, At, B0); PG8_MMA(0, 1, At, B1); PG8_BAR; PG8_SCHED;
	s_waitcnt lgkmcnt(0)
	v_mfma_f32_16x16x32_bf16 v[92:95], v[148:151], v[198:201], v[92:95]
	v_mfma_f32_16x16x32_bf16 v[88:91], v[156:159], v[198:201], v[88:91]
	v_mfma_f32_16x16x32_bf16 v[84:87], v[148:151], v[206:209], v[84:87]
	v_mfma_f32_16x16x32_bf16 v[80:83], v[156:159], v[206:209], v[80:83]
	v_mfma_f32_16x16x32_bf16 v[76:79], v[148:151], v[214:217], v[76:79]
	v_mfma_f32_16x16x32_bf16 v[72:75], v[156:159], v[214:217], v[72:75]
	v_mfma_f32_16x16x32_bf16 v[68:71], v[148:151], v[222:225], v[68:71]
	v_mfma_f32_16x16x32_bf16 v[64:67], v[156:159], v[222:225], v[64:67]
	v_mfma_f32_16x16x32_bf16 v[92:95], v[152:155], v[202:205], v[92:95]
	v_mfma_f32_16x16x32_bf16 v[88:91], v[160:163], v[202:205], v[88:91]
	v_mfma_f32_16x16x32_bf16 v[84:87], v[152:155], v[210:213], v[84:87]
	v_mfma_f32_16x16x32_bf16 v[80:83], v[160:163], v[210:213], v[80:83]
	v_mfma_f32_16x16x32_bf16 v[76:79], v[152:155], v[218:221], v[76:79]
	v_mfma_f32_16x16x32_bf16 v[72:75], v[160:163], v[218:221], v[72:75]
	v_mfma_f32_16x16x32_bf16 v[68:71], v[152:155], v[226:229], v[68:71]
	v_mfma_f32_16x16x32_bf16 v[64:67], v[160:163], v[226:229], v[64:67]
	v_mfma_f32_16x16x32_bf16 v[28:31], v[166:169], v[198:201], v[28:31]
	v_mfma_f32_16x16x32_bf16 v[24:27], v[174:177], v[198:201], v[24:27]
	v_mfma_f32_16x16x32_bf16 v[20:23], v[166:169], v[206:209], v[20:23]
	v_mfma_f32_16x16x32_bf16 v[16:19], v[174:177], v[206:209], v[16:19]
	v_mfma_f32_16x16x32_bf16 v[12:15], v[166:169], v[214:217], v[12:15]
	v_mfma_f32_16x16x32_bf16 v[8:11], v[174:177], v[214:217], v[8:11]
	v_mfma_f32_16x16x32_bf16 v[4:7], v[166:169], v[222:225], v[4:7]
	v_mfma_f32_16x16x32_bf16 v[0:3], v[174:177], v[222:225], v[0:3]
	v_mfma_f32_16x16x32_bf16 v[28:31], v[170:173], v[202:205], v[28:31]
	v_mfma_f32_16x16x32_bf16 v[24:27], v[194:197], v[202:205], v[24:27]
	v_mfma_f32_16x16x32_bf16 v[20:23], v[170:173], v[210:213], v[20:23]
	v_mfma_f32_16x16x32_bf16 v[16:19], v[194:197], v[210:213], v[16:19]
	v_mfma_f32_16x16x32_bf16 v[12:15], v[170:173], v[218:221], v[12:15]
	v_mfma_f32_16x16x32_bf16 v[8:11], v[194:197], v[218:221], v[8:11]
	v_mfma_f32_16x16x32_bf16 v[4:7], v[170:173], v[226:229], v[4:7]
	v_mfma_f32_16x16x32_bf16 v[0:3], v[194:197], v[226:229], v[0:3]
	s_barrier
	s_add_i32 s9, 0, 0x18000
	v_add_u32_e32 v138, s9, v187
	s_add_i32 s34, 0, 0x1c000
	ds_read_b128 v[148:151], v138
	ds_read_b128 v[152:155], v138 offset:1024
	ds_read_b128 v[156:159], v138 offset:2048
	ds_read_b128 v[160:163], v138 offset:3072
	v_add_u32_e32 v138, s34, v187
	ds_read_b128 v[166:169], v138
	ds_read_b128 v[170:173], v138 offset:1024
	ds_read_b128 v[174:177], v138 offset:2048
	ds_read_b128 v[194:197], v138 offset:3072
	s_add_u32 s6, s72, 0xd0000
	s_addc_u32 s7, s73, 0
	s_mov_b32 m0, s86
	v_lshl_add_u64 v[238:239], s[6:7], 0, v[128:129]
	ds_read_b128 v[198:201], v190 offset:32768
	ds_read_b128 v[202:205], v190 offset:33792
	ds_read_b128 v[206:209], v190 offset:34816
	ds_read_b128 v[210:213], v190 offset:35840
	ds_read_b128 v[214:217], v190 offset:36864
	ds_read_b128 v[218:221], v190 offset:37888
	ds_read_b128 v[222:225], v190 offset:38912
	ds_read_b128 v[226:229], v190 offset:39936
	global_load_lds_dwordx4 v[238:239], off
	v_lshl_add_u64 v[238:239], s[6:7], 0, v[132:133]
	s_mov_b32 m0, s87
	s_nop 0
	global_load_lds_dwordx4 v[238:239], off
	s_waitcnt vmcnt(8)
	s_waitcnt lgkmcnt(0)
	s_barrier
	s_waitcnt lgkmcnt(0)
	v_mfma_f32_16x16x32_bf16 v[124:127], v[148:151], v[198:201], v[124:127]
	v_mfma_f32_16x16x32_bf16 v[120:123], v[156:159], v[198:201], v[120:123]
	v_mfma_f32_16x16x32_bf16 v[116:119], v[148:151], v[206:209], v[116:119]
	v_mfma_f32_16x16x32_bf16 v[112:115], v[156:159], v[206:209], v[112:115]
	v_mfma_f32_16x16x32_bf16 v[108:111], v[148:151], v[214:217], v[108:111]
	v_mfma_f32_16x16x32_bf16 v[104:107], v[156:159], v[214:217], v[104:107]
	v_mfma_f32_16x16x32_bf16 v[100:103], v[148:151], v[222:225], v[100:103]
	v_mfma_f32_16x16x32_bf16 v[96:99], v[156:159], v[222:225], v[96:99]
	v_mfma_f32_16x16x32_bf16 v[124:127], v[152:155], v[202:205], v[124:127]
	v_mfma_f32_16x16x32_bf16 v[120:123], v[160:163], v[202:205], v[120:123]
	v_mfma_f32_16x16x32_bf16 v[116:119], v[152:155], v[210:213], v[116:119]
	v_mfma_f32_16x16x32_bf16 v[112:115], v[160:163], v[210:213], v[112:115]
	v_mfma_f32_16x16x32_bf16 v[108:111], v[152:155], v[218:221], v[108:111]
	v_mfma_f32_16x16x32_bf16 v[104:107], v[160:163], v[218:221], v[104:107]
	v_mfma_f32_16x16x32_bf16 v[100:103], v[152:155], v[226:229], v[100:103]
	v_mfma_f32_16x16x32_bf16 v[96:99], v[160:163], v[226:229], v[96:99]
	v_mfma_f32_16x16x32_bf16 v[60:63], v[166:169], v[198:201], v[60:63]
	v_mfma_f32_16x16x32_bf16 v[56:59], v[174:177], v[198:201], v[56:59]
	v_mfma_f32_16x16x32_bf16 v[52:55], v[166:169], v[206:209], v[52:55]
	v_mfma_f32_16x16x32_bf16 v[48:51], v[174:177], v[206:209], v[48:51]
	v_mfma_f32_16x16x32_bf16 v[44:47], v[166:169], v[214:217], v[44:47]
	v_mfma_f32_16x16x32_bf16 v[40:43], v[174:177], v[214:217], v[40:43]
	v_mfma_f32_16x16x32_bf16 v[36:39], v[166:169], v[222:225], v[36:39]
	v_mfma_f32_16x16x32_bf16 v[32:35], v[174:177], v[222:225], v[32:35]
	v_mfma_f32_16x16x32_bf16 v[60:63], v[170:173], v[202:205], v[60:63]
	v_mfma_f32_16x16x32_bf16 v[56:59], v[194:197], v[202:205], v[56:59]
	v_mfma_f32_16x16x32_bf16 v[52:55], v[170:173], v[210:213], v[52:55]
	v_mfma_f32_16x16x32_bf16 v[48:51], v[194:197], v[210:213], v[48:51]
	v_mfma_f32_16x16x32_bf16 v[44:47], v[170:173], v[218:221], v[44:47]
	v_mfma_f32_16x16x32_bf16 v[40:43], v[194:197], v[218:221], v[40:43]
	v_mfma_f32_16x16x32_bf16 v[36:39], v[170:173], v[226:229], v[36:39]
	v_mfma_f32_16x16x32_bf16 v[32:35], v[194:197], v[226:229], v[32:35]
	s_barrier
; #define PG8_STAGE(bufoff, gbase, voff) do { _Pragma("unroll") for (int _i = 0; _i < 2; ++_i) \
;         __builtin_amdgcn_global_load_lds((const unsigned*)((const char*)(gbase) + (voff)[_i]), (PG8_LAS unsigned*)(lds + (bufoff) + ldsw + _i * 8192), 16, 0, 0); } while (0)
; #define PG8_LDA(dst, b, h) do { _Pragma("unroll") for (int m = 0; m < 4; ++m) _Pragma("unroll") for (int k = 0; k < 2; ++k) dst[m][k] = *(const PG8_LAS bf16x8*)(lds + PG8_SA(b, h) + aoff + m * 2048 + k * 1024); } while (0)
; #define PG8_MMA(ai, bj, At, Bt) do { __builtin_amdgcn_s_setprio(1); _Pragma("unroll") for (int m = 0; m < 4; ++m) _Pragma("unroll") for (int n = 0; n < 2; ++n) _Pragma("unroll") for (int k = 0; k < 2; ++k) \
;         acc[ai][bj][m][n] = __builtin_amdgcn_mfma_f32_16x16x32_bf16(Bt[n][k], At[m][k], acc[ai][bj][m][n], 0, 0, 0); __builtin_amdgcn_s_setprio(0); } while (0)
; #define PG8_WAIT_V(n) asm volatile("s_waitcnt vmcnt(" #n ")" ::: "memory")
; #define PG8_WAIT_L(n) asm volatile("s_waitcnt lgkmcnt(" #n ")" ::: "memory")
; #define PG8_BAR __builtin_amdgcn_s_barrier()
; #define PG8_SCHED __builtin_amdgcn_sched_barrier(0)
; template <class Epi, class Sched, bool ALIGN_EPI = false, bool SP2 = false>
; __device__ __forceinline__ void gemm_phase(PG8_LAS unsigned char* lds, const Gemm g, const Sched& S, const Epi& E) {
;     ...
;             PG8_LDA(At, 1, 1); PG8_STAGE(PG8_SB(1, 0), b3, voffB); PG8_STAGE(PG8_SB(1, 1), b3 + hstepB, voffB); PG8_STAGE(PG8_SA(1, 0), a3, voffA);
;             PG8_WAIT_V(8); PG8_WAIT_L(0); PG8_BAR; PG8_MMA(1, 0, At, B0); PG8_MMA(1, 1, At, B1); PG8_BAR; PG8_SCHED;
	s_add_i32 s6, s9, s81
	v_lshl_add_u64 v[230:231], v[230:231], 0, s[44:45]
	s_mov_b32 m0, s6
	ds_read_b128 v[198:201], v190 offset:49152
	ds_read_b128 v[202:205], v190 offset:50176
	ds_read_b128 v[206:209], v190 offset:51200
	ds_read_b128 v[210:213], v190 offset:52224
	ds_read_b128 v[214:217], v190 offset:53248
	ds_read_b128 v[218:221], v190 offset:54272
	ds_read_b128 v[222:225], v190 offset:55296
	ds_read_b128 v[226:229], v190 offset:56320
	global_load_lds_dwordx4 v[230:231], off
	s_add_i32 m0, s6, 0x2000
	s_add_u32 s6, s70, 0x20080
	v_lshl_add_u64 v[230:231], v[232:233], 0, s[44:45]
	s_addc_u32 s7, s71, 0
	s_add_i32 s9, s34, s81
	global_load_lds_dwordx4 v[230:231], off
	v_lshl_add_u64 v[230:231], s[6:7], 0, v[130:131]
	s_mov_b32 m0, s9
	s_nop 0
	global_load_lds_dwordx4 v[230:231], off
	v_lshl_add_u64 v[230:231], s[6:7], 0, v[134:135]
	s_add_i32 m0, s9, 0x2000
	s_nop 0
	global_load_lds_dwordx4 v[230:231], off
	v_lshl_add_u64 v[230:231], v[234:235], 0, s[44:45]
	s_mov_b32 m0, s90
	s_nop 0
	global_load_lds_dwordx4 v[230:231], off
	v_lshl_add_u64 v[230:231], v[236:237], 0, s[44:45]
	s_mov_b32 m0, s91
	s_nop 0
	global_load_lds_dwordx4 v[230:231], off
	s_waitcnt vmcnt(8)
	s_waitcnt lgkmcnt(0)
	s_barrier
	s_waitcnt lgkmcnt(0)
	v_mfma_f32_16x16x32_bf16 v[92:95], v[148:151], v[198:201], v[92:95]
	v_mfma_f32_16x16x32_bf16 v[88:91], v[156:159], v[198:201], v[88:91]
	v_mfma_f32_16x16x32_bf16 v[84:87], v[148:151], v[206:209], v[84:87]
	v_mfma_f32_16x16x32_bf16 v[80:83], v[156:159], v[206:209], v[80:83]
	v_mfma_f32_16x16x32_bf16 v[76:79], v[148:151], v[214:217], v[76:79]
	v_mfma_f32_16x16x32_bf16 v[72:75], v[156:159], v[214:217], v[72:75]
	v_mfma_f32_16x16x32_bf16 v[68:71], v[148:151], v[222:225], v[68:71]
	v_mfma_f32_16x16x32_bf16 v[64:67], v[156:159], v[222:225], v[64:67]
	v_mfma_f32_16x16x32_bf16 v[92:95], v[152:155], v[202:205], v[92:95]
	v_mfma_f32_16x16x32_bf16 v[88:91], v[160:163], v[202:205], v[88:91]
	v_mfma_f32_16x16x32_bf16 v[84:87], v[152:155], v[210:213], v[84:87]
	v_mfma_f32_16x16x32_bf16 v[80:83], v[160:163], v[210:213], v[80:83]
	v_mfma_f32_16x16x32_bf16 v[76:79], v[152:155], v[218:221], v[76:79]
	v_mfma_f32_16x16x32_bf16 v[72:75], v[160:163], v[218:221], v[72:75]
	v_mfma_f32_16x16x32_bf16 v[68:71], v[152:155], v[226:229], v[68:71]
	v_mfma_f32_16x16x32_bf16 v[64:67], v[160:163], v[226:229], v[64:67]
	v_mfma_f32_16x16x32_bf16 v[28:31], v[166:169], v[198:201], v[28:31]
	v_mfma_f32_16x16x32_bf16 v[24:27], v[174:177], v[198:201], v[24:27]
	v_mfma_f32_16x16x32_bf16 v[20:23], v[166:169], v[206:209], v[20:23]
	v_mfma_f32_16x16x32_bf16 v[16:19], v[174:177], v[206:209], v[16:19]
	v_mfma_f32_16x16x32_bf16 v[12:15], v[166:169], v[214:217], v[12:15]
	v_mfma_f32_16x16x32_bf16 v[8:11], v[174:177], v[214:217], v[8:11]
	v_mfma_f32_16x16x32_bf16 v[4:7], v[166:169], v[222:225], v[4:7]
	v_mfma_f32_16x16x32_bf16 v[0:3], v[174:177], v[222:225], v[0:3]
	v_mfma_f32_16x16x32_bf16 v[28:31], v[170:173], v[202:205], v[28:31]
	v_mfma_f32_16x16x32_bf16 v[24:27], v[194:197], v[202:205], v[24:27]
	v_mfma_f32_16x16x32_bf16 v[20:23], v[170:173], v[210:213], v[20:23]
	v_mfma_f32_16x16x32_bf16 v[16:19], v[194:197], v[210:213], v[16:19]
	v_mfma_f32_16x16x32_bf16 v[12:15], v[170:173], v[218:221], v[12:15]
	v_mfma_f32_16x16x32_bf16 v[8:11], v[194:197], v[218:221], v[8:11]
	v_mfma_f32_16x16x32_bf16 v[4:7], v[170:173], v[226:229], v[4:7]
	v_mfma_f32_16x16x32_bf16 v[0:3], v[194:197], v[226:229], v[0:3]
	s_barrier
	s_add_i32 vcc_lo, vcc_lo, 2
	s_add_u32 s0, s0, 0x100
	s_addc_u32 s1, s1, 0
	s_add_u32 s75, s75, 0x100
	s_addc_u32 s97, s97, 0
	s_cmp_gt_u32 vcc_lo, 5
	s_cbranch_scc0 .LBB0_471
	s_and_b64 vcc, exec, s[54:55]
	s_cbranch_vccz .LBB0_474
	s_barrier

; #define PG8_STAGE(bufoff, gbase, voff) do { _Pragma("unroll") for (int _i = 0; _i < 2; ++_i) \
;         __builtin_amdgcn_global_load_lds((const unsigned*)((const char*)(gbase) + (voff)[_i]), (PG8_LAS unsigned*)(lds + (bufoff) + ldsw + _i * 8192), 16, 0, 0); } while (0)
; #define PG8_LDA(dst, b, h) do { _Pragma("unroll") for (int m = 0; m < 4; ++m) _Pragma("unroll") for (int k = 0; k < 2; ++k) dst[m][k] = *(const PG8_LAS bf16x8*)(lds + PG8_SA(b, h) + aoff + m * 2048 + k * 1024); } while (0)
; #define PG8_LDB(dst, b, h) do { _Pragma("unroll") for (int n = 0; n < 2; ++n) _Pragma("unroll") for (int k = 0; k < 2; ++k) dst[n][k] = *(const PG8_LAS bf16x8*)(lds + PG8_SB(b, h) + boff + n * 2048 + k * 1024); } while (0)
; #define PG8_MMA(ai, bj, At, Bt) do { __builtin_amdgcn_s_setprio(1); _Pragma("unroll") for (int m = 0; m < 4; ++m) _Pragma("unroll") for (int n = 0; n < 2; ++n) _Pragma("unroll") for (int k = 0; k < 2; ++k) \
;         acc[ai][bj][m][n] = __builtin_amdgcn_mfma_f32_16x16x32_bf16(Bt[n][k], At[m][k], acc[ai][bj][m][n], 0, 0, 0); __builtin_amdgcn_s_setprio(0); } while (0)
; #define PG8_WAIT_V(n) asm volatile("s_waitcnt vmcnt(" #n ")" ::: "memory")
; #define PG8_WAIT_L(n) asm volatile("s_waitcnt lgkmcnt(" #n ")" ::: "memory")
; #define PG8_BAR __builtin_amdgcn_s_barrier()
; #define PG8_SCHED __builtin_amdgcn_sched_barrier(0)
; template <class Epi, class Sched, bool ALIGN_EPI = false, bool SP2 = false>
; __device__ __forceinline__ void gemm_phase(PG8_LAS unsigned char* lds, const Gemm g, const Sched& S, const Epi& E) {
;     ...
;             PG8_LDB(B0, 0, 0); PG8_LDB(B1, 0, 1); PG8_SCHED; PG8_LDA(At, 0, 0); PG8_STAGE(PG8_SA(1, 1), a1 + hstepA, voffA);
;             PG8_WAIT_V(8); PG8_WAIT_L(0); PG8_BAR; PG8_MMA(0, 0, At, B0); PG8_MMA(0, 1, At, B1); PG8_BAR; PG8_SCHED;
;             PG8_LDA(At, 0, 1); PG8_STAGE(PG8_SB(0, 0), b2, voffB); PG8_STAGE(PG8_SB(0, 1), b2 + hstepB, voffB); PG8_STAGE(PG8_SA(0, 0), a2, voffA);
;             PG8_WAIT_V(8); PG8_WAIT_L(0); PG8_BAR; PG8_MMA(1, 0, At, B0); PG8_MMA(1, 1, At, B1); PG8_BAR; PG8_SCHED;
.LBB0_525:
	ds_read_b128 v[144:147], v172
	ds_read_b128 v[148:151], v172 offset:1024
	ds_read_b128 v[152:155], v172 offset:2048
	ds_read_b128 v[156:159], v172 offset:3072
	ds_read_b128 v[160:163], v173
	ds_read_b128 v[178:181], v173 offset:1024
	ds_read_b128 v[182:185], v173 offset:2048
	ds_read_b128 v[186:189], v173 offset:3072
	s_add_u32 s4, s0, 0xfff30080
	s_addc_u32 s5, s1, -1
	s_cmp_eq_u32 vcc_hi, 4
	s_cselect_b32 s11, s65, s5
	s_cselect_b32 s10, s64, s4
	s_cselect_b32 s5, s63, vcc_lo
	s_cselect_b32 s4, s96, s97
	v_lshl_add_u64 v[166:167], s[0:1], 0, v[136:137]
	s_add_i32 m0, s78, 0xc000
	ds_read_b128 v[190:193], v174
	ds_read_b128 v[194:197], v174 offset:1024
	ds_read_b128 v[198:201], v174 offset:2048
	ds_read_b128 v[202:205], v174 offset:3072
	ds_read_b128 v[206:209], v174 offset:4096
	ds_read_b128 v[210:213], v174 offset:5120
	ds_read_b128 v[214:217], v174 offset:6144
	ds_read_b128 v[218:221], v174 offset:7168
	global_load_lds_dwordx4 v[166:167], off
	v_lshl_add_u64 v[166:167], s[0:1], 0, v[138:139]
	s_add_i32 m0, s78, 0xe000
	s_nop 0
	global_load_lds_dwordx4 v[166:167], off
	s_waitcnt vmcnt(8)
	s_waitcnt lgkmcnt(0)
	s_barrier
	s_waitcnt lgkmcnt(0)
	v_mfma_f32_16x16x32_bf16 v[124:127], v[144:147], v[190:193], v[124:127]
	v_mfma_f32_16x16x32_bf16 v[120:123], v[152:155], v[190:193], v[120:123]
	v_mfma_f32_16x16x32_bf16 v[116:119], v[144:147], v[198:201], v[116:119]
	v_mfma_f32_16x16x32_bf16 v[112:115], v[152:155], v[198:201], v[112:115]
	v_mfma_f32_16x16x32_bf16 v[108:111], v[144:147], v[206:209], v[108:111]
	v_mfma_f32_16x16x32_bf16 v[104:107], v[152:155], v[206:209], v[104:107]
	v_mfma_f32_16x16x32_bf16 v[100:103], v[144:147], v[214:217], v[100:103]
	v_mfma_f32_16x16x32_bf16 v[96:99], v[152:155], v[214:217], v[96:99]
	v_mfma_f32_16x16x32_bf16 v[124:127], v[148:151], v[194:197], v[124:127]
	v_mfma_f32_16x16x32_bf16 v[120:123], v[156:159], v[194:197], v[120:123]
	v_mfma_f32_16x16x32_bf16 v[116:119], v[148:151], v[202:205], v[116:119]
	v_mfma_f32_16x16x32_bf16 v[112:115], v[156:159], v[202:205], v[112:115]
	v_mfma_f32_16x16x32_bf16 v[108:111], v[148:151], v[210:213], v[108:111]
	v_mfma_f32_16x16x32_bf16 v[104:107], v[156:159], v[210:213], v[104:107]
	v_mfma_f32_16x16x32_bf16 v[100:103], v[148:151], v[218:221], v[100:103]
	v_mfma_f32_16x16x32_bf16 v[96:99], v[156:159], v[218:221], v[96:99]
	v_mfma_f32_16x16x32_bf16 v[76:79], v[160:163], v[190:193], v[76:79]
	v_mfma_f32_16x16x32_bf16 v[68:71], v[182:185], v[190:193], v[68:71]
	v_mfma_f32_16x16x32_bf16 v[60:63], v[160:163], v[198:201], v[60:63]
	v_mfma_f32_16x16x32_bf16 v[56:59], v[182:185], v[198:201], v[56:59]
	v_mfma_f32_16x16x32_bf16 v[44:47], v[160:163], v[206:209], v[44:47]
	v_mfma_f32_16x16x32_bf16 v[40:43], v[182:185], v[206:209], v[40:43]
	v_mfma_f32_16x16x32_bf16 v[36:39], v[160:163], v[214:217], v[36:39]
	v_mfma_f32_16x16x32_bf16 v[32:35], v[182:185], v[214:217], v[32:35]
	v_mfma_f32_16x16x32_bf16 v[76:79], v[178:181], v[194:197], v[76:79]
	v_mfma_f32_16x16x32_bf16 v[68:71], v[186:189], v[194:197], v[68:71]
	v_mfma_f32_16x16x32_bf16 v[60:63], v[178:181], v[202:205], v[60:63]
	v_mfma_f32_16x16x32_bf16 v[56:59], v[186:189], v[202:205], v[56:59]
	v_mfma_f32_16x16x32_bf16 v[44:47], v[178:181], v[210:213], v[44:47]
	v_mfma_f32_16x16x32_bf16 v[40:43], v[186:189], v[210:213], v[40:43]
	v_mfma_f32_16x16x32_bf16 v[36:39], v[178:181], v[218:221], v[36:39]
	v_mfma_f32_16x16x32_bf16 v[32:35], v[186:189], v[218:221], v[32:35]
	s_barrier
	s_add_i32 s6, s87, s70
	v_lshl_add_u64 v[166:167], s[4:5], 0, v[130:131]
	s_mov_b32 m0, s6
	ds_read_b128 v[190:193], v174 offset:16384
	ds_read_b128 v[194:197], v174 offset:17408
	ds_read_b128 v[198:201], v174 offset:18432
	ds_read_b128 v[202:205], v174 offset:19456
	ds_read_b128 v[206:209], v174 offset:20480
	ds_read_b128 v[210:213], v174 offset:21504
	ds_read_b128 v[214:217], v174 offset:22528
	ds_read_b128 v[218:221], v174 offset:23552
	global_load_lds_dwordx4 v[166:167], off
	s_add_i32 m0, s6, 0x2000
	s_add_u32 s6, s4, 0x20000
	v_lshl_add_u64 v[222:223], s[4:5], 0, v[134:135]
	s_addc_u32 s7, s5, 0
	s_add_i32 s9, s88, s70
	global_load_lds_dwordx4 v[222:223], off
	v_lshl_add_u64 v[224:225], s[6:7], 0, v[130:131]
	s_mov_b32 m0, s9
	v_lshl_add_u64 v[226:227], s[10:11], 0, v[132:133]
	global_load_lds_dwordx4 v[224:225], off
	v_lshl_add_u64 v[224:225], s[6:7], 0, v[134:135]
	s_add_i32 m0, s9, 0x2000
	s_nop 0
	global_load_lds_dwordx4 v[224:225], off
	v_lshl_add_u64 v[224:225], s[10:11], 0, v[128:129]
	s_mov_b32 m0, s78
	s_nop 0
	global_load_lds_dwordx4 v[224:225], off
	s_mov_b32 m0, s79
	s_nop 0
	global_load_lds_dwordx4 v[226:227], off
	s_waitcnt vmcnt(8)
	s_waitcnt lgkmcnt(0)
	s_barrier
; #define PG8_STAGE(bufoff, gbase, voff) do { _Pragma("unroll") for (int _i = 0; _i < 2; ++_i) \
;         __builtin_amdgcn_global_load_lds((const unsigned*)((const char*)(gbase) + (voff)[_i]), (PG8_LAS unsigned*)(lds + (bufoff) + ldsw + _i * 8192), 16, 0, 0); } while (0)
; #define PG8_LDA(dst, b, h) do { _Pragma("unroll") for (int m = 0; m < 4; ++m) _Pragma("unroll") for (int k = 0; k < 2; ++k) dst[m][k] = *(const PG8_LAS bf16x8*)(lds + PG8_SA(b, h) + aoff + m * 2048 + k * 1024); } while (0)
; #define PG8_LDB(dst, b, h) do { _Pragma("unroll") for (int n = 0; n < 2; ++n) _Pragma("unroll") for (int k = 0; k < 2; ++k) dst[n][k] = *(const PG8_LAS bf16x8*)(lds + PG8_SB(b, h) + boff + n * 2048 + k * 1024); } while (0)
; #define PG8_MMA(ai, bj, At, Bt) do { __builtin_amdgcn_s_setprio(1); _Pragma("unroll") for (int m = 0; m < 4; ++m) _Pragma("unroll") for (int n = 0; n < 2; ++n) _Pragma("unroll") for (int k = 0; k < 2; ++k) \
;         acc[ai][bj][m][n] = __builtin_amdgcn_mfma_f32_16x16x32_bf16(Bt[n][k], At[m][k], acc[ai][bj][m][n], 0, 0, 0); __builtin_amdgcn_s_setprio(0); } while (0)
; #define PG8_WAIT_V(n) asm volatile("s_waitcnt vmcnt(" #n ")" ::: "memory")
; #define PG8_WAIT_L(n) asm volatile("s_waitcnt lgkmcnt(" #n ")" ::: "memory")
; #define PG8_BAR __builtin_amdgcn_s_barrier()
; #define PG8_SCHED __builtin_amdgcn_sched_barrier(0)
; template <class Epi, class Sched, bool ALIGN_EPI = false, bool SP2 = false>
; __device__ __forceinline__ void gemm_phase(PG8_LAS unsigned char* lds, const Gemm g, const Sched& S, const Epi& E) {
;     ...
;             PG8_WAIT_V(8); PG8_WAIT_L(0); PG8_BAR; PG8_MMA(1, 0, At, B0); PG8_MMA(1, 1, At, B1); PG8_BAR; PG8_SCHED;
;             PG8_LDB(B0, 1, 0); PG8_LDB(B1, 1, 1); PG8_SCHED; PG8_LDA(At, 1, 0); PG8_STAGE(PG8_SA(0, 1), a2 + hstepA, voffA);
;             PG8_WAIT_V(8); PG8_WAIT_L(0); PG8_BAR; PG8_MMA(0, 0, At, B0); PG8_MMA(0, 1, At, B1); PG8_BAR; PG8_SCHED;
	s_waitcnt lgkmcnt(0)
	v_mfma_f32_16x16x32_bf16 v[92:95], v[144:147], v[190:193], v[92:95]
	v_mfma_f32_16x16x32_bf16 v[88:91], v[152:155], v[190:193], v[88:91]
	v_mfma_f32_16x16x32_bf16 v[84:87], v[144:147], v[198:201], v[84:87]
	v_mfma_f32_16x16x32_bf16 v[80:83], v[152:155], v[198:201], v[80:83]
	v_mfma_f32_16x16x32_bf16 v[72:75], v[144:147], v[206:209], v[72:75]
	v_mfma_f32_16x16x32_bf16 v[64:67], v[152:155], v[206:209], v[64:67]
	v_mfma_f32_16x16x32_bf16 v[52:55], v[144:147], v[214:217], v[52:55]
	v_mfma_f32_16x16x32_bf16 v[48:51], v[152:155], v[214:217], v[48:51]
	v_mfma_f32_16x16x32_bf16 v[92:95], v[148:151], v[194:197], v[92:95]
	v_mfma_f32_16x16x32_bf16 v[88:91], v[156:159], v[194:197], v[88:91]
	v_mfma_f32_16x16x32_bf16 v[84:87], v[148:151], v[202:205], v[84:87]
	v_mfma_f32_16x16x32_bf16 v[80:83], v[156:159], v[202:205], v[80:83]
	v_mfma_f32_16x16x32_bf16 v[72:75], v[148:151], v[210:213], v[72:75]
	v_mfma_f32_16x16x32_bf16 v[64:67], v[156:159], v[210:213], v[64:67]
	v_mfma_f32_16x16x32_bf16 v[52:55], v[148:151], v[218:221], v[52:55]
	v_mfma_f32_16x16x32_bf16 v[48:51], v[156:159], v[218:221], v[48:51]
	v_mfma_f32_16x16x32_bf16 v[28:31], v[160:163], v[190:193], v[28:31]
	v_mfma_f32_16x16x32_bf16 v[24:27], v[182:185], v[190:193], v[24:27]
	v_mfma_f32_16x16x32_bf16 v[20:23], v[160:163], v[198:201], v[20:23]
	v_mfma_f32_16x16x32_bf16 v[16:19], v[182:185], v[198:201], v[16:19]
	v_mfma_f32_16x16x32_bf16 v[12:15], v[160:163], v[206:209], v[12:15]
	v_mfma_f32_16x16x32_bf16 v[8:11], v[182:185], v[206:209], v[8:11]
	v_mfma_f32_16x16x32_bf16 v[4:7], v[160:163], v[214:217], v[4:7]
	v_mfma_f32_16x16x32_bf16 v[0:3], v[182:185], v[214:217], v[0:3]
	v_mfma_f32_16x16x32_bf16 v[28:31], v[178:181], v[194:197], v[28:31]
	v_mfma_f32_16x16x32_bf16 v[24:27], v[186:189], v[194:197], v[24:27]
	v_mfma_f32_16x16x32_bf16 v[20:23], v[178:181], v[202:205], v[20:23]
	v_mfma_f32_16x16x32_bf16 v[16:19], v[186:189], v[202:205], v[16:19]
	v_mfma_f32_16x16x32_bf16 v[12:15], v[178:181], v[210:213], v[12:15]
	v_mfma_f32_16x16x32_bf16 v[8:11], v[186:189], v[210:213], v[8:11]
	v_mfma_f32_16x16x32_bf16 v[4:7], v[178:181], v[218:221], v[4:7]
	v_mfma_f32_16x16x32_bf16 v[0:3], v[186:189], v[218:221], v[0:3]
	s_barrier
	s_add_i32 s9, 0, 0x18000
	s_add_i32 s34, 0, 0x1c000
	v_add_u32_e32 v156, s9, v170
	v_add_u32_e32 v168, s34, v170
	ds_read_b128 v[144:147], v156
	ds_read_b128 v[148:151], v156 offset:1024
	ds_read_b128 v[152:155], v156 offset:2048
	ds_read_b128 v[156:159], v156 offset:3072
	ds_read_b128 v[160:163], v168
	ds_read_b128 v[178:181], v168 offset:1024
	ds_read_b128 v[182:185], v168 offset:2048
	ds_read_b128 v[186:189], v168 offset:3072
	s_add_u32 s6, s10, 0xd0000
	s_addc_u32 s7, s11, 0
	s_mov_b32 m0, s80
	v_lshl_add_u64 v[228:229], s[6:7], 0, v[128:129]
	ds_read_b128 v[190:193], v174 offset:32768
	ds_read_b128 v[194:197], v174 offset:33792
	ds_read_b128 v[198:201], v174 offset:34816
	ds_read_b128 v[202:205], v174 offset:35840
	ds_read_b128 v[206:209], v174 offset:36864
	ds_read_b128 v[210:213], v174 offset:37888
	ds_read_b128 v[214:217], v174 offset:38912
	ds_read_b128 v[218:221], v174 offset:39936
	global_load_lds_dwordx4 v[228:229], off
	v_lshl_add_u64 v[228:229], s[6:7], 0, v[132:133]
	s_mov_b32 m0, s81
	s_nop 0
	global_load_lds_dwordx4 v[228:229], off
	s_waitcnt vmcnt(8)
	s_waitcnt lgkmcnt(0)
	s_barrier
	s_waitcnt lgkmcnt(0)
	v_mfma_f32_16x16x32_bf16 v[124:127], v[144:147], v[190:193], v[124:127]
	v_mfma_f32_16x16x32_bf16 v[120:123], v[152:155], v[190:193], v[120:123]
	v_mfma_f32_16x16x32_bf16 v[116:119], v[144:147], v[198:201], v[116:119]
	v_mfma_f32_16x16x32_bf16 v[112:115], v[152:155], v[198:201], v[112:115]
	v_mfma_f32_16x16x32_bf16 v[108:111], v[144:147], v[206:209], v[108:111]
	v_mfma_f32_16x16x32_bf16 v[104:107], v[152:155], v[206:209], v[104:107]
	v_mfma_f32_16x16x32_bf16 v[100:103], v[144:147], v[214:217], v[100:103]
	v_mfma_f32_16x16x32_bf16 v[96:99], v[152:155], v[214:217], v[96:99]
	v_mfma_f32_16x16x32_bf16 v[124:127], v[148:151], v[194:197], v[124:127]
	v_mfma_f32_16x16x32_bf16 v[120:123], v[156:159], v[194:197], v[120:123]
	v_mfma_f32_16x16x32_bf16 v[116:119], v[148:151], v[202:205], v[116:119]
	v_mfma_f32_16x16x32_bf16 v[112:115], v[156:159], v[202:205], v[112:115]
	v_mfma_f32_16x16x32_bf16 v[108:111], v[148:151], v[210:213], v[108:111]
	v_mfma_f32_16x16x32_bf16 v[104:107], v[156:159], v[210:213], v[104:107]
	v_mfma_f32_16x16x32_bf16 v[100:103], v[148:151], v[218:221], v[100:103]
	v_mfma_f32_16x16x32_bf16 v[96:99], v[156:159], v[218:221], v[96:99]
	v_mfma_f32_16x16x32_bf16 v[76:79], v[160:163], v[190:193], v[76:79]
	v_mfma_f32_16x16x32_bf16 v[68:71], v[182:185], v[190:193], v[68:71]
	v_mfma_f32_16x16x32_bf16 v[60:63], v[160:163], v[198:201], v[60:63]
	v_mfma_f32_16x16x32_bf16 v[56:59], v[182:185], v[198:201], v[56:59]
	v_mfma_f32_16x16x32_bf16 v[44:47], v[160:163], v[206:209], v[44:47]
	v_mfma_f32_16x16x32_bf16 v[40:43], v[182:185], v[206:209], v[40:43]
	v_mfma_f32_16x16x32_bf16 v[36:39], v[160:163], v[214:217], v[36:39]
	v_mfma_f32_16x16x32_bf16 v[32:35], v[182:185], v[214:217], v[32:35]
	v_mfma_f32_16x16x32_bf16 v[76:79], v[178:181], v[194:197], v[76:79]
	v_mfma_f32_16x16x32_bf16 v[68:71], v[186:189], v[194:197], v[68:71]
	v_mfma_f32_16x16x32_bf16 v[60:63], v[178:181], v[202:205], v[60:63]
	v_mfma_f32_16x16x32_bf16 v[56:59], v[186:189], v[202:205], v[56:59]
	v_mfma_f32_16x16x32_bf16 v[44:47], v[178:181], v[210:213], v[44:47]
	v_mfma_f32_16x16x32_bf16 v[40:43], v[186:189], v[210:213], v[40:43]
	v_mfma_f32_16x16x32_bf16 v[36:39], v[178:181], v[218:221], v[36:39]
	v_mfma_f32_16x16x32_bf16 v[32:35], v[186:189], v[218:221], v[32:35]
	s_barrier
; #define PG8_STAGE(bufoff, gbase, voff) do { _Pragma("unroll") for (int _i = 0; _i < 2; ++_i) \
;         __builtin_amdgcn_global_load_lds((const unsigned*)((const char*)(gbase) + (voff)[_i]), (PG8_LAS unsigned*)(lds + (bufoff) + ldsw + _i * 8192), 16, 0, 0); } while (0)
; #define PG8_LDA(dst, b, h) do { _Pragma("unroll") for (int m = 0; m < 4; ++m) _Pragma("unroll") for (int k = 0; k < 2; ++k) dst[m][k] = *(const PG8_LAS bf16x8*)(lds + PG8_SA(b, h) + aoff + m * 2048 + k * 1024); } while (0)
; #define PG8_MMA(ai, bj, At, Bt) do { __builtin_amdgcn_s_setprio(1); _Pragma("unroll") for (int m = 0; m < 4; ++m) _Pragma("unroll") for (int n = 0; n < 2; ++n) _Pragma("unroll") for (int k = 0; k < 2; ++k) \
;         acc[ai][bj][m][n] = __builtin_amdgcn_mfma_f32_16x16x32_bf16(Bt[n][k], At[m][k], acc[ai][bj][m][n], 0, 0, 0); __builtin_amdgcn_s_setprio(0); } while (0)
; #define PG8_WAIT_V(n) asm volatile("s_waitcnt vmcnt(" #n ")" ::: "memory")
; #define PG8_WAIT_L(n) asm volatile("s_waitcnt lgkmcnt(" #n ")" ::: "memory")
; #define PG8_BAR __builtin_amdgcn_s_barrier()
; #define PG8_SCHED __builtin_amdgcn_sched_barrier(0)
; template <class Epi, class Sched, bool ALIGN_EPI = false, bool SP2 = false>
; __device__ __forceinline__ void gemm_phase(PG8_LAS unsigned char* lds, const Gemm g, const Sched& S, const Epi& E) {
;     ...
;             PG8_LDA(At, 1, 1); PG8_STAGE(PG8_SB(1, 0), b3, voffB); PG8_STAGE(PG8_SB(1, 1), b3 + hstepB, voffB); PG8_STAGE(PG8_SA(1, 0), a3, voffA);
;             PG8_WAIT_V(8); PG8_WAIT_L(0); PG8_BAR; PG8_MMA(1, 0, At, B0); PG8_MMA(1, 1, At, B1); PG8_BAR; PG8_SCHED;
	s_add_i32 s6, s9, s70
	v_lshl_add_u64 v[166:167], v[166:167], 0, s[38:39]
	s_mov_b32 m0, s6
	ds_read_b128 v[190:193], v174 offset:49152
	ds_read_b128 v[194:197], v174 offset:50176
	ds_read_b128 v[198:201], v174 offset:51200
	ds_read_b128 v[202:205], v174 offset:52224
	ds_read_b128 v[206:209], v174 offset:53248
	ds_read_b128 v[210:213], v174 offset:54272
	ds_read_b128 v[214:217], v174 offset:55296
	ds_read_b128 v[218:221], v174 offset:56320
	global_load_lds_dwordx4 v[166:167], off
	s_add_i32 m0, s6, 0x2000
	s_add_u32 s4, s4, 0x20080
	v_lshl_add_u64 v[166:167], v[222:223], 0, s[38:39]
	s_addc_u32 s5, s5, 0
	s_add_i32 s6, s34, s70
	global_load_lds_dwordx4 v[166:167], off
	v_lshl_add_u64 v[166:167], s[4:5], 0, v[130:131]
	s_mov_b32 m0, s6
	s_nop 0
	global_load_lds_dwordx4 v[166:167], off
	v_lshl_add_u64 v[166:167], s[4:5], 0, v[134:135]
	s_add_i32 m0, s6, 0x2000
	s_nop 0
	global_load_lds_dwordx4 v[166:167], off
	v_lshl_add_u64 v[166:167], v[224:225], 0, s[38:39]
	s_mov_b32 m0, s83
	s_nop 0
	global_load_lds_dwordx4 v[166:167], off
	v_lshl_add_u64 v[166:167], v[226:227], 0, s[38:39]
	s_mov_b32 m0, s86
	s_nop 0
	global_load_lds_dwordx4 v[166:167], off
	s_waitcnt vmcnt(8)
	s_waitcnt lgkmcnt(0)
	s_barrier
	s_waitcnt lgkmcnt(0)
	v_mfma_f32_16x16x32_bf16 v[92:95], v[144:147], v[190:193], v[92:95]
	v_mfma_f32_16x16x32_bf16 v[88:91], v[152:155], v[190:193], v[88:91]
	v_mfma_f32_16x16x32_bf16 v[84:87], v[144:147], v[198:201], v[84:87]
	v_mfma_f32_16x16x32_bf16 v[80:83], v[152:155], v[198:201], v[80:83]
	v_mfma_f32_16x16x32_bf16 v[72:75], v[144:147], v[206:209], v[72:75]
	v_mfma_f32_16x16x32_bf16 v[64:67], v[152:155], v[206:209], v[64:67]
	v_mfma_f32_16x16x32_bf16 v[52:55], v[144:147], v[214:217], v[52:55]
	v_mfma_f32_16x16x32_bf16 v[48:51], v[152:155], v[214:217], v[48:51]
	v_mfma_f32_16x16x32_bf16 v[92:95], v[148:151], v[194:197], v[92:95]
	v_mfma_f32_16x16x32_bf16 v[88:91], v[156:159], v[194:197], v[88:91]
	v_mfma_f32_16x16x32_bf16 v[84:87], v[148:151], v[202:205], v[84:87]
	v_mfma_f32_16x16x32_bf16 v[80:83], v[156:159], v[202:205], v[80:83]
	v_mfma_f32_16x16x32_bf16 v[72:75], v[148:151], v[210:213], v[72:75]
	v_mfma_f32_16x16x32_bf16 v[64:67], v[156:159], v[210:213], v[64:67]
	v_mfma_f32_16x16x32_bf16 v[52:55], v[148:151], v[218:221], v[52:55]
	v_mfma_f32_16x16x32_bf16 v[48:51], v[156:159], v[218:221], v[48:51]
	v_mfma_f32_16x16x32_bf16 v[28:31], v[160:163], v[190:193], v[28:31]
	v_mfma_f32_16x16x32_bf16 v[24:27], v[182:185], v[190:193], v[24:27]
	v_mfma_f32_16x16x32_bf16 v[20:23], v[160:163], v[198:201], v[20:23]
	v_mfma_f32_16x16x32_bf16 v[16:19], v[182:185], v[198:201], v[16:19]
	v_mfma_f32_16x16x32_bf16 v[12:15], v[160:163], v[206:209], v[12:15]
	v_mfma_f32_16x16x32_bf16 v[8:11], v[182:185], v[206:209], v[8:11]
	v_mfma_f32_16x16x32_bf16 v[4:7], v[160:163], v[214:217], v[4:7]
	v_mfma_f32_16x16x32_bf16 v[0:3], v[182:185], v[214:217], v[0:3]
	v_mfma_f32_16x16x32_bf16 v[28:31], v[178:181], v[194:197], v[28:31]
	v_mfma_f32_16x16x32_bf16 v[24:27], v[186:189], v[194:197], v[24:27]
	v_mfma_f32_16x16x32_bf16 v[20:23], v[178:181], v[202:205], v[20:23]
	v_mfma_f32_16x16x32_bf16 v[16:19], v[186:189], v[202:205], v[16:19]
	v_mfma_f32_16x16x32_bf16 v[12:15], v[178:181], v[210:213], v[12:15]
	v_mfma_f32_16x16x32_bf16 v[8:11], v[186:189], v[210:213], v[8:11]
	v_mfma_f32_16x16x32_bf16 v[4:7], v[178:181], v[218:221], v[4:7]
	v_mfma_f32_16x16x32_bf16 v[0:3], v[186:189], v[218:221], v[0:3]
	s_barrier
	s_add_i32 vcc_hi, vcc_hi, 2
	s_add_u32 s0, s0, 0x100
	s_addc_u32 s1, s1, 0
	s_add_u32 s97, s97, 0x100
	s_addc_u32 vcc_lo, vcc_lo, 0
	s_cmp_gt_u32 vcc_hi, 5
	s_cbranch_scc0 .LBB0_525
	s_and_b64 vcc, exec, s[40:41]
	s_cbranch_vccz .LBB0_528
	s_barrier

; #define PG8_STAGE(bufoff, gbase, voff) do { _Pragma("unroll") for (int _i = 0; _i < 2; ++_i) \
;         __builtin_amdgcn_global_load_lds((const unsigned*)((const char*)(gbase) + (voff)[_i]), (PG8_LAS unsigned*)(lds + (bufoff) + ldsw + _i * 8192), 16, 0, 0); } while (0)
; #define PG8_LDA(dst, b, h) do { _Pragma("unroll") for (int m = 0; m < 4; ++m) _Pragma("unroll") for (int k = 0; k < 2; ++k) dst[m][k] = *(const PG8_LAS bf16x8*)(lds + PG8_SA(b, h) + aoff + m * 2048 + k * 1024); } while (0)
; #define PG8_LDB(dst, b, h) do { _Pragma("unroll") for (int n = 0; n < 2; ++n) _Pragma("unroll") for (int k = 0; k < 2; ++k) dst[n][k] = *(const PG8_LAS bf16x8*)(lds + PG8_SB(b, h) + boff + n * 2048 + k * 1024); } while (0)
; #define PG8_MMA(ai, bj, At, Bt) do { __builtin_amdgcn_s_setprio(1); _Pragma("unroll") for (int m = 0; m < 4; ++m) _Pragma("unroll") for (int n = 0; n < 2; ++n) _Pragma("unroll") for (int k = 0; k < 2; ++k) \
;         acc[ai][bj][m][n] = __builtin_amdgcn_mfma_f32_16x16x32_bf16(Bt[n][k], At[m][k], acc[ai][bj][m][n], 0, 0, 0); __builtin_amdgcn_s_setprio(0); } while (0)
; #define PG8_WAIT_V(n) asm volatile("s_waitcnt vmcnt(" #n ")" ::: "memory")
; #define PG8_WAIT_L(n) asm volatile("s_waitcnt lgkmcnt(" #n ")" ::: "memory")
; #define PG8_BAR __builtin_amdgcn_s_barrier()
; #define PG8_SCHED __builtin_amdgcn_sched_barrier(0)
; template <class Epi, class Sched, bool ALIGN_EPI = false, bool SP2 = false>
; __device__ __forceinline__ void gemm_phase(PG8_LAS unsigned char* lds, const Gemm g, const Sched& S, const Epi& E) {
;     ...
;             PG8_LDB(B0, 0, 0); PG8_LDB(B1, 0, 1); PG8_SCHED; PG8_LDA(At, 0, 0); PG8_STAGE(PG8_SA(1, 1), a1 + hstepA, voffA);
;             PG8_WAIT_V(8); PG8_WAIT_L(0); PG8_BAR; PG8_MMA(0, 0, At, B0); PG8_MMA(0, 1, At, B1); PG8_BAR; PG8_SCHED;
;             PG8_LDA(At, 0, 1); PG8_STAGE(PG8_SB(0, 0), b2, voffB); PG8_STAGE(PG8_SB(0, 1), b2 + hstepB, voffB); PG8_STAGE(PG8_SA(0, 0), a2, voffA);
;             PG8_WAIT_V(8); PG8_WAIT_L(0); PG8_BAR; PG8_MMA(1, 0, At, B0); PG8_MMA(1, 1, At, B1); PG8_BAR; PG8_SCHED;
.LBB0_694:
	ds_read_b128 v[56:59], v196
	ds_read_b128 v[64:67], v196 offset:1024
	ds_read_b128 v[72:75], v196 offset:2048
	ds_read_b128 v[76:79], v196 offset:3072
	ds_read_b128 v[144:147], v197
	ds_read_b128 v[166:169], v197 offset:1024
	ds_read_b128 v[170:173], v197 offset:2048
	ds_read_b128 v[174:177], v197 offset:3072
	s_add_u32 s6, s58, 0xfff80080
	s_addc_u32 s7, s59, -1
	s_cmp_eq_u32 s95, 28
	s_cselect_b32 s65, s5, s7
	s_cselect_b32 s64, s39, s6
	s_cselect_b32 s63, s37, s94
	s_cselect_b32 s62, s55, s93
	v_lshl_add_u64 v[162:163], s[58:59], 0, v[154:155]
	s_add_i32 m0, s69, 0xc000
	ds_read_b128 v[178:181], v198
	ds_read_b128 v[182:185], v198 offset:1024
	ds_read_b128 v[200:203], v198 offset:2048
	ds_read_b128 v[204:207], v198 offset:3072
	ds_read_b128 v[208:211], v198 offset:4096
	ds_read_b128 v[212:215], v198 offset:5120
	ds_read_b128 v[216:219], v198 offset:6144
	ds_read_b128 v[220:223], v198 offset:7168
	global_load_lds_dwordx4 v[162:163], off
	v_lshl_add_u64 v[162:163], s[58:59], 0, v[156:157]
	s_add_i32 m0, s69, 0xe000
	s_nop 0
	global_load_lds_dwordx4 v[162:163], off
	s_waitcnt vmcnt(8)
	s_waitcnt lgkmcnt(0)
	s_barrier
	s_waitcnt lgkmcnt(0)
	v_mfma_f32_16x16x32_bf16 v[140:143], v[56:59], v[178:181], v[140:143]
	v_mfma_f32_16x16x32_bf16 v[136:139], v[72:75], v[178:181], v[136:139]
	v_mfma_f32_16x16x32_bf16 v[124:127], v[56:59], v[200:203], v[124:127]
	v_mfma_f32_16x16x32_bf16 v[120:123], v[72:75], v[200:203], v[120:123]
	v_mfma_f32_16x16x32_bf16 v[108:111], v[56:59], v[208:211], v[108:111]
	v_mfma_f32_16x16x32_bf16 v[104:107], v[72:75], v[208:211], v[104:107]
	v_mfma_f32_16x16x32_bf16 v[92:95], v[56:59], v[216:219], v[92:95]
	v_mfma_f32_16x16x32_bf16 v[88:91], v[72:75], v[216:219], v[88:91]
	v_mfma_f32_16x16x32_bf16 v[140:143], v[64:67], v[182:185], v[140:143]
	v_mfma_f32_16x16x32_bf16 v[136:139], v[76:79], v[182:185], v[136:139]
	v_mfma_f32_16x16x32_bf16 v[124:127], v[64:67], v[204:207], v[124:127]
	v_mfma_f32_16x16x32_bf16 v[120:123], v[76:79], v[204:207], v[120:123]
	v_mfma_f32_16x16x32_bf16 v[108:111], v[64:67], v[212:215], v[108:111]
	v_mfma_f32_16x16x32_bf16 v[104:107], v[76:79], v[212:215], v[104:107]
	v_mfma_f32_16x16x32_bf16 v[92:95], v[64:67], v[220:223], v[92:95]
	v_mfma_f32_16x16x32_bf16 v[88:91], v[76:79], v[220:223], v[88:91]
	v_mfma_f32_16x16x32_bf16 v[132:135], v[144:147], v[178:181], v[132:135]
	v_mfma_f32_16x16x32_bf16 v[128:131], v[170:173], v[178:181], v[128:131]
	v_mfma_f32_16x16x32_bf16 v[116:119], v[144:147], v[200:203], v[116:119]
	v_mfma_f32_16x16x32_bf16 v[112:115], v[170:173], v[200:203], v[112:115]
	v_mfma_f32_16x16x32_bf16 v[100:103], v[144:147], v[208:211], v[100:103]
	v_mfma_f32_16x16x32_bf16 v[96:99], v[170:173], v[208:211], v[96:99]
	v_mfma_f32_16x16x32_bf16 v[84:87], v[144:147], v[216:219], v[84:87]
	v_mfma_f32_16x16x32_bf16 v[80:83], v[170:173], v[216:219], v[80:83]
	v_mfma_f32_16x16x32_bf16 v[132:135], v[166:169], v[182:185], v[132:135]
	v_mfma_f32_16x16x32_bf16 v[128:131], v[174:177], v[182:185], v[128:131]
	v_mfma_f32_16x16x32_bf16 v[116:119], v[166:169], v[204:207], v[116:119]
	v_mfma_f32_16x16x32_bf16 v[112:115], v[174:177], v[204:207], v[112:115]
	v_mfma_f32_16x16x32_bf16 v[100:103], v[166:169], v[212:215], v[100:103]
	v_mfma_f32_16x16x32_bf16 v[96:99], v[174:177], v[212:215], v[96:99]
	v_mfma_f32_16x16x32_bf16 v[84:87], v[166:169], v[220:223], v[84:87]
	v_mfma_f32_16x16x32_bf16 v[80:83], v[174:177], v[220:223], v[80:83]
	s_barrier
	s_add_i32 s6, s90, s68
	v_lshl_add_u64 v[162:163], s[62:63], 0, v[148:149]
	s_mov_b32 m0, s6
	ds_read_b128 v[178:181], v198 offset:16384
	ds_read_b128 v[182:185], v198 offset:17408
	ds_read_b128 v[200:203], v198 offset:18432
	ds_read_b128 v[204:207], v198 offset:19456
	ds_read_b128 v[208:211], v198 offset:20480
	ds_read_b128 v[212:215], v198 offset:21504
	ds_read_b128 v[216:219], v198 offset:22528
	ds_read_b128 v[220:223], v198 offset:23552
	global_load_lds_dwordx4 v[162:163], off
	s_add_i32 m0, s6, 0x2000
	s_add_u32 s6, s62, 0x80000
	v_lshl_add_u64 v[224:225], s[62:63], 0, v[150:151]
	s_addc_u32 s7, s63, 0
	s_add_i32 s9, s91, s68
	global_load_lds_dwordx4 v[224:225], off
	v_lshl_add_u64 v[226:227], s[6:7], 0, v[148:149]
	s_mov_b32 m0, s9
	v_lshl_add_u64 v[228:229], s[64:65], 0, v[150:151]
	global_load_lds_dwordx4 v[226:227], off
	v_lshl_add_u64 v[226:227], s[6:7], 0, v[150:151]
	s_add_i32 m0, s9, 0x2000
	s_nop 0
	global_load_lds_dwordx4 v[226:227], off
	v_lshl_add_u64 v[226:227], s[64:65], 0, v[148:149]
	s_mov_b32 m0, s69
	s_nop 0
	global_load_lds_dwordx4 v[226:227], off
	s_mov_b32 m0, s72
	s_nop 0
	global_load_lds_dwordx4 v[228:229], off
	s_waitcnt vmcnt(8)
	s_waitcnt lgkmcnt(0)
	s_barrier
; #define PG8_STAGE(bufoff, gbase, voff) do { _Pragma("unroll") for (int _i = 0; _i < 2; ++_i) \
;         __builtin_amdgcn_global_load_lds((const unsigned*)((const char*)(gbase) + (voff)[_i]), (PG8_LAS unsigned*)(lds + (bufoff) + ldsw + _i * 8192), 16, 0, 0); } while (0)
; #define PG8_LDA(dst, b, h) do { _Pragma("unroll") for (int m = 0; m < 4; ++m) _Pragma("unroll") for (int k = 0; k < 2; ++k) dst[m][k] = *(const PG8_LAS bf16x8*)(lds + PG8_SA(b, h) + aoff + m * 2048 + k * 1024); } while (0)
; #define PG8_LDB(dst, b, h) do { _Pragma("unroll") for (int n = 0; n < 2; ++n) _Pragma("unroll") for (int k = 0; k < 2; ++k) dst[n][k] = *(const PG8_LAS bf16x8*)(lds + PG8_SB(b, h) + boff + n * 2048 + k * 1024); } while (0)
; #define PG8_MMA(ai, bj, At, Bt) do { __builtin_amdgcn_s_setprio(1); _Pragma("unroll") for (int m = 0; m < 4; ++m) _Pragma("unroll") for (int n = 0; n < 2; ++n) _Pragma("unroll") for (int k = 0; k < 2; ++k) \
;         acc[ai][bj][m][n] = __builtin_amdgcn_mfma_f32_16x16x32_bf16(Bt[n][k], At[m][k], acc[ai][bj][m][n], 0, 0, 0); __builtin_amdgcn_s_setprio(0); } while (0)
; #define PG8_WAIT_V(n) asm volatile("s_waitcnt vmcnt(" #n ")" ::: "memory")
; #define PG8_WAIT_L(n) asm volatile("s_waitcnt lgkmcnt(" #n ")" ::: "memory")
; #define PG8_BAR __builtin_amdgcn_s_barrier()
; #define PG8_SCHED __builtin_amdgcn_sched_barrier(0)
; template <class Epi, class Sched, bool ALIGN_EPI = false, bool SP2 = false>
; __device__ __forceinline__ void gemm_phase(PG8_LAS unsigned char* lds, const Gemm g, const Sched& S, const Epi& E) {
;     ...
;             PG8_WAIT_V(8); PG8_WAIT_L(0); PG8_BAR; PG8_MMA(1, 0, At, B0); PG8_MMA(1, 1, At, B1); PG8_BAR; PG8_SCHED;
;             PG8_LDB(B0, 1, 0); PG8_LDB(B1, 1, 1); PG8_SCHED; PG8_LDA(At, 1, 0); PG8_STAGE(PG8_SA(0, 1), a2 + hstepA, voffA);
;             PG8_WAIT_V(8); PG8_WAIT_L(0); PG8_BAR; PG8_MMA(0, 0, At, B0); PG8_MMA(0, 1, At, B1); PG8_BAR; PG8_SCHED;
	s_waitcnt lgkmcnt(0)
	v_mfma_f32_16x16x32_bf16 v[68:71], v[56:59], v[178:181], v[68:71]
	v_mfma_f32_16x16x32_bf16 v[60:63], v[72:75], v[178:181], v[60:63]
	v_mfma_f32_16x16x32_bf16 v[44:47], v[56:59], v[200:203], v[44:47]
	v_mfma_f32_16x16x32_bf16 v[40:43], v[72:75], v[200:203], v[40:43]
	v_mfma_f32_16x16x32_bf16 v[28:31], v[56:59], v[208:211], v[28:31]
	v_mfma_f32_16x16x32_bf16 v[24:27], v[72:75], v[208:211], v[24:27]
	v_mfma_f32_16x16x32_bf16 v[12:15], v[56:59], v[216:219], v[12:15]
	v_mfma_f32_16x16x32_bf16 v[8:11], v[72:75], v[216:219], v[8:11]
	v_mfma_f32_16x16x32_bf16 v[68:71], v[64:67], v[182:185], v[68:71]
	v_mfma_f32_16x16x32_bf16 v[60:63], v[76:79], v[182:185], v[60:63]
	v_mfma_f32_16x16x32_bf16 v[44:47], v[64:67], v[204:207], v[44:47]
	v_mfma_f32_16x16x32_bf16 v[40:43], v[76:79], v[204:207], v[40:43]
	v_mfma_f32_16x16x32_bf16 v[28:31], v[64:67], v[212:215], v[28:31]
	v_mfma_f32_16x16x32_bf16 v[24:27], v[76:79], v[212:215], v[24:27]
	v_mfma_f32_16x16x32_bf16 v[12:15], v[64:67], v[220:223], v[12:15]
	v_mfma_f32_16x16x32_bf16 v[8:11], v[76:79], v[220:223], v[8:11]
	v_mfma_f32_16x16x32_bf16 v[52:55], v[144:147], v[178:181], v[52:55]
	v_mfma_f32_16x16x32_bf16 v[48:51], v[170:173], v[178:181], v[48:51]
	v_mfma_f32_16x16x32_bf16 v[36:39], v[144:147], v[200:203], v[36:39]
	v_mfma_f32_16x16x32_bf16 v[32:35], v[170:173], v[200:203], v[32:35]
	v_mfma_f32_16x16x32_bf16 v[20:23], v[144:147], v[208:211], v[20:23]
	v_mfma_f32_16x16x32_bf16 v[16:19], v[170:173], v[208:211], v[16:19]
	v_mfma_f32_16x16x32_bf16 v[4:7], v[144:147], v[216:219], v[4:7]
	v_mfma_f32_16x16x32_bf16 v[0:3], v[170:173], v[216:219], v[0:3]
	v_mfma_f32_16x16x32_bf16 v[52:55], v[166:169], v[182:185], v[52:55]
	v_mfma_f32_16x16x32_bf16 v[48:51], v[174:177], v[182:185], v[48:51]
	v_mfma_f32_16x16x32_bf16 v[36:39], v[166:169], v[204:207], v[36:39]
	v_mfma_f32_16x16x32_bf16 v[32:35], v[174:177], v[204:207], v[32:35]
	v_mfma_f32_16x16x32_bf16 v[20:23], v[166:169], v[212:215], v[20:23]
	v_mfma_f32_16x16x32_bf16 v[16:19], v[174:177], v[212:215], v[16:19]
	v_mfma_f32_16x16x32_bf16 v[4:7], v[166:169], v[220:223], v[4:7]
	v_mfma_f32_16x16x32_bf16 v[0:3], v[174:177], v[220:223], v[0:3]
	s_barrier
	s_add_i32 s9, 0, 0x18000
	s_add_i32 s34, 0, 0x1c000
	v_add_u32_e32 v76, s9, v194
	v_add_u32_e32 v152, s34, v194
	ds_read_b128 v[56:59], v76
	ds_read_b128 v[64:67], v76 offset:1024
	ds_read_b128 v[72:75], v76 offset:2048
	ds_read_b128 v[76:79], v76 offset:3072
	ds_read_b128 v[144:147], v152
	ds_read_b128 v[166:169], v152 offset:1024
	ds_read_b128 v[170:173], v152 offset:2048
	ds_read_b128 v[174:177], v152 offset:3072
	s_add_u32 s6, s64, 0x80000
	s_addc_u32 s7, s65, 0
	s_mov_b32 m0, s73
	v_lshl_add_u64 v[230:231], s[6:7], 0, v[148:149]
	ds_read_b128 v[178:181], v198 offset:32768
	ds_read_b128 v[182:185], v198 offset:33792
	ds_read_b128 v[200:203], v198 offset:34816
	ds_read_b128 v[204:207], v198 offset:35840
	ds_read_b128 v[208:211], v198 offset:36864
	ds_read_b128 v[212:215], v198 offset:37888
	ds_read_b128 v[216:219], v198 offset:38912
	ds_read_b128 v[220:223], v198 offset:39936
	global_load_lds_dwordx4 v[230:231], off
	v_lshl_add_u64 v[230:231], s[6:7], 0, v[150:151]
	s_mov_b32 m0, s74
	s_nop 0
	global_load_lds_dwordx4 v[230:231], off
	s_waitcnt vmcnt(8)
	s_waitcnt lgkmcnt(0)
	s_barrier
	s_waitcnt lgkmcnt(0)
	v_mfma_f32_16x16x32_bf16 v[140:143], v[56:59], v[178:181], v[140:143]
	v_mfma_f32_16x16x32_bf16 v[136:139], v[72:75], v[178:181], v[136:139]
	v_mfma_f32_16x16x32_bf16 v[124:127], v[56:59], v[200:203], v[124:127]
	v_mfma_f32_16x16x32_bf16 v[120:123], v[72:75], v[200:203], v[120:123]
	v_mfma_f32_16x16x32_bf16 v[108:111], v[56:59], v[208:211], v[108:111]
	v_mfma_f32_16x16x32_bf16 v[104:107], v[72:75], v[208:211], v[104:107]
	v_mfma_f32_16x16x32_bf16 v[92:95], v[56:59], v[216:219], v[92:95]
	v_mfma_f32_16x16x32_bf16 v[88:91], v[72:75], v[216:219], v[88:91]
	v_mfma_f32_16x16x32_bf16 v[140:143], v[64:67], v[182:185], v[140:143]
	v_mfma_f32_16x16x32_bf16 v[136:139], v[76:79], v[182:185], v[136:139]
	v_mfma_f32_16x16x32_bf16 v[124:127], v[64:67], v[204:207], v[124:127]
	v_mfma_f32_16x16x32_bf16 v[120:123], v[76:79], v[204:207], v[120:123]
	v_mfma_f32_16x16x32_bf16 v[108:111], v[64:67], v[212:215], v[108:111]
	v_mfma_f32_16x16x32_bf16 v[104:107], v[76:79], v[212:215], v[104:107]
	v_mfma_f32_16x16x32_bf16 v[92:95], v[64:67], v[220:223], v[92:95]
	v_mfma_f32_16x16x32_bf16 v[88:91], v[76:79], v[220:223], v[88:91]
	v_mfma_f32_16x16x32_bf16 v[132:135], v[144:147], v[178:181], v[132:135]
	v_mfma_f32_16x16x32_bf16 v[128:131], v[170:173], v[178:181], v[128:131]
	v_mfma_f32_16x16x32_bf16 v[116:119], v[144:147], v[200:203], v[116:119]
	v_mfma_f32_16x16x32_bf16 v[112:115], v[170:173], v[200:203], v[112:115]
	v_mfma_f32_16x16x32_bf16 v[100:103], v[144:147], v[208:211], v[100:103]
	v_mfma_f32_16x16x32_bf16 v[96:99], v[170:173], v[208:211], v[96:99]
	v_mfma_f32_16x16x32_bf16 v[84:87], v[144:147], v[216:219], v[84:87]
	v_mfma_f32_16x16x32_bf16 v[80:83], v[170:173], v[216:219], v[80:83]
	v_mfma_f32_16x16x32_bf16 v[132:135], v[166:169], v[182:185], v[132:135]
	v_mfma_f32_16x16x32_bf16 v[128:131], v[174:177], v[182:185], v[128:131]
	v_mfma_f32_16x16x32_bf16 v[116:119], v[166:169], v[204:207], v[116:119]
	v_mfma_f32_16x16x32_bf16 v[112:115], v[174:177], v[204:207], v[112:115]
	v_mfma_f32_16x16x32_bf16 v[100:103], v[166:169], v[212:215], v[100:103]
	v_mfma_f32_16x16x32_bf16 v[96:99], v[174:177], v[212:215], v[96:99]
	v_mfma_f32_16x16x32_bf16 v[84:87], v[166:169], v[220:223], v[84:87]
	v_mfma_f32_16x16x32_bf16 v[80:83], v[174:177], v[220:223], v[80:83]
	s_barrier
; #define PG8_STAGE(bufoff, gbase, voff) do { _Pragma("unroll") for (int _i = 0; _i < 2; ++_i) \
;         __builtin_amdgcn_global_load_lds((const unsigned*)((const char*)(gbase) + (voff)[_i]), (PG8_LAS unsigned*)(lds + (bufoff) + ldsw + _i * 8192), 16, 0, 0); } while (0)
; #define PG8_LDA(dst, b, h) do { _Pragma("unroll") for (int m = 0; m < 4; ++m) _Pragma("unroll") for (int k = 0; k < 2; ++k) dst[m][k] = *(const PG8_LAS bf16x8*)(lds + PG8_SA(b, h) + aoff + m * 2048 + k * 1024); } while (0)
; #define PG8_MMA(ai, bj, At, Bt) do { __builtin_amdgcn_s_setprio(1); _Pragma("unroll") for (int m = 0; m < 4; ++m) _Pragma("unroll") for (int n = 0; n < 2; ++n) _Pragma("unroll") for (int k = 0; k < 2; ++k) \
;         acc[ai][bj][m][n] = __builtin_amdgcn_mfma_f32_16x16x32_bf16(Bt[n][k], At[m][k], acc[ai][bj][m][n], 0, 0, 0); __builtin_amdgcn_s_setprio(0); } while (0)
; #define PG8_WAIT_V(n) asm volatile("s_waitcnt vmcnt(" #n ")" ::: "memory")
; #define PG8_WAIT_L(n) asm volatile("s_waitcnt lgkmcnt(" #n ")" ::: "memory")
; #define PG8_BAR __builtin_amdgcn_s_barrier()
; #define PG8_SCHED __builtin_amdgcn_sched_barrier(0)
; template <class Epi, class Sched, bool ALIGN_EPI = false, bool SP2 = false>
; __device__ __forceinline__ void gemm_phase(PG8_LAS unsigned char* lds, const Gemm g, const Sched& S, const Epi& E) {
;     ...
;             PG8_LDA(At, 1, 1); PG8_STAGE(PG8_SB(1, 0), b3, voffB); PG8_STAGE(PG8_SB(1, 1), b3 + hstepB, voffB); PG8_STAGE(PG8_SA(1, 0), a3, voffA);
;             PG8_WAIT_V(8); PG8_WAIT_L(0); PG8_BAR; PG8_MMA(1, 0, At, B0); PG8_MMA(1, 1, At, B1); PG8_BAR; PG8_SCHED;
	s_add_i32 s6, s9, s68
	v_lshl_add_u64 v[162:163], v[162:163], 0, s[16:17]
	s_mov_b32 m0, s6
	ds_read_b128 v[178:181], v198 offset:49152
	ds_read_b128 v[182:185], v198 offset:50176
	ds_read_b128 v[200:203], v198 offset:51200
	ds_read_b128 v[204:207], v198 offset:52224
	ds_read_b128 v[208:211], v198 offset:53248
	ds_read_b128 v[212:215], v198 offset:54272
	ds_read_b128 v[216:219], v198 offset:55296
	ds_read_b128 v[220:223], v198 offset:56320
	global_load_lds_dwordx4 v[162:163], off
	s_add_i32 m0, s6, 0x2000
	s_add_u32 s6, s62, 0x80080
	v_lshl_add_u64 v[162:163], v[224:225], 0, s[16:17]
	s_addc_u32 s7, s63, 0
	s_add_i32 s9, s34, s68
	global_load_lds_dwordx4 v[162:163], off
	v_lshl_add_u64 v[162:163], s[6:7], 0, v[148:149]
	s_mov_b32 m0, s9
	s_nop 0
	global_load_lds_dwordx4 v[162:163], off
	v_lshl_add_u64 v[162:163], s[6:7], 0, v[150:151]
	s_add_i32 m0, s9, 0x2000
	s_nop 0
	global_load_lds_dwordx4 v[162:163], off
	v_lshl_add_u64 v[162:163], v[226:227], 0, s[16:17]
	s_mov_b32 m0, s82
	s_nop 0
	global_load_lds_dwordx4 v[162:163], off
	v_lshl_add_u64 v[162:163], v[228:229], 0, s[16:17]
	s_mov_b32 m0, s83
	s_nop 0
	global_load_lds_dwordx4 v[162:163], off
	s_waitcnt vmcnt(8)
	s_waitcnt lgkmcnt(0)
	s_barrier
	s_waitcnt lgkmcnt(0)
	v_mfma_f32_16x16x32_bf16 v[68:71], v[56:59], v[178:181], v[68:71]
	v_mfma_f32_16x16x32_bf16 v[60:63], v[72:75], v[178:181], v[60:63]
	v_mfma_f32_16x16x32_bf16 v[44:47], v[56:59], v[200:203], v[44:47]
	v_mfma_f32_16x16x32_bf16 v[40:43], v[72:75], v[200:203], v[40:43]
	v_mfma_f32_16x16x32_bf16 v[28:31], v[56:59], v[208:211], v[28:31]
	v_mfma_f32_16x16x32_bf16 v[24:27], v[72:75], v[208:211], v[24:27]
	v_mfma_f32_16x16x32_bf16 v[12:15], v[56:59], v[216:219], v[12:15]
	v_mfma_f32_16x16x32_bf16 v[8:11], v[72:75], v[216:219], v[8:11]
	v_mfma_f32_16x16x32_bf16 v[68:71], v[64:67], v[182:185], v[68:71]
	v_mfma_f32_16x16x32_bf16 v[60:63], v[76:79], v[182:185], v[60:63]
	v_mfma_f32_16x16x32_bf16 v[44:47], v[64:67], v[204:207], v[44:47]
	v_mfma_f32_16x16x32_bf16 v[40:43], v[76:79], v[204:207], v[40:43]
	v_mfma_f32_16x16x32_bf16 v[28:31], v[64:67], v[212:215], v[28:31]
	v_mfma_f32_16x16x32_bf16 v[24:27], v[76:79], v[212:215], v[24:27]
	v_mfma_f32_16x16x32_bf16 v[12:15], v[64:67], v[220:223], v[12:15]
	v_mfma_f32_16x16x32_bf16 v[8:11], v[76:79], v[220:223], v[8:11]
	v_mfma_f32_16x16x32_bf16 v[52:55], v[144:147], v[178:181], v[52:55]
	v_mfma_f32_16x16x32_bf16 v[48:51], v[170:173], v[178:181], v[48:51]
	v_mfma_f32_16x16x32_bf16 v[36:39], v[144:147], v[200:203], v[36:39]
	v_mfma_f32_16x16x32_bf16 v[32:35], v[170:173], v[200:203], v[32:35]
	v_mfma_f32_16x16x32_bf16 v[20:23], v[144:147], v[208:211], v[20:23]
	v_mfma_f32_16x16x32_bf16 v[16:19], v[170:173], v[208:211], v[16:19]
	v_mfma_f32_16x16x32_bf16 v[4:7], v[144:147], v[216:219], v[4:7]
	v_mfma_f32_16x16x32_bf16 v[0:3], v[170:173], v[216:219], v[0:3]
	v_mfma_f32_16x16x32_bf16 v[52:55], v[166:169], v[182:185], v[52:55]
	v_mfma_f32_16x16x32_bf16 v[48:51], v[174:177], v[182:185], v[48:51]
	v_mfma_f32_16x16x32_bf16 v[36:39], v[166:169], v[204:207], v[36:39]
	v_mfma_f32_16x16x32_bf16 v[32:35], v[174:177], v[204:207], v[32:35]
	v_mfma_f32_16x16x32_bf16 v[20:23], v[166:169], v[212:215], v[20:23]
	v_mfma_f32_16x16x32_bf16 v[16:19], v[174:177], v[212:215], v[16:19]
	v_mfma_f32_16x16x32_bf16 v[4:7], v[166:169], v[220:223], v[4:7]
	v_mfma_f32_16x16x32_bf16 v[0:3], v[174:177], v[220:223], v[0:3]
	s_barrier
	s_add_i32 s95, s95, 2
	s_add_u32 s58, s58, 0x100
	s_addc_u32 s59, s59, 0
	s_add_u32 s93, s93, 0x100
	s_addc_u32 s94, s94, 0
	s_cmp_gt_u32 s95, 29
	s_cbranch_scc0 .LBB0_694
	s_and_b64 vcc, exec, s[24:25]
	s_cbranch_vccz .LBB0_697
	s_barrier

; #define PG8_STAGE(bufoff, gbase, voff) do { _Pragma("unroll") for (int _i = 0; _i < 2; ++_i) \
;         __builtin_amdgcn_global_load_lds((const unsigned*)((const char*)(gbase) + (voff)[_i]), (PG8_LAS unsigned*)(lds + (bufoff) + ldsw + _i * 8192), 16, 0, 0); } while (0)
; #define PG8_LDA(dst, b, h) do { _Pragma("unroll") for (int m = 0; m < 4; ++m) _Pragma("unroll") for (int k = 0; k < 2; ++k) dst[m][k] = *(const PG8_LAS bf16x8*)(lds + PG8_SA(b, h) + aoff + m * 2048 + k * 1024); } while (0)
; #define PG8_LDB(dst, b, h) do { _Pragma("unroll") for (int n = 0; n < 2; ++n) _Pragma("unroll") for (int k = 0; k < 2; ++k) dst[n][k] = *(const PG8_LAS bf16x8*)(lds + PG8_SB(b, h) + boff + n * 2048 + k * 1024); } while (0)
; #define PG8_MMA(ai, bj, At, Bt) do { __builtin_amdgcn_s_setprio(1); _Pragma("unroll") for (int m = 0; m < 4; ++m) _Pragma("unroll") for (int n = 0; n < 2; ++n) _Pragma("unroll") for (int k = 0; k < 2; ++k) \
;         acc[ai][bj][m][n] = __builtin_amdgcn_mfma_f32_16x16x32_bf16(Bt[n][k], At[m][k], acc[ai][bj][m][n], 0, 0, 0); __builtin_amdgcn_s_setprio(0); } while (0)
; #define PG8_WAIT_V(n) asm volatile("s_waitcnt vmcnt(" #n ")" ::: "memory")
; #define PG8_WAIT_L(n) asm volatile("s_waitcnt lgkmcnt(" #n ")" ::: "memory")
; #define PG8_BAR __builtin_amdgcn_s_barrier()
; #define PG8_SCHED __builtin_amdgcn_sched_barrier(0)
; template <class Epi, class Sched, bool ALIGN_EPI = false, bool SP2 = false>
; __device__ __forceinline__ void gemm_phase(PG8_LAS unsigned char* lds, const Gemm g, const Sched& S, const Epi& E) {
;     ...
;             PG8_LDB(B0, 0, 0); PG8_LDB(B1, 0, 1); PG8_SCHED; PG8_LDA(At, 0, 0); PG8_STAGE(PG8_SA(1, 1), a1 + hstepA, voffA);
;             PG8_WAIT_V(8); PG8_WAIT_L(0); PG8_BAR; PG8_MMA(0, 0, At, B0); PG8_MMA(0, 1, At, B1); PG8_BAR; PG8_SCHED;
;             PG8_LDA(At, 0, 1); PG8_STAGE(PG8_SB(0, 0), b2, voffB); PG8_STAGE(PG8_SB(0, 1), b2 + hstepB, voffB); PG8_STAGE(PG8_SA(0, 0), a2, voffA);
;             PG8_WAIT_V(8); PG8_WAIT_L(0); PG8_BAR; PG8_MMA(1, 0, At, B0); PG8_MMA(1, 1, At, B1); PG8_BAR; PG8_SCHED;
.LBB0_874:
	ds_read_b128 v[138:141], v135
	ds_read_b128 v[142:145], v135 offset:1024
	ds_read_b128 v[152:155], v135 offset:2048
	ds_read_b128 v[156:159], v135 offset:3072
	ds_read_b128 v[160:163], v136
	ds_read_b128 v[166:169], v136 offset:1024
	ds_read_b128 v[170:173], v136 offset:2048
	ds_read_b128 v[174:177], v136 offset:3072
	s_add_u32 s6, s62, 0xfff80080
	s_addc_u32 s7, s63, -1
	s_cmp_eq_u32 s53, 4
	s_cselect_b32 s69, s55, s7
	s_cselect_b32 s68, s54, s6
	s_cselect_b32 s65, s59, s45
	s_cselect_b32 s64, s58, s41
	v_lshl_add_u64 v[146:147], s[62:63], 0, v[128:129]
	s_add_i32 m0, s15, 0xc000
	ds_read_b128 v[178:181], v137
	ds_read_b128 v[182:185], v137 offset:1024
	ds_read_b128 v[186:189], v137 offset:2048
	ds_read_b128 v[190:193], v137 offset:3072
	ds_read_b128 v[194:197], v137 offset:4096
	ds_read_b128 v[198:201], v137 offset:5120
	ds_read_b128 v[202:205], v137 offset:6144
	ds_read_b128 v[206:209], v137 offset:7168
	global_load_lds_dwordx4 v[146:147], off
	v_lshl_add_u64 v[146:147], s[62:63], 0, v[130:131]
	s_add_i32 m0, s15, 0xe000
	s_nop 0
	global_load_lds_dwordx4 v[146:147], off
	s_waitcnt vmcnt(8)
	s_waitcnt lgkmcnt(0)
	s_barrier
	s_waitcnt lgkmcnt(0)
	v_mfma_f32_16x16x32_bf16 v[124:127], v[138:141], v[178:181], v[124:127]
	v_mfma_f32_16x16x32_bf16 v[120:123], v[152:155], v[178:181], v[120:123]
	v_mfma_f32_16x16x32_bf16 v[116:119], v[138:141], v[186:189], v[116:119]
	v_mfma_f32_16x16x32_bf16 v[112:115], v[152:155], v[186:189], v[112:115]
	v_mfma_f32_16x16x32_bf16 v[104:107], v[138:141], v[194:197], v[104:107]
	v_mfma_f32_16x16x32_bf16 v[96:99], v[152:155], v[194:197], v[96:99]
	v_mfma_f32_16x16x32_bf16 v[88:91], v[138:141], v[202:205], v[88:91]
	v_mfma_f32_16x16x32_bf16 v[80:83], v[152:155], v[202:205], v[80:83]
	v_mfma_f32_16x16x32_bf16 v[124:127], v[142:145], v[182:185], v[124:127]
	v_mfma_f32_16x16x32_bf16 v[120:123], v[156:159], v[182:185], v[120:123]
	v_mfma_f32_16x16x32_bf16 v[116:119], v[142:145], v[190:193], v[116:119]
	v_mfma_f32_16x16x32_bf16 v[112:115], v[156:159], v[190:193], v[112:115]
	v_mfma_f32_16x16x32_bf16 v[104:107], v[142:145], v[198:201], v[104:107]
	v_mfma_f32_16x16x32_bf16 v[96:99], v[156:159], v[198:201], v[96:99]
	v_mfma_f32_16x16x32_bf16 v[88:91], v[142:145], v[206:209], v[88:91]
	v_mfma_f32_16x16x32_bf16 v[80:83], v[156:159], v[206:209], v[80:83]
	v_mfma_f32_16x16x32_bf16 v[108:111], v[160:163], v[178:181], v[108:111]
	v_mfma_f32_16x16x32_bf16 v[100:103], v[170:173], v[178:181], v[100:103]
	v_mfma_f32_16x16x32_bf16 v[92:95], v[160:163], v[186:189], v[92:95]
	v_mfma_f32_16x16x32_bf16 v[84:87], v[170:173], v[186:189], v[84:87]
	v_mfma_f32_16x16x32_bf16 v[76:79], v[160:163], v[194:197], v[76:79]
	v_mfma_f32_16x16x32_bf16 v[72:75], v[170:173], v[194:197], v[72:75]
	v_mfma_f32_16x16x32_bf16 v[68:71], v[160:163], v[202:205], v[68:71]
	v_mfma_f32_16x16x32_bf16 v[64:67], v[170:173], v[202:205], v[64:67]
	v_mfma_f32_16x16x32_bf16 v[108:111], v[166:169], v[182:185], v[108:111]
	v_mfma_f32_16x16x32_bf16 v[100:103], v[174:177], v[182:185], v[100:103]
	v_mfma_f32_16x16x32_bf16 v[92:95], v[166:169], v[190:193], v[92:95]
	v_mfma_f32_16x16x32_bf16 v[84:87], v[174:177], v[190:193], v[84:87]
	v_mfma_f32_16x16x32_bf16 v[76:79], v[166:169], v[198:201], v[76:79]
	v_mfma_f32_16x16x32_bf16 v[72:75], v[174:177], v[198:201], v[72:75]
	v_mfma_f32_16x16x32_bf16 v[68:71], v[166:169], v[206:209], v[68:71]
	v_mfma_f32_16x16x32_bf16 v[64:67], v[174:177], v[206:209], v[64:67]
	s_barrier
	s_add_i32 s6, s87, s72
	v_lshl_add_u64 v[146:147], s[64:65], 0, v[148:149]
	s_mov_b32 m0, s6
	ds_read_b128 v[178:181], v137 offset:16384
	ds_read_b128 v[182:185], v137 offset:17408
	ds_read_b128 v[186:189], v137 offset:18432
	ds_read_b128 v[190:193], v137 offset:19456
	ds_read_b128 v[194:197], v137 offset:20480
	ds_read_b128 v[198:201], v137 offset:21504
	ds_read_b128 v[202:205], v137 offset:22528
	ds_read_b128 v[206:209], v137 offset:23552
	global_load_lds_dwordx4 v[146:147], off
	s_add_i32 m0, s6, 0x2000
	s_add_u32 s6, s64, 0x80000
	v_lshl_add_u64 v[210:211], s[64:65], 0, v[150:151]
	s_addc_u32 s7, s65, 0
	s_add_i32 s9, s88, s72
	global_load_lds_dwordx4 v[210:211], off
	v_lshl_add_u64 v[212:213], s[6:7], 0, v[148:149]
	s_mov_b32 m0, s9
	v_lshl_add_u64 v[214:215], s[68:69], 0, v[150:151]
	global_load_lds_dwordx4 v[212:213], off
	v_lshl_add_u64 v[212:213], s[6:7], 0, v[150:151]
	s_add_i32 m0, s9, 0x2000
	s_nop 0
	global_load_lds_dwordx4 v[212:213], off
	v_lshl_add_u64 v[212:213], s[68:69], 0, v[148:149]
	s_mov_b32 m0, s15
	s_nop 0
	global_load_lds_dwordx4 v[212:213], off
	s_mov_b32 m0, s73
	s_nop 0
	global_load_lds_dwordx4 v[214:215], off
	s_waitcnt vmcnt(8)
	s_waitcnt lgkmcnt(0)
	s_barrier
; #define PG8_STAGE(bufoff, gbase, voff) do { _Pragma("unroll") for (int _i = 0; _i < 2; ++_i) \
;         __builtin_amdgcn_global_load_lds((const unsigned*)((const char*)(gbase) + (voff)[_i]), (PG8_LAS unsigned*)(lds + (bufoff) + ldsw + _i * 8192), 16, 0, 0); } while (0)
; #define PG8_LDA(dst, b, h) do { _Pragma("unroll") for (int m = 0; m < 4; ++m) _Pragma("unroll") for (int k = 0; k < 2; ++k) dst[m][k] = *(const PG8_LAS bf16x8*)(lds + PG8_SA(b, h) + aoff + m * 2048 + k * 1024); } while (0)
; #define PG8_LDB(dst, b, h) do { _Pragma("unroll") for (int n = 0; n < 2; ++n) _Pragma("unroll") for (int k = 0; k < 2; ++k) dst[n][k] = *(const PG8_LAS bf16x8*)(lds + PG8_SB(b, h) + boff + n * 2048 + k * 1024); } while (0)
; #define PG8_MMA(ai, bj, At, Bt) do { __builtin_amdgcn_s_setprio(1); _Pragma("unroll") for (int m = 0; m < 4; ++m) _Pragma("unroll") for (int n = 0; n < 2; ++n) _Pragma("unroll") for (int k = 0; k < 2; ++k) \
;         acc[ai][bj][m][n] = __builtin_amdgcn_mfma_f32_16x16x32_bf16(Bt[n][k], At[m][k], acc[ai][bj][m][n], 0, 0, 0); __builtin_amdgcn_s_setprio(0); } while (0)
; #define PG8_WAIT_V(n) asm volatile("s_waitcnt vmcnt(" #n ")" ::: "memory")
; #define PG8_WAIT_L(n) asm volatile("s_waitcnt lgkmcnt(" #n ")" ::: "memory")
; #define PG8_BAR __builtin_amdgcn_s_barrier()
; #define PG8_SCHED __builtin_amdgcn_sched_barrier(0)
; template <class Epi, class Sched, bool ALIGN_EPI = false, bool SP2 = false>
; __device__ __forceinline__ void gemm_phase(PG8_LAS unsigned char* lds, const Gemm g, const Sched& S, const Epi& E) {
;     ...
;             PG8_WAIT_V(8); PG8_WAIT_L(0); PG8_BAR; PG8_MMA(1, 0, At, B0); PG8_MMA(1, 1, At, B1); PG8_BAR; PG8_SCHED;
;             PG8_LDB(B0, 1, 0); PG8_LDB(B1, 1, 1); PG8_SCHED; PG8_LDA(At, 1, 0); PG8_STAGE(PG8_SA(0, 1), a2 + hstepA, voffA);
;             PG8_WAIT_V(8); PG8_WAIT_L(0); PG8_BAR; PG8_MMA(0, 0, At, B0); PG8_MMA(0, 1, At, B1); PG8_BAR; PG8_SCHED;
	s_waitcnt lgkmcnt(0)
	v_mfma_f32_16x16x32_bf16 v[60:63], v[138:141], v[178:181], v[60:63]
	v_mfma_f32_16x16x32_bf16 v[56:59], v[152:155], v[178:181], v[56:59]
	v_mfma_f32_16x16x32_bf16 v[52:55], v[138:141], v[186:189], v[52:55]
	v_mfma_f32_16x16x32_bf16 v[48:51], v[152:155], v[186:189], v[48:51]
	v_mfma_f32_16x16x32_bf16 v[40:43], v[138:141], v[194:197], v[40:43]
	v_mfma_f32_16x16x32_bf16 v[32:35], v[152:155], v[194:197], v[32:35]
	v_mfma_f32_16x16x32_bf16 v[24:27], v[138:141], v[202:205], v[24:27]
	v_mfma_f32_16x16x32_bf16 v[16:19], v[152:155], v[202:205], v[16:19]
	v_mfma_f32_16x16x32_bf16 v[60:63], v[142:145], v[182:185], v[60:63]
	v_mfma_f32_16x16x32_bf16 v[56:59], v[156:159], v[182:185], v[56:59]
	v_mfma_f32_16x16x32_bf16 v[52:55], v[142:145], v[190:193], v[52:55]
	v_mfma_f32_16x16x32_bf16 v[48:51], v[156:159], v[190:193], v[48:51]
	v_mfma_f32_16x16x32_bf16 v[40:43], v[142:145], v[198:201], v[40:43]
	v_mfma_f32_16x16x32_bf16 v[32:35], v[156:159], v[198:201], v[32:35]
	v_mfma_f32_16x16x32_bf16 v[24:27], v[142:145], v[206:209], v[24:27]
	v_mfma_f32_16x16x32_bf16 v[16:19], v[156:159], v[206:209], v[16:19]
	v_mfma_f32_16x16x32_bf16 v[44:47], v[160:163], v[178:181], v[44:47]
	v_mfma_f32_16x16x32_bf16 v[36:39], v[170:173], v[178:181], v[36:39]
	v_mfma_f32_16x16x32_bf16 v[28:31], v[160:163], v[186:189], v[28:31]
	v_mfma_f32_16x16x32_bf16 v[20:23], v[170:173], v[186:189], v[20:23]
	v_mfma_f32_16x16x32_bf16 v[12:15], v[160:163], v[194:197], v[12:15]
	v_mfma_f32_16x16x32_bf16 v[8:11], v[170:173], v[194:197], v[8:11]
	v_mfma_f32_16x16x32_bf16 v[4:7], v[160:163], v[202:205], v[4:7]
	v_mfma_f32_16x16x32_bf16 v[0:3], v[170:173], v[202:205], v[0:3]
	v_mfma_f32_16x16x32_bf16 v[44:47], v[166:169], v[182:185], v[44:47]
	v_mfma_f32_16x16x32_bf16 v[36:39], v[174:177], v[182:185], v[36:39]
	v_mfma_f32_16x16x32_bf16 v[28:31], v[166:169], v[190:193], v[28:31]
	v_mfma_f32_16x16x32_bf16 v[20:23], v[174:177], v[190:193], v[20:23]
	v_mfma_f32_16x16x32_bf16 v[12:15], v[166:169], v[198:201], v[12:15]
	v_mfma_f32_16x16x32_bf16 v[8:11], v[174:177], v[198:201], v[8:11]
	v_mfma_f32_16x16x32_bf16 v[4:7], v[166:169], v[206:209], v[4:7]
	v_mfma_f32_16x16x32_bf16 v[0:3], v[174:177], v[206:209], v[0:3]
	s_barrier
	s_add_i32 s9, 0, 0x18000
	s_add_i32 s34, 0, 0x1c000
	v_add_u32_e32 v156, s9, v132
	v_add_u32_e32 v174, s34, v132
	ds_read_b128 v[138:141], v156
	ds_read_b128 v[142:145], v156 offset:1024
	ds_read_b128 v[152:155], v156 offset:2048
	ds_read_b128 v[156:159], v156 offset:3072
	ds_read_b128 v[160:163], v174
	ds_read_b128 v[166:169], v174 offset:1024
	ds_read_b128 v[170:173], v174 offset:2048
	ds_read_b128 v[174:177], v174 offset:3072
	s_add_u32 s6, s68, 0x80000
	s_addc_u32 s7, s69, 0
	s_mov_b32 m0, s74
	v_lshl_add_u64 v[216:217], s[6:7], 0, v[148:149]
	ds_read_b128 v[178:181], v137 offset:32768
	ds_read_b128 v[182:185], v137 offset:33792
	ds_read_b128 v[186:189], v137 offset:34816
	ds_read_b128 v[190:193], v137 offset:35840
	ds_read_b128 v[194:197], v137 offset:36864
	ds_read_b128 v[198:201], v137 offset:37888
	ds_read_b128 v[202:205], v137 offset:38912
	ds_read_b128 v[206:209], v137 offset:39936
	global_load_lds_dwordx4 v[216:217], off
	v_lshl_add_u64 v[216:217], s[6:7], 0, v[150:151]
	s_mov_b32 m0, s75
	s_nop 0
	global_load_lds_dwordx4 v[216:217], off
	s_waitcnt vmcnt(8)
	s_waitcnt lgkmcnt(0)
	s_barrier
	s_waitcnt lgkmcnt(0)
	v_mfma_f32_16x16x32_bf16 v[124:127], v[138:141], v[178:181], v[124:127]
	v_mfma_f32_16x16x32_bf16 v[120:123], v[152:155], v[178:181], v[120:123]
	v_mfma_f32_16x16x32_bf16 v[116:119], v[138:141], v[186:189], v[116:119]
	v_mfma_f32_16x16x32_bf16 v[112:115], v[152:155], v[186:189], v[112:115]
	v_mfma_f32_16x16x32_bf16 v[104:107], v[138:141], v[194:197], v[104:107]
	v_mfma_f32_16x16x32_bf16 v[96:99], v[152:155], v[194:197], v[96:99]
	v_mfma_f32_16x16x32_bf16 v[88:91], v[138:141], v[202:205], v[88:91]
	v_mfma_f32_16x16x32_bf16 v[80:83], v[152:155], v[202:205], v[80:83]
	v_mfma_f32_16x16x32_bf16 v[124:127], v[142:145], v[182:185], v[124:127]
	v_mfma_f32_16x16x32_bf16 v[120:123], v[156:159], v[182:185], v[120:123]
	v_mfma_f32_16x16x32_bf16 v[116:119], v[142:145], v[190:193], v[116:119]
	v_mfma_f32_16x16x32_bf16 v[112:115], v[156:159], v[190:193], v[112:115]
	v_mfma_f32_16x16x32_bf16 v[104:107], v[142:145], v[198:201], v[104:107]
	v_mfma_f32_16x16x32_bf16 v[96:99], v[156:159], v[198:201], v[96:99]
	v_mfma_f32_16x16x32_bf16 v[88:91], v[142:145], v[206:209], v[88:91]
	v_mfma_f32_16x16x32_bf16 v[80:83], v[156:159], v[206:209], v[80:83]
	v_mfma_f32_16x16x32_bf16 v[108:111], v[160:163], v[178:181], v[108:111]
	v_mfma_f32_16x16x32_bf16 v[100:103], v[170:173], v[178:181], v[100:103]
	v_mfma_f32_16x16x32_bf16 v[92:95], v[160:163], v[186:189], v[92:95]
	v_mfma_f32_16x16x32_bf16 v[84:87], v[170:173], v[186:189], v[84:87]
	v_mfma_f32_16x16x32_bf16 v[76:79], v[160:163], v[194:197], v[76:79]
	v_mfma_f32_16x16x32_bf16 v[72:75], v[170:173], v[194:197], v[72:75]
	v_mfma_f32_16x16x32_bf16 v[68:71], v[160:163], v[202:205], v[68:71]
	v_mfma_f32_16x16x32_bf16 v[64:67], v[170:173], v[202:205], v[64:67]
	v_mfma_f32_16x16x32_bf16 v[108:111], v[166:169], v[182:185], v[108:111]
	v_mfma_f32_16x16x32_bf16 v[100:103], v[174:177], v[182:185], v[100:103]
	v_mfma_f32_16x16x32_bf16 v[92:95], v[166:169], v[190:193], v[92:95]
	v_mfma_f32_16x16x32_bf16 v[84:87], v[174:177], v[190:193], v[84:87]
	v_mfma_f32_16x16x32_bf16 v[76:79], v[166:169], v[198:201], v[76:79]
	v_mfma_f32_16x16x32_bf16 v[72:75], v[174:177], v[198:201], v[72:75]
	v_mfma_f32_16x16x32_bf16 v[68:71], v[166:169], v[206:209], v[68:71]
	v_mfma_f32_16x16x32_bf16 v[64:67], v[174:177], v[206:209], v[64:67]
	s_barrier
; #define PG8_STAGE(bufoff, gbase, voff) do { _Pragma("unroll") for (int _i = 0; _i < 2; ++_i) \
;         __builtin_amdgcn_global_load_lds((const unsigned*)((const char*)(gbase) + (voff)[_i]), (PG8_LAS unsigned*)(lds + (bufoff) + ldsw + _i * 8192), 16, 0, 0); } while (0)
; #define PG8_LDA(dst, b, h) do { _Pragma("unroll") for (int m = 0; m < 4; ++m) _Pragma("unroll") for (int k = 0; k < 2; ++k) dst[m][k] = *(const PG8_LAS bf16x8*)(lds + PG8_SA(b, h) + aoff + m * 2048 + k * 1024); } while (0)
; #define PG8_MMA(ai, bj, At, Bt) do { __builtin_amdgcn_s_setprio(1); _Pragma("unroll") for (int m = 0; m < 4; ++m) _Pragma("unroll") for (int n = 0; n < 2; ++n) _Pragma("unroll") for (int k = 0; k < 2; ++k) \
;         acc[ai][bj][m][n] = __builtin_amdgcn_mfma_f32_16x16x32_bf16(Bt[n][k], At[m][k], acc[ai][bj][m][n], 0, 0, 0); __builtin_amdgcn_s_setprio(0); } while (0)
; #define PG8_WAIT_V(n) asm volatile("s_waitcnt vmcnt(" #n ")" ::: "memory")
; #define PG8_WAIT_L(n) asm volatile("s_waitcnt lgkmcnt(" #n ")" ::: "memory")
; #define PG8_BAR __builtin_amdgcn_s_barrier()
; #define PG8_SCHED __builtin_amdgcn_sched_barrier(0)
; template <class Epi, class Sched, bool ALIGN_EPI = false, bool SP2 = false>
; __device__ __forceinline__ void gemm_phase(PG8_LAS unsigned char* lds, const Gemm g, const Sched& S, const Epi& E) {
;     ...
;         for (int t = 0; t < nt; t += 2) {
;             const bool last = (t == nt - 2);
;     ...
;             PG8_LDA(At, 1, 1); PG8_STAGE(PG8_SB(1, 0), b3, voffB); PG8_STAGE(PG8_SB(1, 1), b3 + hstepB, voffB); PG8_STAGE(PG8_SA(1, 0), a3, voffA);
;             PG8_WAIT_V(8); PG8_WAIT_L(0); PG8_BAR; PG8_MMA(1, 0, At, B0); PG8_MMA(1, 1, At, B1); PG8_BAR; PG8_SCHED;
	s_add_i32 s6, s9, s72
	v_lshl_add_u64 v[146:147], v[146:147], 0, s[12:13]
	s_mov_b32 m0, s6
	ds_read_b128 v[178:181], v137 offset:49152
	ds_read_b128 v[182:185], v137 offset:50176
	ds_read_b128 v[186:189], v137 offset:51200
	ds_read_b128 v[190:193], v137 offset:52224
	ds_read_b128 v[194:197], v137 offset:53248
	ds_read_b128 v[198:201], v137 offset:54272
	ds_read_b128 v[202:205], v137 offset:55296
	ds_read_b128 v[206:209], v137 offset:56320
	global_load_lds_dwordx4 v[146:147], off
	s_add_i32 m0, s6, 0x2000
	s_add_u32 s6, s64, 0x80080
	v_lshl_add_u64 v[146:147], v[210:211], 0, s[12:13]
	s_addc_u32 s7, s65, 0
	s_add_i32 s9, s34, s72
	global_load_lds_dwordx4 v[146:147], off
	v_lshl_add_u64 v[146:147], s[6:7], 0, v[148:149]
	s_mov_b32 m0, s9
	s_nop 0
	global_load_lds_dwordx4 v[146:147], off
	v_lshl_add_u64 v[146:147], s[6:7], 0, v[150:151]
	s_add_i32 m0, s9, 0x2000
	s_nop 0
	global_load_lds_dwordx4 v[146:147], off
	v_lshl_add_u64 v[146:147], v[212:213], 0, s[12:13]
	s_mov_b32 m0, s77
	s_nop 0
	global_load_lds_dwordx4 v[146:147], off
	v_lshl_add_u64 v[146:147], v[214:215], 0, s[12:13]
	s_mov_b32 m0, s82
	s_nop 0
	global_load_lds_dwordx4 v[146:147], off
	s_waitcnt vmcnt(8)
	s_waitcnt lgkmcnt(0)
	s_barrier
	s_waitcnt lgkmcnt(0)
	v_mfma_f32_16x16x32_bf16 v[60:63], v[138:141], v[178:181], v[60:63]
	v_mfma_f32_16x16x32_bf16 v[56:59], v[152:155], v[178:181], v[56:59]
	v_mfma_f32_16x16x32_bf16 v[52:55], v[138:141], v[186:189], v[52:55]
	v_mfma_f32_16x16x32_bf16 v[48:51], v[152:155], v[186:189], v[48:51]
	v_mfma_f32_16x16x32_bf16 v[40:43], v[138:141], v[194:197], v[40:43]
	v_mfma_f32_16x16x32_bf16 v[32:35], v[152:155], v[194:197], v[32:35]
	v_mfma_f32_16x16x32_bf16 v[24:27], v[138:141], v[202:205], v[24:27]
	v_mfma_f32_16x16x32_bf16 v[16:19], v[152:155], v[202:205], v[16:19]
	v_mfma_f32_16x16x32_bf16 v[60:63], v[142:145], v[182:185], v[60:63]
	v_mfma_f32_16x16x32_bf16 v[56:59], v[156:159], v[182:185], v[56:59]
	v_mfma_f32_16x16x32_bf16 v[52:55], v[142:145], v[190:193], v[52:55]
	v_mfma_f32_16x16x32_bf16 v[48:51], v[156:159], v[190:193], v[48:51]
	v_mfma_f32_16x16x32_bf16 v[40:43], v[142:145], v[198:201], v[40:43]
	v_mfma_f32_16x16x32_bf16 v[32:35], v[156:159], v[198:201], v[32:35]
	v_mfma_f32_16x16x32_bf16 v[24:27], v[142:145], v[206:209], v[24:27]
	v_mfma_f32_16x16x32_bf16 v[16:19], v[156:159], v[206:209], v[16:19]
	v_mfma_f32_16x16x32_bf16 v[44:47], v[160:163], v[178:181], v[44:47]
	v_mfma_f32_16x16x32_bf16 v[36:39], v[170:173], v[178:181], v[36:39]
	v_mfma_f32_16x16x32_bf16 v[28:31], v[160:163], v[186:189], v[28:31]
	v_mfma_f32_16x16x32_bf16 v[20:23], v[170:173], v[186:189], v[20:23]
	v_mfma_f32_16x16x32_bf16 v[12:15], v[160:163], v[194:197], v[12:15]
	v_mfma_f32_16x16x32_bf16 v[8:11], v[170:173], v[194:197], v[8:11]
	v_mfma_f32_16x16x32_bf16 v[4:7], v[160:163], v[202:205], v[4:7]
	v_mfma_f32_16x16x32_bf16 v[0:3], v[170:173], v[202:205], v[0:3]
	v_mfma_f32_16x16x32_bf16 v[44:47], v[166:169], v[182:185], v[44:47]
	v_mfma_f32_16x16x32_bf16 v[36:39], v[174:177], v[182:185], v[36:39]
	v_mfma_f32_16x16x32_bf16 v[28:31], v[166:169], v[190:193], v[28:31]
	v_mfma_f32_16x16x32_bf16 v[20:23], v[174:177], v[190:193], v[20:23]
	v_mfma_f32_16x16x32_bf16 v[12:15], v[166:169], v[198:201], v[12:15]
	v_mfma_f32_16x16x32_bf16 v[8:11], v[174:177], v[198:201], v[8:11]
	v_mfma_f32_16x16x32_bf16 v[4:7], v[166:169], v[206:209], v[4:7]
	v_mfma_f32_16x16x32_bf16 v[0:3], v[174:177], v[206:209], v[0:3]
	s_barrier
	s_add_i32 s53, s53, 2
	s_add_u32 s62, s62, 0x100
	s_addc_u32 s63, s63, 0
	s_add_u32 s41, s41, 0x100
	s_addc_u32 s45, s45, 0
	s_cmp_gt_u32 s53, 5
	s_cbranch_scc0 .LBB0_874
	s_and_b64 vcc, exec, s[16:17]
	s_cbranch_vccz .LBB0_877
	s_barrier

; #define PG8_STAGE(bufoff, gbase, voff) do { _Pragma("unroll") for (int _i = 0; _i < 2; ++_i) \
;         __builtin_amdgcn_global_load_lds((const unsigned*)((const char*)(gbase) + (voff)[_i]), (PG8_LAS unsigned*)(lds + (bufoff) + ldsw + _i * 8192), 16, 0, 0); } while (0)
; #define PG8_LDA(dst, b, h) do { _Pragma("unroll") for (int m = 0; m < 4; ++m) _Pragma("unroll") for (int k = 0; k < 2; ++k) dst[m][k] = *(const PG8_LAS bf16x8*)(lds + PG8_SA(b, h) + aoff + m * 2048 + k * 1024); } while (0)
; #define PG8_LDB(dst, b, h) do { _Pragma("unroll") for (int n = 0; n < 2; ++n) _Pragma("unroll") for (int k = 0; k < 2; ++k) dst[n][k] = *(const PG8_LAS bf16x8*)(lds + PG8_SB(b, h) + boff + n * 2048 + k * 1024); } while (0)
; #define PG8_MMA(ai, bj, At, Bt) do { __builtin_amdgcn_s_setprio(1); _Pragma("unroll") for (int m = 0; m < 4; ++m) _Pragma("unroll") for (int n = 0; n < 2; ++n) _Pragma("unroll") for (int k = 0; k < 2; ++k) \
;         acc[ai][bj][m][n] = __builtin_amdgcn_mfma_f32_16x16x32_bf16(Bt[n][k], At[m][k], acc[ai][bj][m][n], 0, 0, 0); __builtin_amdgcn_s_setprio(0); } while (0)
; #define PG8_WAIT_V(n) asm volatile("s_waitcnt vmcnt(" #n ")" ::: "memory")
; template <class Epi, class Sched, bool ALIGN_EPI = false, bool SP2 = false>
; __device__ __forceinline__ void gemm_phase(PG8_LAS unsigned char* lds, const Gemm g, const Sched& S, const Epi& E) {
;     ...
;         const char* nA = has_next ? (const char*)g.A + (size_t)nxt.pm * tstepA + (size_t)nxt.kofs * kmulA : cA; const char* nB = has_next ? (const char*)g.Bt + (size_t)nxt.pn * tstepB + (size_t)nxt.kofs * 2 : cB;
;         for (int t = 0; t < nt; t += 2) {
;             const bool last = (t == nt - 2);
;             const char* a1 = cA + (size_t)(t + 1) * kstepA;
;             const char* a2 = last ? nA : cA + (size_t)(t + 2) * kstepA; const char* b2 = last ? nB : cB + (size_t)(t + 2) * kstep;
;     ...
;             PG8_LDB(B0, 0, 0); PG8_LDB(B1, 0, 1); PG8_SCHED; PG8_LDA(At, 0, 0); PG8_STAGE(PG8_SA(1, 1), a1 + hstepA, voffA);
;             PG8_WAIT_V(8); PG8_WAIT_L(0); PG8_BAR; PG8_MMA(0, 0, At, B0); PG8_MMA(0, 1, At, B1); PG8_BAR; PG8_SCHED;
;             PG8_LDA(At, 0, 1); PG8_STAGE(PG8_SB(0, 0), b2, voffB); PG8_STAGE(PG8_SB(0, 1), b2 + hstepB, voffB); PG8_STAGE(PG8_SA(0, 0), a2, voffA);
;             PG8_WAIT_V(8); PG8_WAIT_L(0); PG8_BAR; PG8_MMA(1, 0, At, B0); PG8_MMA(1, 1, At, B1); PG8_BAR; PG8_SCHED;
.LBB0_1018:
	ds_read_b128 v[156:159], v153
	ds_read_b128 v[160:163], v153 offset:1024
	ds_read_b128 v[166:169], v153 offset:2048
	ds_read_b128 v[170:173], v153 offset:3072
	ds_read_b128 v[174:177], v154
	ds_read_b128 v[178:181], v154 offset:1024
	ds_read_b128 v[182:185], v154 offset:2048
	ds_read_b128 v[186:189], v154 offset:3072
	s_add_u32 s6, s44, 0xfff80080
	s_addc_u32 s7, s45, -1
	s_cmp_eq_u32 s87, 28
	s_cselect_b32 s55, s27, s7
	s_cselect_b32 s54, s56, s6
	s_cselect_b32 s53, s25, s86
	s_cselect_b32 s52, s57, s83
	v_lshl_add_u64 v[222:223], s[44:45], 0, v[144:145]
	s_add_i32 m0, s65, 0xc000
	ds_read_b128 v[190:193], v155
	ds_read_b128 v[194:197], v155 offset:1024
	ds_read_b128 v[198:201], v155 offset:2048
	ds_read_b128 v[202:205], v155 offset:3072
	ds_read_b128 v[206:209], v155 offset:4096
	ds_read_b128 v[210:213], v155 offset:5120
	ds_read_b128 v[214:217], v155 offset:6144
	ds_read_b128 v[218:221], v155 offset:7168
	global_load_lds_dwordx4 v[222:223], off
	v_lshl_add_u64 v[222:223], s[44:45], 0, v[146:147]
	s_add_i32 m0, s65, 0xe000
	s_nop 0
	global_load_lds_dwordx4 v[222:223], off
	s_waitcnt vmcnt(8)
	s_waitcnt lgkmcnt(0)
	s_barrier
	s_waitcnt lgkmcnt(0)
	v_mfma_f32_16x16x32_bf16 v[124:127], v[156:159], v[190:193], v[124:127]
	v_mfma_f32_16x16x32_bf16 v[120:123], v[166:169], v[190:193], v[120:123]
	v_mfma_f32_16x16x32_bf16 v[108:111], v[156:159], v[198:201], v[108:111]
	v_mfma_f32_16x16x32_bf16 v[104:107], v[166:169], v[198:201], v[104:107]
	v_mfma_f32_16x16x32_bf16 v[92:95], v[156:159], v[206:209], v[92:95]
	v_mfma_f32_16x16x32_bf16 v[88:91], v[166:169], v[206:209], v[88:91]
	v_mfma_f32_16x16x32_bf16 v[76:79], v[156:159], v[214:217], v[76:79]
	v_mfma_f32_16x16x32_bf16 v[72:75], v[166:169], v[214:217], v[72:75]
	v_mfma_f32_16x16x32_bf16 v[124:127], v[160:163], v[194:197], v[124:127]
	v_mfma_f32_16x16x32_bf16 v[120:123], v[170:173], v[194:197], v[120:123]
	v_mfma_f32_16x16x32_bf16 v[108:111], v[160:163], v[202:205], v[108:111]
	v_mfma_f32_16x16x32_bf16 v[104:107], v[170:173], v[202:205], v[104:107]
	v_mfma_f32_16x16x32_bf16 v[92:95], v[160:163], v[210:213], v[92:95]
	v_mfma_f32_16x16x32_bf16 v[88:91], v[170:173], v[210:213], v[88:91]
	v_mfma_f32_16x16x32_bf16 v[76:79], v[160:163], v[218:221], v[76:79]
	v_mfma_f32_16x16x32_bf16 v[72:75], v[170:173], v[218:221], v[72:75]
	v_mfma_f32_16x16x32_bf16 v[116:119], v[174:177], v[190:193], v[116:119]
	v_mfma_f32_16x16x32_bf16 v[112:115], v[182:185], v[190:193], v[112:115]
	v_mfma_f32_16x16x32_bf16 v[100:103], v[174:177], v[198:201], v[100:103]
	v_mfma_f32_16x16x32_bf16 v[96:99], v[182:185], v[198:201], v[96:99]
	v_mfma_f32_16x16x32_bf16 v[84:87], v[174:177], v[206:209], v[84:87]
	v_mfma_f32_16x16x32_bf16 v[80:83], v[182:185], v[206:209], v[80:83]
	v_mfma_f32_16x16x32_bf16 v[68:71], v[174:177], v[214:217], v[68:71]
	v_mfma_f32_16x16x32_bf16 v[64:67], v[182:185], v[214:217], v[64:67]
	v_mfma_f32_16x16x32_bf16 v[116:119], v[178:181], v[194:197], v[116:119]
	v_mfma_f32_16x16x32_bf16 v[112:115], v[186:189], v[194:197], v[112:115]
	v_mfma_f32_16x16x32_bf16 v[100:103], v[178:181], v[202:205], v[100:103]
	v_mfma_f32_16x16x32_bf16 v[96:99], v[186:189], v[202:205], v[96:99]
	v_mfma_f32_16x16x32_bf16 v[84:87], v[178:181], v[210:213], v[84:87]
	v_mfma_f32_16x16x32_bf16 v[80:83], v[186:189], v[210:213], v[80:83]
	v_mfma_f32_16x16x32_bf16 v[68:71], v[178:181], v[218:221], v[68:71]
	v_mfma_f32_16x16x32_bf16 v[64:67], v[186:189], v[218:221], v[64:67]
	s_barrier
	s_add_i32 s6, s77, s62
	v_lshl_add_u64 v[222:223], s[52:53], 0, v[130:131]
	s_mov_b32 m0, s6
	ds_read_b128 v[190:193], v155 offset:16384
	ds_read_b128 v[194:197], v155 offset:17408
	ds_read_b128 v[198:201], v155 offset:18432
	ds_read_b128 v[202:205], v155 offset:19456
	ds_read_b128 v[206:209], v155 offset:20480
	ds_read_b128 v[210:213], v155 offset:21504
	ds_read_b128 v[214:217], v155 offset:22528
	ds_read_b128 v[218:221], v155 offset:23552
	global_load_lds_dwordx4 v[222:223], off
	s_add_i32 m0, s6, 0x2000
	s_add_u32 s6, s52, 0x80000
	v_lshl_add_u64 v[224:225], s[52:53], 0, v[134:135]
	s_addc_u32 s7, s53, 0
	s_add_i32 s9, s82, s62
	global_load_lds_dwordx4 v[224:225], off
	v_lshl_add_u64 v[226:227], s[6:7], 0, v[130:131]
	s_mov_b32 m0, s9
	v_lshl_add_u64 v[228:229], s[54:55], 0, v[132:133]
	global_load_lds_dwordx4 v[226:227], off
	v_lshl_add_u64 v[226:227], s[6:7], 0, v[134:135]
	s_add_i32 m0, s9, 0x2000
	s_nop 0
	global_load_lds_dwordx4 v[226:227], off
	v_lshl_add_u64 v[226:227], s[54:55], 0, v[128:129]
	s_mov_b32 m0, s65
	s_nop 0
	global_load_lds_dwordx4 v[226:227], off
	s_mov_b32 m0, s68
	s_nop 0
	global_load_lds_dwordx4 v[228:229], off
	s_waitcnt vmcnt(8)
	s_waitcnt lgkmcnt(0)
	s_barrier
; #define PG8_STAGE(bufoff, gbase, voff) do { _Pragma("unroll") for (int _i = 0; _i < 2; ++_i) \
;         __builtin_amdgcn_global_load_lds((const unsigned*)((const char*)(gbase) + (voff)[_i]), (PG8_LAS unsigned*)(lds + (bufoff) + ldsw + _i * 8192), 16, 0, 0); } while (0)
; #define PG8_LDA(dst, b, h) do { _Pragma("unroll") for (int m = 0; m < 4; ++m) _Pragma("unroll") for (int k = 0; k < 2; ++k) dst[m][k] = *(const PG8_LAS bf16x8*)(lds + PG8_SA(b, h) + aoff + m * 2048 + k * 1024); } while (0)
; #define PG8_LDB(dst, b, h) do { _Pragma("unroll") for (int n = 0; n < 2; ++n) _Pragma("unroll") for (int k = 0; k < 2; ++k) dst[n][k] = *(const PG8_LAS bf16x8*)(lds + PG8_SB(b, h) + boff + n * 2048 + k * 1024); } while (0)
; #define PG8_MMA(ai, bj, At, Bt) do { __builtin_amdgcn_s_setprio(1); _Pragma("unroll") for (int m = 0; m < 4; ++m) _Pragma("unroll") for (int n = 0; n < 2; ++n) _Pragma("unroll") for (int k = 0; k < 2; ++k) \
;         acc[ai][bj][m][n] = __builtin_amdgcn_mfma_f32_16x16x32_bf16(Bt[n][k], At[m][k], acc[ai][bj][m][n], 0, 0, 0); __builtin_amdgcn_s_setprio(0); } while (0)
; #define PG8_WAIT_V(n) asm volatile("s_waitcnt vmcnt(" #n ")" ::: "memory")
; #define PG8_WAIT_L(n) asm volatile("s_waitcnt lgkmcnt(" #n ")" ::: "memory")
; #define PG8_BAR __builtin_amdgcn_s_barrier()
; #define PG8_SCHED __builtin_amdgcn_sched_barrier(0)
; template <class Epi, class Sched, bool ALIGN_EPI = false, bool SP2 = false>
; __device__ __forceinline__ void gemm_phase(PG8_LAS unsigned char* lds, const Gemm g, const Sched& S, const Epi& E) {
;     ...
;             PG8_WAIT_V(8); PG8_WAIT_L(0); PG8_BAR; PG8_MMA(1, 0, At, B0); PG8_MMA(1, 1, At, B1); PG8_BAR; PG8_SCHED;
;             PG8_LDB(B0, 1, 0); PG8_LDB(B1, 1, 1); PG8_SCHED; PG8_LDA(At, 1, 0); PG8_STAGE(PG8_SA(0, 1), a2 + hstepA, voffA);
;             PG8_WAIT_V(8); PG8_WAIT_L(0); PG8_BAR; PG8_MMA(0, 0, At, B0); PG8_MMA(0, 1, At, B1); PG8_BAR; PG8_SCHED;
	s_waitcnt lgkmcnt(0)
	v_mfma_f32_16x16x32_bf16 v[60:63], v[156:159], v[190:193], v[60:63]
	v_mfma_f32_16x16x32_bf16 v[56:59], v[166:169], v[190:193], v[56:59]
	v_mfma_f32_16x16x32_bf16 v[44:47], v[156:159], v[198:201], v[44:47]
	v_mfma_f32_16x16x32_bf16 v[40:43], v[166:169], v[198:201], v[40:43]
	v_mfma_f32_16x16x32_bf16 v[28:31], v[156:159], v[206:209], v[28:31]
	v_mfma_f32_16x16x32_bf16 v[24:27], v[166:169], v[206:209], v[24:27]
	v_mfma_f32_16x16x32_bf16 v[12:15], v[156:159], v[214:217], v[12:15]
	v_mfma_f32_16x16x32_bf16 v[8:11], v[166:169], v[214:217], v[8:11]
	v_mfma_f32_16x16x32_bf16 v[60:63], v[160:163], v[194:197], v[60:63]
	v_mfma_f32_16x16x32_bf16 v[56:59], v[170:173], v[194:197], v[56:59]
	v_mfma_f32_16x16x32_bf16 v[44:47], v[160:163], v[202:205], v[44:47]
	v_mfma_f32_16x16x32_bf16 v[40:43], v[170:173], v[202:205], v[40:43]
	v_mfma_f32_16x16x32_bf16 v[28:31], v[160:163], v[210:213], v[28:31]
	v_mfma_f32_16x16x32_bf16 v[24:27], v[170:173], v[210:213], v[24:27]
	v_mfma_f32_16x16x32_bf16 v[12:15], v[160:163], v[218:221], v[12:15]
	v_mfma_f32_16x16x32_bf16 v[8:11], v[170:173], v[218:221], v[8:11]
	v_mfma_f32_16x16x32_bf16 v[52:55], v[174:177], v[190:193], v[52:55]
	v_mfma_f32_16x16x32_bf16 v[48:51], v[182:185], v[190:193], v[48:51]
	v_mfma_f32_16x16x32_bf16 v[36:39], v[174:177], v[198:201], v[36:39]
	v_mfma_f32_16x16x32_bf16 v[32:35], v[182:185], v[198:201], v[32:35]
	v_mfma_f32_16x16x32_bf16 v[20:23], v[174:177], v[206:209], v[20:23]
	v_mfma_f32_16x16x32_bf16 v[16:19], v[182:185], v[206:209], v[16:19]
	v_mfma_f32_16x16x32_bf16 v[4:7], v[174:177], v[214:217], v[4:7]
	v_mfma_f32_16x16x32_bf16 v[0:3], v[182:185], v[214:217], v[0:3]
	v_mfma_f32_16x16x32_bf16 v[52:55], v[178:181], v[194:197], v[52:55]
	v_mfma_f32_16x16x32_bf16 v[48:51], v[186:189], v[194:197], v[48:51]
	v_mfma_f32_16x16x32_bf16 v[36:39], v[178:181], v[202:205], v[36:39]
	v_mfma_f32_16x16x32_bf16 v[32:35], v[186:189], v[202:205], v[32:35]
	v_mfma_f32_16x16x32_bf16 v[20:23], v[178:181], v[210:213], v[20:23]
	v_mfma_f32_16x16x32_bf16 v[16:19], v[186:189], v[210:213], v[16:19]
	v_mfma_f32_16x16x32_bf16 v[4:7], v[178:181], v[218:221], v[4:7]
	v_mfma_f32_16x16x32_bf16 v[0:3], v[186:189], v[218:221], v[0:3]
	s_barrier
	s_add_i32 s9, 0, 0x18000
	s_add_i32 s34, 0, 0x1c000
	v_add_u32_e32 v170, s9, v152
	v_add_u32_e32 v186, s34, v152
	ds_read_b128 v[156:159], v170
	ds_read_b128 v[160:163], v170 offset:1024
	ds_read_b128 v[166:169], v170 offset:2048
	ds_read_b128 v[170:173], v170 offset:3072
	ds_read_b128 v[174:177], v186
	ds_read_b128 v[178:181], v186 offset:1024
	ds_read_b128 v[182:185], v186 offset:2048
	ds_read_b128 v[186:189], v186 offset:3072
	s_add_u32 s6, s54, 0x80000
	s_addc_u32 s7, s55, 0
	s_mov_b32 m0, s69
	v_lshl_add_u64 v[230:231], s[6:7], 0, v[128:129]
	ds_read_b128 v[190:193], v155 offset:32768
	ds_read_b128 v[194:197], v155 offset:33792
	ds_read_b128 v[198:201], v155 offset:34816
	ds_read_b128 v[202:205], v155 offset:35840
	ds_read_b128 v[206:209], v155 offset:36864
	ds_read_b128 v[210:213], v155 offset:37888
	ds_read_b128 v[214:217], v155 offset:38912
	ds_read_b128 v[218:221], v155 offset:39936
	global_load_lds_dwordx4 v[230:231], off
	v_lshl_add_u64 v[230:231], s[6:7], 0, v[132:133]
	s_mov_b32 m0, s70
	s_nop 0
	global_load_lds_dwordx4 v[230:231], off
	s_waitcnt vmcnt(8)
	s_waitcnt lgkmcnt(0)
	s_barrier
	s_waitcnt lgkmcnt(0)
	v_mfma_f32_16x16x32_bf16 v[124:127], v[156:159], v[190:193], v[124:127]
	v_mfma_f32_16x16x32_bf16 v[120:123], v[166:169], v[190:193], v[120:123]
	v_mfma_f32_16x16x32_bf16 v[108:111], v[156:159], v[198:201], v[108:111]
	v_mfma_f32_16x16x32_bf16 v[104:107], v[166:169], v[198:201], v[104:107]
	v_mfma_f32_16x16x32_bf16 v[92:95], v[156:159], v[206:209], v[92:95]
	v_mfma_f32_16x16x32_bf16 v[88:91], v[166:169], v[206:209], v[88:91]
	v_mfma_f32_16x16x32_bf16 v[76:79], v[156:159], v[214:217], v[76:79]
	v_mfma_f32_16x16x32_bf16 v[72:75], v[166:169], v[214:217], v[72:75]
	v_mfma_f32_16x16x32_bf16 v[124:127], v[160:163], v[194:197], v[124:127]
	v_mfma_f32_16x16x32_bf16 v[120:123], v[170:173], v[194:197], v[120:123]
	v_mfma_f32_16x16x32_bf16 v[108:111], v[160:163], v[202:205], v[108:111]
	v_mfma_f32_16x16x32_bf16 v[104:107], v[170:173], v[202:205], v[104:107]
	v_mfma_f32_16x16x32_bf16 v[92:95], v[160:163], v[210:213], v[92:95]
	v_mfma_f32_16x16x32_bf16 v[88:91], v[170:173], v[210:213], v[88:91]
	v_mfma_f32_16x16x32_bf16 v[76:79], v[160:163], v[218:221], v[76:79]
	v_mfma_f32_16x16x32_bf16 v[72:75], v[170:173], v[218:221], v[72:75]
	v_mfma_f32_16x16x32_bf16 v[116:119], v[174:177], v[190:193], v[116:119]
	v_mfma_f32_16x16x32_bf16 v[112:115], v[182:185], v[190:193], v[112:115]
	v_mfma_f32_16x16x32_bf16 v[100:103], v[174:177], v[198:201], v[100:103]
	v_mfma_f32_16x16x32_bf16 v[96:99], v[182:185], v[198:201], v[96:99]
	v_mfma_f32_16x16x32_bf16 v[84:87], v[174:177], v[206:209], v[84:87]
	v_mfma_f32_16x16x32_bf16 v[80:83], v[182:185], v[206:209], v[80:83]
	v_mfma_f32_16x16x32_bf16 v[68:71], v[174:177], v[214:217], v[68:71]
	v_mfma_f32_16x16x32_bf16 v[64:67], v[182:185], v[214:217], v[64:67]
	v_mfma_f32_16x16x32_bf16 v[116:119], v[178:181], v[194:197], v[116:119]
	v_mfma_f32_16x16x32_bf16 v[112:115], v[186:189], v[194:197], v[112:115]
	v_mfma_f32_16x16x32_bf16 v[100:103], v[178:181], v[202:205], v[100:103]
	v_mfma_f32_16x16x32_bf16 v[96:99], v[186:189], v[202:205], v[96:99]
	v_mfma_f32_16x16x32_bf16 v[84:87], v[178:181], v[210:213], v[84:87]
	v_mfma_f32_16x16x32_bf16 v[80:83], v[186:189], v[210:213], v[80:83]
	v_mfma_f32_16x16x32_bf16 v[68:71], v[178:181], v[218:221], v[68:71]
	v_mfma_f32_16x16x32_bf16 v[64:67], v[186:189], v[218:221], v[64:67]
	s_barrier
; #define PG8_STAGE(bufoff, gbase, voff) do { _Pragma("unroll") for (int _i = 0; _i < 2; ++_i) \
;         __builtin_amdgcn_global_load_lds((const unsigned*)((const char*)(gbase) + (voff)[_i]), (PG8_LAS unsigned*)(lds + (bufoff) + ldsw + _i * 8192), 16, 0, 0); } while (0)
; #define PG8_LDA(dst, b, h) do { _Pragma("unroll") for (int m = 0; m < 4; ++m) _Pragma("unroll") for (int k = 0; k < 2; ++k) dst[m][k] = *(const PG8_LAS bf16x8*)(lds + PG8_SA(b, h) + aoff + m * 2048 + k * 1024); } while (0)
; #define PG8_MMA(ai, bj, At, Bt) do { __builtin_amdgcn_s_setprio(1); _Pragma("unroll") for (int m = 0; m < 4; ++m) _Pragma("unroll") for (int n = 0; n < 2; ++n) _Pragma("unroll") for (int k = 0; k < 2; ++k) \
;         acc[ai][bj][m][n] = __builtin_amdgcn_mfma_f32_16x16x32_bf16(Bt[n][k], At[m][k], acc[ai][bj][m][n], 0, 0, 0); __builtin_amdgcn_s_setprio(0); } while (0)
; #define PG8_WAIT_V(n) asm volatile("s_waitcnt vmcnt(" #n ")" ::: "memory")
; #define PG8_WAIT_L(n) asm volatile("s_waitcnt lgkmcnt(" #n ")" ::: "memory")
; #define PG8_BAR __builtin_amdgcn_s_barrier()
; #define PG8_SCHED __builtin_amdgcn_sched_barrier(0)
; template <class Epi, class Sched, bool ALIGN_EPI = false, bool SP2 = false>
; __device__ __forceinline__ void gemm_phase(PG8_LAS unsigned char* lds, const Gemm g, const Sched& S, const Epi& E) {
;     ...
;         for (int t = 0; t < nt; t += 2) {
;             const bool last = (t == nt - 2);
;     ...
;             PG8_LDA(At, 1, 1); PG8_STAGE(PG8_SB(1, 0), b3, voffB); PG8_STAGE(PG8_SB(1, 1), b3 + hstepB, voffB); PG8_STAGE(PG8_SA(1, 0), a3, voffA);
;             PG8_WAIT_V(8); PG8_WAIT_L(0); PG8_BAR; PG8_MMA(1, 0, At, B0); PG8_MMA(1, 1, At, B1); PG8_BAR; PG8_SCHED;
	s_add_i32 s6, s9, s62
	v_lshl_add_u64 v[222:223], v[222:223], 0, s[14:15]
	s_mov_b32 m0, s6
	ds_read_b128 v[190:193], v155 offset:49152
	ds_read_b128 v[194:197], v155 offset:50176
	ds_read_b128 v[198:201], v155 offset:51200
	ds_read_b128 v[202:205], v155 offset:52224
	ds_read_b128 v[206:209], v155 offset:53248
	ds_read_b128 v[210:213], v155 offset:54272
	ds_read_b128 v[214:217], v155 offset:55296
	ds_read_b128 v[218:221], v155 offset:56320
	global_load_lds_dwordx4 v[222:223], off
	s_add_i32 m0, s6, 0x2000
	s_add_u32 s6, s52, 0x80080
	v_lshl_add_u64 v[222:223], v[224:225], 0, s[14:15]
	s_addc_u32 s7, s53, 0
	s_add_i32 s9, s34, s62
	global_load_lds_dwordx4 v[222:223], off
	v_lshl_add_u64 v[222:223], s[6:7], 0, v[130:131]
	s_mov_b32 m0, s9
	s_nop 0
	global_load_lds_dwordx4 v[222:223], off
	v_lshl_add_u64 v[222:223], s[6:7], 0, v[134:135]
	s_add_i32 m0, s9, 0x2000
	s_nop 0
	global_load_lds_dwordx4 v[222:223], off
	v_lshl_add_u64 v[222:223], v[226:227], 0, s[14:15]
	s_mov_b32 m0, s73
	s_nop 0
	global_load_lds_dwordx4 v[222:223], off
	v_lshl_add_u64 v[222:223], v[228:229], 0, s[14:15]
	s_mov_b32 m0, s74
	s_nop 0
	global_load_lds_dwordx4 v[222:223], off
	s_waitcnt vmcnt(8)
	s_waitcnt lgkmcnt(0)
	s_barrier
	s_waitcnt lgkmcnt(0)
	v_mfma_f32_16x16x32_bf16 v[60:63], v[156:159], v[190:193], v[60:63]
	v_mfma_f32_16x16x32_bf16 v[56:59], v[166:169], v[190:193], v[56:59]
	v_mfma_f32_16x16x32_bf16 v[44:47], v[156:159], v[198:201], v[44:47]
	v_mfma_f32_16x16x32_bf16 v[40:43], v[166:169], v[198:201], v[40:43]
	v_mfma_f32_16x16x32_bf16 v[28:31], v[156:159], v[206:209], v[28:31]
	v_mfma_f32_16x16x32_bf16 v[24:27], v[166:169], v[206:209], v[24:27]
	v_mfma_f32_16x16x32_bf16 v[12:15], v[156:159], v[214:217], v[12:15]
	v_mfma_f32_16x16x32_bf16 v[8:11], v[166:169], v[214:217], v[8:11]
	v_mfma_f32_16x16x32_bf16 v[60:63], v[160:163], v[194:197], v[60:63]
	v_mfma_f32_16x16x32_bf16 v[56:59], v[170:173], v[194:197], v[56:59]
	v_mfma_f32_16x16x32_bf16 v[44:47], v[160:163], v[202:205], v[44:47]
	v_mfma_f32_16x16x32_bf16 v[40:43], v[170:173], v[202:205], v[40:43]
	v_mfma_f32_16x16x32_bf16 v[28:31], v[160:163], v[210:213], v[28:31]
	v_mfma_f32_16x16x32_bf16 v[24:27], v[170:173], v[210:213], v[24:27]
	v_mfma_f32_16x16x32_bf16 v[12:15], v[160:163], v[218:221], v[12:15]
	v_mfma_f32_16x16x32_bf16 v[8:11], v[170:173], v[218:221], v[8:11]
	v_mfma_f32_16x16x32_bf16 v[52:55], v[174:177], v[190:193], v[52:55]
	v_mfma_f32_16x16x32_bf16 v[48:51], v[182:185], v[190:193], v[48:51]
	v_mfma_f32_16x16x32_bf16 v[36:39], v[174:177], v[198:201], v[36:39]
	v_mfma_f32_16x16x32_bf16 v[32:35], v[182:185], v[198:201], v[32:35]
	v_mfma_f32_16x16x32_bf16 v[20:23], v[174:177], v[206:209], v[20:23]
	v_mfma_f32_16x16x32_bf16 v[16:19], v[182:185], v[206:209], v[16:19]
	v_mfma_f32_16x16x32_bf16 v[4:7], v[174:177], v[214:217], v[4:7]
	v_mfma_f32_16x16x32_bf16 v[0:3], v[182:185], v[214:217], v[0:3]
	v_mfma_f32_16x16x32_bf16 v[52:55], v[178:181], v[194:197], v[52:55]
	v_mfma_f32_16x16x32_bf16 v[48:51], v[186:189], v[194:197], v[48:51]
	v_mfma_f32_16x16x32_bf16 v[36:39], v[178:181], v[202:205], v[36:39]
	v_mfma_f32_16x16x32_bf16 v[32:35], v[186:189], v[202:205], v[32:35]
	v_mfma_f32_16x16x32_bf16 v[20:23], v[178:181], v[210:213], v[20:23]
	v_mfma_f32_16x16x32_bf16 v[16:19], v[186:189], v[210:213], v[16:19]
	v_mfma_f32_16x16x32_bf16 v[4:7], v[178:181], v[218:221], v[4:7]
	v_mfma_f32_16x16x32_bf16 v[0:3], v[186:189], v[218:221], v[0:3]
	s_barrier
	s_add_i32 s87, s87, 2
	s_add_u32 s44, s44, 0x100
	s_addc_u32 s45, s45, 0
	s_add_u32 s83, s83, 0x100
	s_addc_u32 s86, s86, 0
	s_cmp_gt_u32 s87, 29
	s_cbranch_scc0 .LBB0_1018
	s_and_b64 vcc, exec, s[16:17]
	s_cbranch_vccz .LBB0_1021
	s_barrier

; #define PG8_STAGE(bufoff, gbase, voff) do { _Pragma("unroll") for (int _i = 0; _i < 2; ++_i) \
;         __builtin_amdgcn_global_load_lds((const unsigned*)((const char*)(gbase) + (voff)[_i]), (PG8_LAS unsigned*)(lds + (bufoff) + ldsw + _i * 8192), 16, 0, 0); } while (0)
; #define PG8_LDA(dst, b, h) do { _Pragma("unroll") for (int m = 0; m < 4; ++m) _Pragma("unroll") for (int k = 0; k < 2; ++k) dst[m][k] = *(const PG8_LAS bf16x8*)(lds + PG8_SA(b, h) + aoff + m * 2048 + k * 1024); } while (0)
; #define PG8_LDB(dst, b, h) do { _Pragma("unroll") for (int n = 0; n < 2; ++n) _Pragma("unroll") for (int k = 0; k < 2; ++k) dst[n][k] = *(const PG8_LAS bf16x8*)(lds + PG8_SB(b, h) + boff + n * 2048 + k * 1024); } while (0)
; #define PG8_MMA(ai, bj, At, Bt) do { __builtin_amdgcn_s_setprio(1); _Pragma("unroll") for (int m = 0; m < 4; ++m) _Pragma("unroll") for (int n = 0; n < 2; ++n) _Pragma("unroll") for (int k = 0; k < 2; ++k) \
;         acc[ai][bj][m][n] = __builtin_amdgcn_mfma_f32_16x16x32_bf16(Bt[n][k], At[m][k], acc[ai][bj][m][n], 0, 0, 0); __builtin_amdgcn_s_setprio(0); } while (0)
; #define PG8_WAIT_V(n) asm volatile("s_waitcnt vmcnt(" #n ")" ::: "memory")
; template <class Epi, class Sched, bool ALIGN_EPI = false, bool SP2 = false>
; __device__ __forceinline__ void gemm_phase(PG8_LAS unsigned char* lds, const Gemm g, const Sched& S, const Epi& E) {
;     ...
;         const char* nA = has_next ? (const char*)g.A + (size_t)nxt.pm * tstepA + (size_t)nxt.kofs * kmulA : cA; const char* nB = has_next ? (const char*)g.Bt + (size_t)nxt.pn * tstepB + (size_t)nxt.kofs * 2 : cB;
;         for (int t = 0; t < nt; t += 2) {
;             const bool last = (t == nt - 2);
;             const char* a1 = cA + (size_t)(t + 1) * kstepA;
;             const char* a2 = last ? nA : cA + (size_t)(t + 2) * kstepA; const char* b2 = last ? nB : cB + (size_t)(t + 2) * kstep;
;     ...
;             PG8_LDB(B0, 0, 0); PG8_LDB(B1, 0, 1); PG8_SCHED; PG8_LDA(At, 0, 0); PG8_STAGE(PG8_SA(1, 1), a1 + hstepA, voffA);
;             PG8_WAIT_V(8); PG8_WAIT_L(0); PG8_BAR; PG8_MMA(0, 0, At, B0); PG8_MMA(0, 1, At, B1); PG8_BAR; PG8_SCHED;
;             PG8_LDA(At, 0, 1); PG8_STAGE(PG8_SB(0, 0), b2, voffB); PG8_STAGE(PG8_SB(0, 1), b2 + hstepB, voffB); PG8_STAGE(PG8_SA(0, 0), a2, voffA);
;             PG8_WAIT_V(8); PG8_WAIT_L(0); PG8_BAR; PG8_MMA(1, 0, At, B0); PG8_MMA(1, 1, At, B1); PG8_BAR; PG8_SCHED;
.LBB0_1097:
	ds_read_b128 v[88:91], v181
	ds_read_b128 v[96:99], v181 offset:1024
	ds_read_b128 v[108:111], v181 offset:2048
	ds_read_b128 v[112:115], v181 offset:3072
	ds_read_b128 v[158:161], v182
	ds_read_b128 v[166:169], v182 offset:1024
	ds_read_b128 v[170:173], v182 offset:2048
	ds_read_b128 v[184:187], v182 offset:3072
	s_add_u32 s6, s64, 0xffe04000
	s_addc_u32 s7, s65, -1
	s_cmpk_eq_i32 s9, 0x7c
	s_cselect_b32 s7, s57, s7
	s_cselect_b32 s6, s96, s6
	s_cselect_b32 s69, s55, vcc_hi
	s_cselect_b32 s68, s97, vcc_lo
	v_lshl_add_u64 v[162:163], s[64:65], 0, v[144:145]
	s_add_i32 m0, s72, 0xc000
	ds_read_b128 v[188:191], v183
	ds_read_b128 v[192:195], v183 offset:1024
	ds_read_b128 v[196:199], v183 offset:2048
	ds_read_b128 v[200:203], v183 offset:3072
	ds_read_b128 v[204:207], v183 offset:4096
	ds_read_b128 v[208:211], v183 offset:5120
	ds_read_b128 v[212:215], v183 offset:6144
	ds_read_b128 v[216:219], v183 offset:7168
	global_load_lds_dwordx4 v[162:163], off
	v_lshl_add_u64 v[162:163], v[162:163], 0, s[14:15]
	s_add_i32 m0, s72, 0xe000
	s_nop 0
	global_load_lds_dwordx4 v[162:163], off
	s_waitcnt vmcnt(8)
	s_waitcnt lgkmcnt(0)
	s_barrier
	s_waitcnt lgkmcnt(0)
	v_mfma_f32_16x16x32_bf16 v[140:143], v[88:91], v[188:191], v[140:143]
	v_mfma_f32_16x16x32_bf16 v[136:139], v[108:111], v[188:191], v[136:139]
	v_mfma_f32_16x16x32_bf16 v[124:127], v[88:91], v[196:199], v[124:127]
	v_mfma_f32_16x16x32_bf16 v[120:123], v[108:111], v[196:199], v[120:123]
	v_mfma_f32_16x16x32_bf16 v[100:103], v[88:91], v[204:207], v[100:103]
	v_mfma_f32_16x16x32_bf16 v[92:95], v[108:111], v[204:207], v[92:95]
	v_mfma_f32_16x16x32_bf16 v[76:79], v[88:91], v[212:215], v[76:79]
	v_mfma_f32_16x16x32_bf16 v[72:75], v[108:111], v[212:215], v[72:75]
	v_mfma_f32_16x16x32_bf16 v[140:143], v[96:99], v[192:195], v[140:143]
	v_mfma_f32_16x16x32_bf16 v[136:139], v[112:115], v[192:195], v[136:139]
	v_mfma_f32_16x16x32_bf16 v[124:127], v[96:99], v[200:203], v[124:127]
	v_mfma_f32_16x16x32_bf16 v[120:123], v[112:115], v[200:203], v[120:123]
	v_mfma_f32_16x16x32_bf16 v[100:103], v[96:99], v[208:211], v[100:103]
	v_mfma_f32_16x16x32_bf16 v[92:95], v[112:115], v[208:211], v[92:95]
	v_mfma_f32_16x16x32_bf16 v[76:79], v[96:99], v[216:219], v[76:79]
	v_mfma_f32_16x16x32_bf16 v[72:75], v[112:115], v[216:219], v[72:75]
	v_mfma_f32_16x16x32_bf16 v[132:135], v[158:161], v[188:191], v[132:135]
	v_mfma_f32_16x16x32_bf16 v[128:131], v[170:173], v[188:191], v[128:131]
	v_mfma_f32_16x16x32_bf16 v[116:119], v[158:161], v[196:199], v[116:119]
	v_mfma_f32_16x16x32_bf16 v[104:107], v[170:173], v[196:199], v[104:107]
	v_mfma_f32_16x16x32_bf16 v[84:87], v[158:161], v[204:207], v[84:87]
	v_mfma_f32_16x16x32_bf16 v[80:83], v[170:173], v[204:207], v[80:83]
	v_mfma_f32_16x16x32_bf16 v[68:71], v[158:161], v[212:215], v[68:71]
	v_mfma_f32_16x16x32_bf16 v[64:67], v[170:173], v[212:215], v[64:67]
	v_mfma_f32_16x16x32_bf16 v[132:135], v[166:169], v[192:195], v[132:135]
	v_mfma_f32_16x16x32_bf16 v[128:131], v[184:187], v[192:195], v[128:131]
	v_mfma_f32_16x16x32_bf16 v[116:119], v[166:169], v[200:203], v[116:119]
	v_mfma_f32_16x16x32_bf16 v[104:107], v[184:187], v[200:203], v[104:107]
	v_mfma_f32_16x16x32_bf16 v[84:87], v[166:169], v[208:211], v[84:87]
	v_mfma_f32_16x16x32_bf16 v[80:83], v[184:187], v[208:211], v[80:83]
	v_mfma_f32_16x16x32_bf16 v[68:71], v[166:169], v[216:219], v[68:71]
	v_mfma_f32_16x16x32_bf16 v[64:67], v[184:187], v[216:219], v[64:67]
	s_barrier
	s_add_i32 s34, s92, s71
	v_lshl_add_u64 v[162:163], s[68:69], 0, v[146:147]
	s_mov_b32 m0, s34
	ds_read_b128 v[188:191], v183 offset:16384
	ds_read_b128 v[192:195], v183 offset:17408
	ds_read_b128 v[196:199], v183 offset:18432
	ds_read_b128 v[200:203], v183 offset:19456
	ds_read_b128 v[204:207], v183 offset:20480
	ds_read_b128 v[208:211], v183 offset:21504
	ds_read_b128 v[212:215], v183 offset:22528
	ds_read_b128 v[216:219], v183 offset:23552
	global_load_lds_dwordx4 v[162:163], off
	s_add_i32 m0, s34, 0x2000
	s_add_u32 s34, s68, 0x200000
	v_lshl_add_u64 v[174:175], s[68:69], 0, v[148:149]
	s_addc_u32 s35, s69, 0
	s_add_i32 s84, s93, s71
	global_load_lds_dwordx4 v[174:175], off
	v_lshl_add_u64 v[220:221], s[34:35], 0, v[146:147]
	s_mov_b32 m0, s84
	s_nop 0
	global_load_lds_dwordx4 v[220:221], off
	v_lshl_add_u64 v[220:221], s[34:35], 0, v[148:149]
	s_add_i32 m0, s84, 0x2000
	s_nop 0
	global_load_lds_dwordx4 v[220:221], off
	v_lshl_add_u64 v[220:221], s[6:7], 0, v[144:145]
	s_mov_b32 m0, s72
	v_lshl_add_u64 v[222:223], v[220:221], 0, s[14:15]
	global_load_lds_dwordx4 v[220:221], off
	s_mov_b32 m0, s73
	s_nop 0
	global_load_lds_dwordx4 v[222:223], off
	s_waitcnt vmcnt(8)
	s_waitcnt lgkmcnt(0)
	s_barrier
; #define PG8_STAGE(bufoff, gbase, voff) do { _Pragma("unroll") for (int _i = 0; _i < 2; ++_i) \
;         __builtin_amdgcn_global_load_lds((const unsigned*)((const char*)(gbase) + (voff)[_i]), (PG8_LAS unsigned*)(lds + (bufoff) + ldsw + _i * 8192), 16, 0, 0); } while (0)
; #define PG8_LDA(dst, b, h) do { _Pragma("unroll") for (int m = 0; m < 4; ++m) _Pragma("unroll") for (int k = 0; k < 2; ++k) dst[m][k] = *(const PG8_LAS bf16x8*)(lds + PG8_SA(b, h) + aoff + m * 2048 + k * 1024); } while (0)
; #define PG8_LDB(dst, b, h) do { _Pragma("unroll") for (int n = 0; n < 2; ++n) _Pragma("unroll") for (int k = 0; k < 2; ++k) dst[n][k] = *(const PG8_LAS bf16x8*)(lds + PG8_SB(b, h) + boff + n * 2048 + k * 1024); } while (0)
; #define PG8_MMA(ai, bj, At, Bt) do { __builtin_amdgcn_s_setprio(1); _Pragma("unroll") for (int m = 0; m < 4; ++m) _Pragma("unroll") for (int n = 0; n < 2; ++n) _Pragma("unroll") for (int k = 0; k < 2; ++k) \
;         acc[ai][bj][m][n] = __builtin_amdgcn_mfma_f32_16x16x32_bf16(Bt[n][k], At[m][k], acc[ai][bj][m][n], 0, 0, 0); __builtin_amdgcn_s_setprio(0); } while (0)
; #define PG8_WAIT_V(n) asm volatile("s_waitcnt vmcnt(" #n ")" ::: "memory")
; #define PG8_WAIT_L(n) asm volatile("s_waitcnt lgkmcnt(" #n ")" ::: "memory")
; #define PG8_BAR __builtin_amdgcn_s_barrier()
; #define PG8_SCHED __builtin_amdgcn_sched_barrier(0)
; template <class Epi, class Sched, bool ALIGN_EPI = false, bool SP2 = false>
; __device__ __forceinline__ void gemm_phase(PG8_LAS unsigned char* lds, const Gemm g, const Sched& S, const Epi& E) {
;     ...
;             PG8_WAIT_V(8); PG8_WAIT_L(0); PG8_BAR; PG8_MMA(1, 0, At, B0); PG8_MMA(1, 1, At, B1); PG8_BAR; PG8_SCHED;
;             PG8_LDB(B0, 1, 0); PG8_LDB(B1, 1, 1); PG8_SCHED; PG8_LDA(At, 1, 0); PG8_STAGE(PG8_SA(0, 1), a2 + hstepA, voffA);
;             PG8_WAIT_V(8); PG8_WAIT_L(0); PG8_BAR; PG8_MMA(0, 0, At, B0); PG8_MMA(0, 1, At, B1); PG8_BAR; PG8_SCHED;
	s_waitcnt lgkmcnt(0)
	v_mfma_f32_16x16x32_bf16 v[60:63], v[88:91], v[188:191], v[60:63]
	v_mfma_f32_16x16x32_bf16 v[56:59], v[108:111], v[188:191], v[56:59]
	v_mfma_f32_16x16x32_bf16 v[44:47], v[88:91], v[196:199], v[44:47]
	v_mfma_f32_16x16x32_bf16 v[40:43], v[108:111], v[196:199], v[40:43]
	v_mfma_f32_16x16x32_bf16 v[28:31], v[88:91], v[204:207], v[28:31]
	v_mfma_f32_16x16x32_bf16 v[24:27], v[108:111], v[204:207], v[24:27]
	v_mfma_f32_16x16x32_bf16 v[12:15], v[88:91], v[212:215], v[12:15]
	v_mfma_f32_16x16x32_bf16 v[8:11], v[108:111], v[212:215], v[8:11]
	v_mfma_f32_16x16x32_bf16 v[60:63], v[96:99], v[192:195], v[60:63]
	v_mfma_f32_16x16x32_bf16 v[56:59], v[112:115], v[192:195], v[56:59]
	v_mfma_f32_16x16x32_bf16 v[44:47], v[96:99], v[200:203], v[44:47]
	v_mfma_f32_16x16x32_bf16 v[40:43], v[112:115], v[200:203], v[40:43]
	v_mfma_f32_16x16x32_bf16 v[28:31], v[96:99], v[208:211], v[28:31]
	v_mfma_f32_16x16x32_bf16 v[24:27], v[112:115], v[208:211], v[24:27]
	v_mfma_f32_16x16x32_bf16 v[12:15], v[96:99], v[216:219], v[12:15]
	v_mfma_f32_16x16x32_bf16 v[8:11], v[112:115], v[216:219], v[8:11]
	v_mfma_f32_16x16x32_bf16 v[52:55], v[158:161], v[188:191], v[52:55]
	v_mfma_f32_16x16x32_bf16 v[48:51], v[170:173], v[188:191], v[48:51]
	v_mfma_f32_16x16x32_bf16 v[36:39], v[158:161], v[196:199], v[36:39]
	v_mfma_f32_16x16x32_bf16 v[32:35], v[170:173], v[196:199], v[32:35]
	v_mfma_f32_16x16x32_bf16 v[20:23], v[158:161], v[204:207], v[20:23]
	v_mfma_f32_16x16x32_bf16 v[16:19], v[170:173], v[204:207], v[16:19]
	v_mfma_f32_16x16x32_bf16 v[4:7], v[158:161], v[212:215], v[4:7]
	v_mfma_f32_16x16x32_bf16 v[0:3], v[170:173], v[212:215], v[0:3]
	v_mfma_f32_16x16x32_bf16 v[52:55], v[166:169], v[192:195], v[52:55]
	v_mfma_f32_16x16x32_bf16 v[48:51], v[184:187], v[192:195], v[48:51]
	v_mfma_f32_16x16x32_bf16 v[36:39], v[166:169], v[200:203], v[36:39]
	v_mfma_f32_16x16x32_bf16 v[32:35], v[184:187], v[200:203], v[32:35]
	v_mfma_f32_16x16x32_bf16 v[20:23], v[166:169], v[208:211], v[20:23]
	v_mfma_f32_16x16x32_bf16 v[16:19], v[184:187], v[208:211], v[16:19]
	v_mfma_f32_16x16x32_bf16 v[4:7], v[166:169], v[216:219], v[4:7]
	v_mfma_f32_16x16x32_bf16 v[0:3], v[184:187], v[216:219], v[0:3]
	s_barrier
	s_add_i32 s6, 0, 0x18000
	s_add_i32 s34, 0, 0x1c000
	v_add_u32_e32 v112, s6, v151
	v_add_u32_e32 v152, s34, v151
	ds_read_b128 v[88:91], v112
	ds_read_b128 v[96:99], v112 offset:1024
	ds_read_b128 v[108:111], v112 offset:2048
	ds_read_b128 v[112:115], v112 offset:3072
	ds_read_b128 v[158:161], v152
	ds_read_b128 v[166:169], v152 offset:1024
	ds_read_b128 v[170:173], v152 offset:2048
	ds_read_b128 v[184:187], v152 offset:3072
	s_mov_b32 m0, s74
	v_lshl_add_u64 v[222:223], v[220:221], 0, s[12:13]
	ds_read_b128 v[188:191], v183 offset:32768
	ds_read_b128 v[192:195], v183 offset:33792
	ds_read_b128 v[196:199], v183 offset:34816
	ds_read_b128 v[200:203], v183 offset:35840
	ds_read_b128 v[204:207], v183 offset:36864
	ds_read_b128 v[208:211], v183 offset:37888
	ds_read_b128 v[212:215], v183 offset:38912
	ds_read_b128 v[216:219], v183 offset:39936
	global_load_lds_dwordx4 v[222:223], off
	v_lshl_add_u64 v[222:223], v[220:221], 0, s[16:17]
	s_mov_b32 m0, s75
	s_nop 0
	global_load_lds_dwordx4 v[222:223], off
	s_waitcnt vmcnt(8)
	s_waitcnt lgkmcnt(0)
	s_barrier
	s_waitcnt lgkmcnt(0)
	v_mfma_f32_16x16x32_bf16 v[140:143], v[88:91], v[188:191], v[140:143]
	v_mfma_f32_16x16x32_bf16 v[136:139], v[108:111], v[188:191], v[136:139]
	v_mfma_f32_16x16x32_bf16 v[124:127], v[88:91], v[196:199], v[124:127]
	v_mfma_f32_16x16x32_bf16 v[120:123], v[108:111], v[196:199], v[120:123]
	v_mfma_f32_16x16x32_bf16 v[100:103], v[88:91], v[204:207], v[100:103]
	v_mfma_f32_16x16x32_bf16 v[92:95], v[108:111], v[204:207], v[92:95]
	v_mfma_f32_16x16x32_bf16 v[76:79], v[88:91], v[212:215], v[76:79]
	v_mfma_f32_16x16x32_bf16 v[72:75], v[108:111], v[212:215], v[72:75]
	v_mfma_f32_16x16x32_bf16 v[140:143], v[96:99], v[192:195], v[140:143]
	v_mfma_f32_16x16x32_bf16 v[136:139], v[112:115], v[192:195], v[136:139]
	v_mfma_f32_16x16x32_bf16 v[124:127], v[96:99], v[200:203], v[124:127]
	v_mfma_f32_16x16x32_bf16 v[120:123], v[112:115], v[200:203], v[120:123]
	v_mfma_f32_16x16x32_bf16 v[100:103], v[96:99], v[208:211], v[100:103]
	v_mfma_f32_16x16x32_bf16 v[92:95], v[112:115], v[208:211], v[92:95]
	v_mfma_f32_16x16x32_bf16 v[76:79], v[96:99], v[216:219], v[76:79]
	v_mfma_f32_16x16x32_bf16 v[72:75], v[112:115], v[216:219], v[72:75]
	v_mfma_f32_16x16x32_bf16 v[132:135], v[158:161], v[188:191], v[132:135]
	v_mfma_f32_16x16x32_bf16 v[128:131], v[170:173], v[188:191], v[128:131]
	v_mfma_f32_16x16x32_bf16 v[116:119], v[158:161], v[196:199], v[116:119]
	v_mfma_f32_16x16x32_bf16 v[104:107], v[170:173], v[196:199], v[104:107]
	v_mfma_f32_16x16x32_bf16 v[84:87], v[158:161], v[204:207], v[84:87]
	v_mfma_f32_16x16x32_bf16 v[80:83], v[170:173], v[204:207], v[80:83]
	v_mfma_f32_16x16x32_bf16 v[68:71], v[158:161], v[212:215], v[68:71]
	v_mfma_f32_16x16x32_bf16 v[64:67], v[170:173], v[212:215], v[64:67]
	v_mfma_f32_16x16x32_bf16 v[132:135], v[166:169], v[192:195], v[132:135]
	v_mfma_f32_16x16x32_bf16 v[128:131], v[184:187], v[192:195], v[128:131]
	v_mfma_f32_16x16x32_bf16 v[116:119], v[166:169], v[200:203], v[116:119]
	v_mfma_f32_16x16x32_bf16 v[104:107], v[184:187], v[200:203], v[104:107]
	v_mfma_f32_16x16x32_bf16 v[84:87], v[166:169], v[208:211], v[84:87]
	v_mfma_f32_16x16x32_bf16 v[80:83], v[184:187], v[208:211], v[80:83]
	v_mfma_f32_16x16x32_bf16 v[68:71], v[166:169], v[216:219], v[68:71]
	v_mfma_f32_16x16x32_bf16 v[64:67], v[184:187], v[216:219], v[64:67]
	s_barrier
; #define PG8_STAGE(bufoff, gbase, voff) do { _Pragma("unroll") for (int _i = 0; _i < 2; ++_i) \
;         __builtin_amdgcn_global_load_lds((const unsigned*)((const char*)(gbase) + (voff)[_i]), (PG8_LAS unsigned*)(lds + (bufoff) + ldsw + _i * 8192), 16, 0, 0); } while (0)
; #define PG8_LDA(dst, b, h) do { _Pragma("unroll") for (int m = 0; m < 4; ++m) _Pragma("unroll") for (int k = 0; k < 2; ++k) dst[m][k] = *(const PG8_LAS bf16x8*)(lds + PG8_SA(b, h) + aoff + m * 2048 + k * 1024); } while (0)
; #define PG8_MMA(ai, bj, At, Bt) do { __builtin_amdgcn_s_setprio(1); _Pragma("unroll") for (int m = 0; m < 4; ++m) _Pragma("unroll") for (int n = 0; n < 2; ++n) _Pragma("unroll") for (int k = 0; k < 2; ++k) \
;         acc[ai][bj][m][n] = __builtin_amdgcn_mfma_f32_16x16x32_bf16(Bt[n][k], At[m][k], acc[ai][bj][m][n], 0, 0, 0); __builtin_amdgcn_s_setprio(0); } while (0)
; #define PG8_WAIT_V(n) asm volatile("s_waitcnt vmcnt(" #n ")" ::: "memory")
; #define PG8_WAIT_L(n) asm volatile("s_waitcnt lgkmcnt(" #n ")" ::: "memory")
; #define PG8_BAR __builtin_amdgcn_s_barrier()
; #define PG8_SCHED __builtin_amdgcn_sched_barrier(0)
; template <class Epi, class Sched, bool ALIGN_EPI = false, bool SP2 = false>
; __device__ __forceinline__ void gemm_phase(PG8_LAS unsigned char* lds, const Gemm g, const Sched& S, const Epi& E) {
;     ...
;         for (int t = 0; t < nt; t += 2) {
;             const bool last = (t == nt - 2);
;     ...
;             PG8_LDA(At, 1, 1); PG8_STAGE(PG8_SB(1, 0), b3, voffB); PG8_STAGE(PG8_SB(1, 1), b3 + hstepB, voffB); PG8_STAGE(PG8_SA(1, 0), a3, voffA);
;             PG8_WAIT_V(8); PG8_WAIT_L(0); PG8_BAR; PG8_MMA(1, 0, At, B0); PG8_MMA(1, 1, At, B1); PG8_BAR; PG8_SCHED;
	s_add_i32 s6, s6, s71
	v_lshl_add_u64 v[162:163], v[162:163], 0, s[36:37]
	s_mov_b32 m0, s6
	ds_read_b128 v[188:191], v183 offset:49152
	ds_read_b128 v[192:195], v183 offset:50176
	ds_read_b128 v[196:199], v183 offset:51200
	ds_read_b128 v[200:203], v183 offset:52224
	ds_read_b128 v[204:207], v183 offset:53248
	ds_read_b128 v[208:211], v183 offset:54272
	ds_read_b128 v[212:215], v183 offset:55296
	ds_read_b128 v[216:219], v183 offset:56320
	global_load_lds_dwordx4 v[162:163], off
	s_add_i32 m0, s6, 0x2000
	s_add_u32 s6, s68, 0x200080
	v_lshl_add_u64 v[162:163], v[174:175], 0, s[36:37]
	s_addc_u32 s7, s69, 0
	s_add_i32 s34, s34, s71
	global_load_lds_dwordx4 v[162:163], off
	v_lshl_add_u64 v[162:163], s[6:7], 0, v[146:147]
	s_mov_b32 m0, s34
	s_nop 0
	global_load_lds_dwordx4 v[162:163], off
	v_lshl_add_u64 v[162:163], s[6:7], 0, v[148:149]
	s_add_i32 m0, s34, 0x2000
	s_nop 0
	global_load_lds_dwordx4 v[162:163], off
	v_lshl_add_u64 v[162:163], v[220:221], 0, s[38:39]
	s_mov_b32 m0, s87
	s_nop 0
	global_load_lds_dwordx4 v[162:163], off
	v_lshl_add_u64 v[162:163], v[220:221], 0, s[40:41]
	s_mov_b32 m0, s88
	s_nop 0
	global_load_lds_dwordx4 v[162:163], off
	s_waitcnt vmcnt(8)
	s_waitcnt lgkmcnt(0)
	s_barrier
	s_waitcnt lgkmcnt(0)
	v_mfma_f32_16x16x32_bf16 v[60:63], v[88:91], v[188:191], v[60:63]
	v_mfma_f32_16x16x32_bf16 v[56:59], v[108:111], v[188:191], v[56:59]
	v_mfma_f32_16x16x32_bf16 v[44:47], v[88:91], v[196:199], v[44:47]
	v_mfma_f32_16x16x32_bf16 v[40:43], v[108:111], v[196:199], v[40:43]
	v_mfma_f32_16x16x32_bf16 v[28:31], v[88:91], v[204:207], v[28:31]
	v_mfma_f32_16x16x32_bf16 v[24:27], v[108:111], v[204:207], v[24:27]
	v_mfma_f32_16x16x32_bf16 v[12:15], v[88:91], v[212:215], v[12:15]
	v_mfma_f32_16x16x32_bf16 v[8:11], v[108:111], v[212:215], v[8:11]
	v_mfma_f32_16x16x32_bf16 v[60:63], v[96:99], v[192:195], v[60:63]
	v_mfma_f32_16x16x32_bf16 v[56:59], v[112:115], v[192:195], v[56:59]
	v_mfma_f32_16x16x32_bf16 v[44:47], v[96:99], v[200:203], v[44:47]
	v_mfma_f32_16x16x32_bf16 v[40:43], v[112:115], v[200:203], v[40:43]
	v_mfma_f32_16x16x32_bf16 v[28:31], v[96:99], v[208:211], v[28:31]
	v_mfma_f32_16x16x32_bf16 v[24:27], v[112:115], v[208:211], v[24:27]
	v_mfma_f32_16x16x32_bf16 v[12:15], v[96:99], v[216:219], v[12:15]
	v_mfma_f32_16x16x32_bf16 v[8:11], v[112:115], v[216:219], v[8:11]
	v_mfma_f32_16x16x32_bf16 v[52:55], v[158:161], v[188:191], v[52:55]
	v_mfma_f32_16x16x32_bf16 v[48:51], v[170:173], v[188:191], v[48:51]
	v_mfma_f32_16x16x32_bf16 v[36:39], v[158:161], v[196:199], v[36:39]
	v_mfma_f32_16x16x32_bf16 v[32:35], v[170:173], v[196:199], v[32:35]
	v_mfma_f32_16x16x32_bf16 v[20:23], v[158:161], v[204:207], v[20:23]
	v_mfma_f32_16x16x32_bf16 v[16:19], v[170:173], v[204:207], v[16:19]
	v_mfma_f32_16x16x32_bf16 v[4:7], v[158:161], v[212:215], v[4:7]
	v_mfma_f32_16x16x32_bf16 v[0:3], v[170:173], v[212:215], v[0:3]
	v_mfma_f32_16x16x32_bf16 v[52:55], v[166:169], v[192:195], v[52:55]
	v_mfma_f32_16x16x32_bf16 v[48:51], v[184:187], v[192:195], v[48:51]
	v_mfma_f32_16x16x32_bf16 v[36:39], v[166:169], v[200:203], v[36:39]
	v_mfma_f32_16x16x32_bf16 v[32:35], v[184:187], v[200:203], v[32:35]
	v_mfma_f32_16x16x32_bf16 v[20:23], v[166:169], v[208:211], v[20:23]
	v_mfma_f32_16x16x32_bf16 v[16:19], v[184:187], v[208:211], v[16:19]
	v_mfma_f32_16x16x32_bf16 v[4:7], v[166:169], v[216:219], v[4:7]
	v_mfma_f32_16x16x32_bf16 v[0:3], v[184:187], v[216:219], v[0:3]
	s_barrier
	s_add_i32 s9, s9, 2
	s_add_u32 vcc_lo, vcc_lo, 0x100
	s_addc_u32 vcc_hi, vcc_hi, 0
	s_add_u32 s64, s64, 0x8000
	s_addc_u32 s65, s65, 0
	s_cmpk_gt_u32 s9, 0x7d
	s_cbranch_scc0 .LBB0_1097
	s_and_b64 vcc, exec, s[44:45]
	s_cbranch_vccz .LBB0_1100
	s_barrier

; #define PG8_STAGE(bufoff, gbase, voff) do { _Pragma("unroll") for (int _i = 0; _i < 2; ++_i) \
;         __builtin_amdgcn_global_load_lds((const unsigned*)((const char*)(gbase) + (voff)[_i]), (PG8_LAS unsigned*)(lds + (bufoff) + ldsw + _i * 8192), 16, 0, 0); } while (0)
; #define PG8_LDA(dst, b, h) do { _Pragma("unroll") for (int m = 0; m < 4; ++m) _Pragma("unroll") for (int k = 0; k < 2; ++k) dst[m][k] = *(const PG8_LAS bf16x8*)(lds + PG8_SA(b, h) + aoff + m * 2048 + k * 1024); } while (0)
; #define PG8_LDB(dst, b, h) do { _Pragma("unroll") for (int n = 0; n < 2; ++n) _Pragma("unroll") for (int k = 0; k < 2; ++k) dst[n][k] = *(const PG8_LAS bf16x8*)(lds + PG8_SB(b, h) + boff + n * 2048 + k * 1024); } while (0)
; #define PG8_MMA(ai, bj, At, Bt) do { __builtin_amdgcn_s_setprio(1); _Pragma("unroll") for (int m = 0; m < 4; ++m) _Pragma("unroll") for (int n = 0; n < 2; ++n) _Pragma("unroll") for (int k = 0; k < 2; ++k) \
;         acc[ai][bj][m][n] = __builtin_amdgcn_mfma_f32_16x16x32_bf16(Bt[n][k], At[m][k], acc[ai][bj][m][n], 0, 0, 0); __builtin_amdgcn_s_setprio(0); } while (0)
; #define PG8_WAIT_V(n) asm volatile("s_waitcnt vmcnt(" #n ")" ::: "memory")
; template <class Epi, class Sched, bool ALIGN_EPI = false, bool SP2 = false>
; __device__ __forceinline__ void gemm_phase(PG8_LAS unsigned char* lds, const Gemm g, const Sched& S, const Epi& E) {
;     ...
;         const char* nA = has_next ? (const char*)g.A + (size_t)nxt.pm * tstepA + (size_t)nxt.kofs * kmulA : cA; const char* nB = has_next ? (const char*)g.Bt + (size_t)nxt.pn * tstepB + (size_t)nxt.kofs * 2 : cB;
;         for (int t = 0; t < nt; t += 2) {
;             const bool last = (t == nt - 2);
;             const char* a1 = cA + (size_t)(t + 1) * kstepA;
;             const char* a2 = last ? nA : cA + (size_t)(t + 2) * kstepA; const char* b2 = last ? nB : cB + (size_t)(t + 2) * kstep;
;     ...
;             PG8_LDB(B0, 0, 0); PG8_LDB(B1, 0, 1); PG8_SCHED; PG8_LDA(At, 0, 0); PG8_STAGE(PG8_SA(1, 1), a1 + hstepA, voffA);
;             PG8_WAIT_V(8); PG8_WAIT_L(0); PG8_BAR; PG8_MMA(0, 0, At, B0); PG8_MMA(0, 1, At, B1); PG8_BAR; PG8_SCHED;
;             PG8_LDA(At, 0, 1); PG8_STAGE(PG8_SB(0, 0), b2, voffB); PG8_STAGE(PG8_SB(0, 1), b2 + hstepB, voffB); PG8_STAGE(PG8_SA(0, 0), a2, voffA);
;             PG8_WAIT_V(8); PG8_WAIT_L(0); PG8_BAR; PG8_MMA(1, 0, At, B0); PG8_MMA(1, 1, At, B1); PG8_BAR; PG8_SCHED;
.LBB0_1117:
	ds_read_b128 v[134:137], v131
	ds_read_b128 v[138:141], v131 offset:1024
	ds_read_b128 v[150:153], v131 offset:2048
	ds_read_b128 v[154:157], v131 offset:3072
	ds_read_b128 v[158:161], v132
	ds_read_b128 v[166:169], v132 offset:1024
	ds_read_b128 v[170:173], v132 offset:2048
	ds_read_b128 v[174:177], v132 offset:3072
	s_add_u32 s6, s72, 0xffe04000
	s_addc_u32 s7, s73, -1
	s_cmp_eq_u32 s65, 28
	s_cselect_b32 s7, s69, s7
	s_cselect_b32 s6, s68, s6
	s_cselect_b32 s75, s71, s63
	s_cselect_b32 s74, s70, s59
	v_lshl_add_u64 v[142:143], s[72:73], 0, v[144:145]
	s_add_i32 m0, s17, 0xc000
	ds_read_b128 v[178:181], v133
	ds_read_b128 v[182:185], v133 offset:1024
	ds_read_b128 v[186:189], v133 offset:2048
	ds_read_b128 v[190:193], v133 offset:3072
	ds_read_b128 v[194:197], v133 offset:4096
	ds_read_b128 v[198:201], v133 offset:5120
	ds_read_b128 v[202:205], v133 offset:6144
	ds_read_b128 v[206:209], v133 offset:7168
	global_load_lds_dwordx4 v[142:143], off
	v_lshl_add_u64 v[142:143], v[142:143], 0, s[36:37]
	s_add_i32 m0, s17, 0xe000
	s_nop 0
	global_load_lds_dwordx4 v[142:143], off
	s_waitcnt vmcnt(8)
	s_waitcnt lgkmcnt(0)
	s_barrier
	s_waitcnt lgkmcnt(0)
	v_mfma_f32_16x16x32_bf16 v[124:127], v[134:137], v[178:181], v[124:127]
	v_mfma_f32_16x16x32_bf16 v[120:123], v[150:153], v[178:181], v[120:123]
	v_mfma_f32_16x16x32_bf16 v[116:119], v[134:137], v[186:189], v[116:119]
	v_mfma_f32_16x16x32_bf16 v[112:115], v[150:153], v[186:189], v[112:115]
	v_mfma_f32_16x16x32_bf16 v[104:107], v[134:137], v[194:197], v[104:107]
	v_mfma_f32_16x16x32_bf16 v[96:99], v[150:153], v[194:197], v[96:99]
	v_mfma_f32_16x16x32_bf16 v[88:91], v[134:137], v[202:205], v[88:91]
	v_mfma_f32_16x16x32_bf16 v[80:83], v[150:153], v[202:205], v[80:83]
	v_mfma_f32_16x16x32_bf16 v[124:127], v[138:141], v[182:185], v[124:127]
	v_mfma_f32_16x16x32_bf16 v[120:123], v[154:157], v[182:185], v[120:123]
	v_mfma_f32_16x16x32_bf16 v[116:119], v[138:141], v[190:193], v[116:119]
	v_mfma_f32_16x16x32_bf16 v[112:115], v[154:157], v[190:193], v[112:115]
	v_mfma_f32_16x16x32_bf16 v[104:107], v[138:141], v[198:201], v[104:107]
	v_mfma_f32_16x16x32_bf16 v[96:99], v[154:157], v[198:201], v[96:99]
	v_mfma_f32_16x16x32_bf16 v[88:91], v[138:141], v[206:209], v[88:91]
	v_mfma_f32_16x16x32_bf16 v[80:83], v[154:157], v[206:209], v[80:83]
	v_mfma_f32_16x16x32_bf16 v[108:111], v[158:161], v[178:181], v[108:111]
	v_mfma_f32_16x16x32_bf16 v[100:103], v[170:173], v[178:181], v[100:103]
	v_mfma_f32_16x16x32_bf16 v[92:95], v[158:161], v[186:189], v[92:95]
	v_mfma_f32_16x16x32_bf16 v[84:87], v[170:173], v[186:189], v[84:87]
	v_mfma_f32_16x16x32_bf16 v[76:79], v[158:161], v[194:197], v[76:79]
	v_mfma_f32_16x16x32_bf16 v[72:75], v[170:173], v[194:197], v[72:75]
	v_mfma_f32_16x16x32_bf16 v[68:71], v[158:161], v[202:205], v[68:71]
	v_mfma_f32_16x16x32_bf16 v[64:67], v[170:173], v[202:205], v[64:67]
	v_mfma_f32_16x16x32_bf16 v[108:111], v[166:169], v[182:185], v[108:111]
	v_mfma_f32_16x16x32_bf16 v[100:103], v[174:177], v[182:185], v[100:103]
	v_mfma_f32_16x16x32_bf16 v[92:95], v[166:169], v[190:193], v[92:95]
	v_mfma_f32_16x16x32_bf16 v[84:87], v[174:177], v[190:193], v[84:87]
	v_mfma_f32_16x16x32_bf16 v[76:79], v[166:169], v[198:201], v[76:79]
	v_mfma_f32_16x16x32_bf16 v[72:75], v[174:177], v[198:201], v[72:75]
	v_mfma_f32_16x16x32_bf16 v[68:71], v[166:169], v[206:209], v[68:71]
	v_mfma_f32_16x16x32_bf16 v[64:67], v[174:177], v[206:209], v[64:67]
	s_barrier
	s_add_i32 s9, s93, s82
	v_lshl_add_u64 v[142:143], s[74:75], 0, v[146:147]
	s_mov_b32 m0, s9
	ds_read_b128 v[178:181], v133 offset:16384
	ds_read_b128 v[182:185], v133 offset:17408
	ds_read_b128 v[186:189], v133 offset:18432
	ds_read_b128 v[190:193], v133 offset:19456
	ds_read_b128 v[194:197], v133 offset:20480
	ds_read_b128 v[198:201], v133 offset:21504
	ds_read_b128 v[202:205], v133 offset:22528
	ds_read_b128 v[206:209], v133 offset:23552
	global_load_lds_dwordx4 v[142:143], off
	s_add_i32 m0, s9, 0x2000
	s_add_u32 s34, s74, 0x200000
	v_lshl_add_u64 v[162:163], s[74:75], 0, v[148:149]
	s_addc_u32 s35, s75, 0
	s_add_i32 s9, s94, s82
	global_load_lds_dwordx4 v[162:163], off
	v_lshl_add_u64 v[210:211], s[34:35], 0, v[146:147]
	s_mov_b32 m0, s9
	s_nop 0
	global_load_lds_dwordx4 v[210:211], off
	v_lshl_add_u64 v[210:211], s[34:35], 0, v[148:149]
	s_add_i32 m0, s9, 0x2000
	s_nop 0
	global_load_lds_dwordx4 v[210:211], off
	v_lshl_add_u64 v[210:211], s[6:7], 0, v[144:145]
	s_mov_b32 m0, s17
	v_lshl_add_u64 v[212:213], v[210:211], 0, s[36:37]
	global_load_lds_dwordx4 v[210:211], off
	s_mov_b32 m0, s83
	s_nop 0
	global_load_lds_dwordx4 v[212:213], off
	s_waitcnt vmcnt(8)
	s_waitcnt lgkmcnt(0)
	s_barrier
; #define PG8_STAGE(bufoff, gbase, voff) do { _Pragma("unroll") for (int _i = 0; _i < 2; ++_i) \
;         __builtin_amdgcn_global_load_lds((const unsigned*)((const char*)(gbase) + (voff)[_i]), (PG8_LAS unsigned*)(lds + (bufoff) + ldsw + _i * 8192), 16, 0, 0); } while (0)
; #define PG8_LDA(dst, b, h) do { _Pragma("unroll") for (int m = 0; m < 4; ++m) _Pragma("unroll") for (int k = 0; k < 2; ++k) dst[m][k] = *(const PG8_LAS bf16x8*)(lds + PG8_SA(b, h) + aoff + m * 2048 + k * 1024); } while (0)
; #define PG8_LDB(dst, b, h) do { _Pragma("unroll") for (int n = 0; n < 2; ++n) _Pragma("unroll") for (int k = 0; k < 2; ++k) dst[n][k] = *(const PG8_LAS bf16x8*)(lds + PG8_SB(b, h) + boff + n * 2048 + k * 1024); } while (0)
; #define PG8_MMA(ai, bj, At, Bt) do { __builtin_amdgcn_s_setprio(1); _Pragma("unroll") for (int m = 0; m < 4; ++m) _Pragma("unroll") for (int n = 0; n < 2; ++n) _Pragma("unroll") for (int k = 0; k < 2; ++k) \
;         acc[ai][bj][m][n] = __builtin_amdgcn_mfma_f32_16x16x32_bf16(Bt[n][k], At[m][k], acc[ai][bj][m][n], 0, 0, 0); __builtin_amdgcn_s_setprio(0); } while (0)
; #define PG8_WAIT_V(n) asm volatile("s_waitcnt vmcnt(" #n ")" ::: "memory")
; #define PG8_WAIT_L(n) asm volatile("s_waitcnt lgkmcnt(" #n ")" ::: "memory")
; #define PG8_BAR __builtin_amdgcn_s_barrier()
; #define PG8_SCHED __builtin_amdgcn_sched_barrier(0)
; template <class Epi, class Sched, bool ALIGN_EPI = false, bool SP2 = false>
; __device__ __forceinline__ void gemm_phase(PG8_LAS unsigned char* lds, const Gemm g, const Sched& S, const Epi& E) {
;     ...
;             PG8_WAIT_V(8); PG8_WAIT_L(0); PG8_BAR; PG8_MMA(1, 0, At, B0); PG8_MMA(1, 1, At, B1); PG8_BAR; PG8_SCHED;
;             PG8_LDB(B0, 1, 0); PG8_LDB(B1, 1, 1); PG8_SCHED; PG8_LDA(At, 1, 0); PG8_STAGE(PG8_SA(0, 1), a2 + hstepA, voffA);
;             PG8_WAIT_V(8); PG8_WAIT_L(0); PG8_BAR; PG8_MMA(0, 0, At, B0); PG8_MMA(0, 1, At, B1); PG8_BAR; PG8_SCHED;
	s_waitcnt lgkmcnt(0)
	v_mfma_f32_16x16x32_bf16 v[60:63], v[134:137], v[178:181], v[60:63]
	v_mfma_f32_16x16x32_bf16 v[56:59], v[150:153], v[178:181], v[56:59]
	v_mfma_f32_16x16x32_bf16 v[52:55], v[134:137], v[186:189], v[52:55]
	v_mfma_f32_16x16x32_bf16 v[48:51], v[150:153], v[186:189], v[48:51]
	v_mfma_f32_16x16x32_bf16 v[40:43], v[134:137], v[194:197], v[40:43]
	v_mfma_f32_16x16x32_bf16 v[32:35], v[150:153], v[194:197], v[32:35]
	v_mfma_f32_16x16x32_bf16 v[24:27], v[134:137], v[202:205], v[24:27]
	v_mfma_f32_16x16x32_bf16 v[16:19], v[150:153], v[202:205], v[16:19]
	v_mfma_f32_16x16x32_bf16 v[60:63], v[138:141], v[182:185], v[60:63]
	v_mfma_f32_16x16x32_bf16 v[56:59], v[154:157], v[182:185], v[56:59]
	v_mfma_f32_16x16x32_bf16 v[52:55], v[138:141], v[190:193], v[52:55]
	v_mfma_f32_16x16x32_bf16 v[48:51], v[154:157], v[190:193], v[48:51]
	v_mfma_f32_16x16x32_bf16 v[40:43], v[138:141], v[198:201], v[40:43]
	v_mfma_f32_16x16x32_bf16 v[32:35], v[154:157], v[198:201], v[32:35]
	v_mfma_f32_16x16x32_bf16 v[24:27], v[138:141], v[206:209], v[24:27]
	v_mfma_f32_16x16x32_bf16 v[16:19], v[154:157], v[206:209], v[16:19]
	v_mfma_f32_16x16x32_bf16 v[44:47], v[158:161], v[178:181], v[44:47]
	v_mfma_f32_16x16x32_bf16 v[36:39], v[170:173], v[178:181], v[36:39]
	v_mfma_f32_16x16x32_bf16 v[28:31], v[158:161], v[186:189], v[28:31]
	v_mfma_f32_16x16x32_bf16 v[20:23], v[170:173], v[186:189], v[20:23]
	v_mfma_f32_16x16x32_bf16 v[12:15], v[158:161], v[194:197], v[12:15]
	v_mfma_f32_16x16x32_bf16 v[8:11], v[170:173], v[194:197], v[8:11]
	v_mfma_f32_16x16x32_bf16 v[4:7], v[158:161], v[202:205], v[4:7]
	v_mfma_f32_16x16x32_bf16 v[0:3], v[170:173], v[202:205], v[0:3]
	v_mfma_f32_16x16x32_bf16 v[44:47], v[166:169], v[182:185], v[44:47]
	v_mfma_f32_16x16x32_bf16 v[36:39], v[174:177], v[182:185], v[36:39]
	v_mfma_f32_16x16x32_bf16 v[28:31], v[166:169], v[190:193], v[28:31]
	v_mfma_f32_16x16x32_bf16 v[20:23], v[174:177], v[190:193], v[20:23]
	v_mfma_f32_16x16x32_bf16 v[12:15], v[166:169], v[198:201], v[12:15]
	v_mfma_f32_16x16x32_bf16 v[8:11], v[174:177], v[198:201], v[8:11]
	v_mfma_f32_16x16x32_bf16 v[4:7], v[166:169], v[206:209], v[4:7]
	v_mfma_f32_16x16x32_bf16 v[0:3], v[174:177], v[206:209], v[0:3]
	s_barrier
	s_add_i32 s9, 0, 0x18000
	s_add_i32 s34, 0, 0x1c000
	v_add_u32_e32 v154, s9, v128
	v_add_u32_e32 v174, s34, v128
	ds_read_b128 v[134:137], v154
	ds_read_b128 v[138:141], v154 offset:1024
	ds_read_b128 v[150:153], v154 offset:2048
	ds_read_b128 v[154:157], v154 offset:3072
	ds_read_b128 v[158:161], v174
	ds_read_b128 v[166:169], v174 offset:1024
	ds_read_b128 v[170:173], v174 offset:2048
	ds_read_b128 v[174:177], v174 offset:3072
	s_mov_b64 s[6:7], 0x200000
	s_mov_b32 m0, s86
	v_lshl_add_u64 v[212:213], v[210:211], 0, s[6:7]
	ds_read_b128 v[178:181], v133 offset:32768
	ds_read_b128 v[182:185], v133 offset:33792
	ds_read_b128 v[186:189], v133 offset:34816
	ds_read_b128 v[190:193], v133 offset:35840
	ds_read_b128 v[194:197], v133 offset:36864
	ds_read_b128 v[198:201], v133 offset:37888
	ds_read_b128 v[202:205], v133 offset:38912
	ds_read_b128 v[206:209], v133 offset:39936
	global_load_lds_dwordx4 v[212:213], off
	v_lshl_add_u64 v[212:213], v[210:211], 0, s[38:39]
	s_mov_b32 m0, s87
	s_nop 0
	global_load_lds_dwordx4 v[212:213], off
	s_waitcnt vmcnt(8)
	s_waitcnt lgkmcnt(0)
	s_barrier
	s_waitcnt lgkmcnt(0)
	v_mfma_f32_16x16x32_bf16 v[124:127], v[134:137], v[178:181], v[124:127]
	v_mfma_f32_16x16x32_bf16 v[120:123], v[150:153], v[178:181], v[120:123]
	v_mfma_f32_16x16x32_bf16 v[116:119], v[134:137], v[186:189], v[116:119]
	v_mfma_f32_16x16x32_bf16 v[112:115], v[150:153], v[186:189], v[112:115]
	v_mfma_f32_16x16x32_bf16 v[104:107], v[134:137], v[194:197], v[104:107]
	v_mfma_f32_16x16x32_bf16 v[96:99], v[150:153], v[194:197], v[96:99]
	v_mfma_f32_16x16x32_bf16 v[88:91], v[134:137], v[202:205], v[88:91]
	v_mfma_f32_16x16x32_bf16 v[80:83], v[150:153], v[202:205], v[80:83]
	v_mfma_f32_16x16x32_bf16 v[124:127], v[138:141], v[182:185], v[124:127]
	v_mfma_f32_16x16x32_bf16 v[120:123], v[154:157], v[182:185], v[120:123]
	v_mfma_f32_16x16x32_bf16 v[116:119], v[138:141], v[190:193], v[116:119]
	v_mfma_f32_16x16x32_bf16 v[112:115], v[154:157], v[190:193], v[112:115]
	v_mfma_f32_16x16x32_bf16 v[104:107], v[138:141], v[198:201], v[104:107]
	v_mfma_f32_16x16x32_bf16 v[96:99], v[154:157], v[198:201], v[96:99]
	v_mfma_f32_16x16x32_bf16 v[88:91], v[138:141], v[206:209], v[88:91]
	v_mfma_f32_16x16x32_bf16 v[80:83], v[154:157], v[206:209], v[80:83]
	v_mfma_f32_16x16x32_bf16 v[108:111], v[158:161], v[178:181], v[108:111]
	v_mfma_f32_16x16x32_bf16 v[100:103], v[170:173], v[178:181], v[100:103]
	v_mfma_f32_16x16x32_bf16 v[92:95], v[158:161], v[186:189], v[92:95]
	v_mfma_f32_16x16x32_bf16 v[84:87], v[170:173], v[186:189], v[84:87]
	v_mfma_f32_16x16x32_bf16 v[76:79], v[158:161], v[194:197], v[76:79]
	v_mfma_f32_16x16x32_bf16 v[72:75], v[170:173], v[194:197], v[72:75]
	v_mfma_f32_16x16x32_bf16 v[68:71], v[158:161], v[202:205], v[68:71]
	v_mfma_f32_16x16x32_bf16 v[64:67], v[170:173], v[202:205], v[64:67]
	v_mfma_f32_16x16x32_bf16 v[108:111], v[166:169], v[182:185], v[108:111]
	v_mfma_f32_16x16x32_bf16 v[100:103], v[174:177], v[182:185], v[100:103]
	v_mfma_f32_16x16x32_bf16 v[92:95], v[166:169], v[190:193], v[92:95]
	v_mfma_f32_16x16x32_bf16 v[84:87], v[174:177], v[190:193], v[84:87]
	v_mfma_f32_16x16x32_bf16 v[76:79], v[166:169], v[198:201], v[76:79]
	v_mfma_f32_16x16x32_bf16 v[72:75], v[174:177], v[198:201], v[72:75]
	v_mfma_f32_16x16x32_bf16 v[68:71], v[166:169], v[206:209], v[68:71]
	v_mfma_f32_16x16x32_bf16 v[64:67], v[174:177], v[206:209], v[64:67]
	s_barrier
; #define PG8_STAGE(bufoff, gbase, voff) do { _Pragma("unroll") for (int _i = 0; _i < 2; ++_i) \
;         __builtin_amdgcn_global_load_lds((const unsigned*)((const char*)(gbase) + (voff)[_i]), (PG8_LAS unsigned*)(lds + (bufoff) + ldsw + _i * 8192), 16, 0, 0); } while (0)
; #define PG8_LDA(dst, b, h) do { _Pragma("unroll") for (int m = 0; m < 4; ++m) _Pragma("unroll") for (int k = 0; k < 2; ++k) dst[m][k] = *(const PG8_LAS bf16x8*)(lds + PG8_SA(b, h) + aoff + m * 2048 + k * 1024); } while (0)
; #define PG8_MMA(ai, bj, At, Bt) do { __builtin_amdgcn_s_setprio(1); _Pragma("unroll") for (int m = 0; m < 4; ++m) _Pragma("unroll") for (int n = 0; n < 2; ++n) _Pragma("unroll") for (int k = 0; k < 2; ++k) \
;         acc[ai][bj][m][n] = __builtin_amdgcn_mfma_f32_16x16x32_bf16(Bt[n][k], At[m][k], acc[ai][bj][m][n], 0, 0, 0); __builtin_amdgcn_s_setprio(0); } while (0)
; #define PG8_WAIT_V(n) asm volatile("s_waitcnt vmcnt(" #n ")" ::: "memory")
; #define PG8_WAIT_L(n) asm volatile("s_waitcnt lgkmcnt(" #n ")" ::: "memory")
; #define PG8_BAR __builtin_amdgcn_s_barrier()
; #define PG8_SCHED __builtin_amdgcn_sched_barrier(0)
; template <class Epi, class Sched, bool ALIGN_EPI = false, bool SP2 = false>
; __device__ __forceinline__ void gemm_phase(PG8_LAS unsigned char* lds, const Gemm g, const Sched& S, const Epi& E) {
;     ...
;         for (int t = 0; t < nt; t += 2) {
;             const bool last = (t == nt - 2);
;     ...
;             PG8_LDA(At, 1, 1); PG8_STAGE(PG8_SB(1, 0), b3, voffB); PG8_STAGE(PG8_SB(1, 1), b3 + hstepB, voffB); PG8_STAGE(PG8_SA(1, 0), a3, voffA);
;             PG8_WAIT_V(8); PG8_WAIT_L(0); PG8_BAR; PG8_MMA(1, 0, At, B0); PG8_MMA(1, 1, At, B1); PG8_BAR; PG8_SCHED;
	s_add_i32 s6, s9, s82
	v_lshl_add_u64 v[142:143], v[142:143], 0, s[14:15]
	s_mov_b32 m0, s6
	ds_read_b128 v[178:181], v133 offset:49152
	ds_read_b128 v[182:185], v133 offset:50176
	ds_read_b128 v[186:189], v133 offset:51200
	ds_read_b128 v[190:193], v133 offset:52224
	ds_read_b128 v[194:197], v133 offset:53248
	ds_read_b128 v[198:201], v133 offset:54272
	ds_read_b128 v[202:205], v133 offset:55296
	ds_read_b128 v[206:209], v133 offset:56320
	global_load_lds_dwordx4 v[142:143], off
	s_add_i32 m0, s6, 0x2000
	s_add_u32 s6, s74, 0x200080
	v_lshl_add_u64 v[142:143], v[162:163], 0, s[14:15]
	s_addc_u32 s7, s75, 0
	s_add_i32 s9, s34, s82
	global_load_lds_dwordx4 v[142:143], off
	v_lshl_add_u64 v[142:143], s[6:7], 0, v[146:147]
	s_mov_b32 m0, s9
	s_nop 0
	global_load_lds_dwordx4 v[142:143], off
	v_lshl_add_u64 v[142:143], s[6:7], 0, v[148:149]
	s_add_i32 m0, s9, 0x2000
	s_nop 0
	global_load_lds_dwordx4 v[142:143], off
	v_lshl_add_u64 v[142:143], v[210:211], 0, s[24:25]
	s_mov_b32 m0, s91
	s_nop 0
	global_load_lds_dwordx4 v[142:143], off
	v_lshl_add_u64 v[142:143], v[210:211], 0, s[40:41]
	s_mov_b32 m0, s92
	s_nop 0
	global_load_lds_dwordx4 v[142:143], off
	s_waitcnt vmcnt(8)
	s_waitcnt lgkmcnt(0)
	s_barrier
	s_waitcnt lgkmcnt(0)
	v_mfma_f32_16x16x32_bf16 v[60:63], v[134:137], v[178:181], v[60:63]
	v_mfma_f32_16x16x32_bf16 v[56:59], v[150:153], v[178:181], v[56:59]
	v_mfma_f32_16x16x32_bf16 v[52:55], v[134:137], v[186:189], v[52:55]
	v_mfma_f32_16x16x32_bf16 v[48:51], v[150:153], v[186:189], v[48:51]
	v_mfma_f32_16x16x32_bf16 v[40:43], v[134:137], v[194:197], v[40:43]
	v_mfma_f32_16x16x32_bf16 v[32:35], v[150:153], v[194:197], v[32:35]
	v_mfma_f32_16x16x32_bf16 v[24:27], v[134:137], v[202:205], v[24:27]
	v_mfma_f32_16x16x32_bf16 v[16:19], v[150:153], v[202:205], v[16:19]
	v_mfma_f32_16x16x32_bf16 v[60:63], v[138:141], v[182:185], v[60:63]
	v_mfma_f32_16x16x32_bf16 v[56:59], v[154:157], v[182:185], v[56:59]
	v_mfma_f32_16x16x32_bf16 v[52:55], v[138:141], v[190:193], v[52:55]
	v_mfma_f32_16x16x32_bf16 v[48:51], v[154:157], v[190:193], v[48:51]
	v_mfma_f32_16x16x32_bf16 v[40:43], v[138:141], v[198:201], v[40:43]
	v_mfma_f32_16x16x32_bf16 v[32:35], v[154:157], v[198:201], v[32:35]
	v_mfma_f32_16x16x32_bf16 v[24:27], v[138:141], v[206:209], v[24:27]
	v_mfma_f32_16x16x32_bf16 v[16:19], v[154:157], v[206:209], v[16:19]
	v_mfma_f32_16x16x32_bf16 v[44:47], v[158:161], v[178:181], v[44:47]
	v_mfma_f32_16x16x32_bf16 v[36:39], v[170:173], v[178:181], v[36:39]
	v_mfma_f32_16x16x32_bf16 v[28:31], v[158:161], v[186:189], v[28:31]
	v_mfma_f32_16x16x32_bf16 v[20:23], v[170:173], v[186:189], v[20:23]
	v_mfma_f32_16x16x32_bf16 v[12:15], v[158:161], v[194:197], v[12:15]
	v_mfma_f32_16x16x32_bf16 v[8:11], v[170:173], v[194:197], v[8:11]
	v_mfma_f32_16x16x32_bf16 v[4:7], v[158:161], v[202:205], v[4:7]
	v_mfma_f32_16x16x32_bf16 v[0:3], v[170:173], v[202:205], v[0:3]
	v_mfma_f32_16x16x32_bf16 v[44:47], v[166:169], v[182:185], v[44:47]
	v_mfma_f32_16x16x32_bf16 v[36:39], v[174:177], v[182:185], v[36:39]
	v_mfma_f32_16x16x32_bf16 v[28:31], v[166:169], v[190:193], v[28:31]
	v_mfma_f32_16x16x32_bf16 v[20:23], v[174:177], v[190:193], v[20:23]
	v_mfma_f32_16x16x32_bf16 v[12:15], v[166:169], v[198:201], v[12:15]
	v_mfma_f32_16x16x32_bf16 v[8:11], v[174:177], v[198:201], v[8:11]
	v_mfma_f32_16x16x32_bf16 v[4:7], v[166:169], v[206:209], v[4:7]
	v_mfma_f32_16x16x32_bf16 v[0:3], v[174:177], v[206:209], v[0:3]
	s_barrier
	s_add_i32 s65, s65, 2
	s_add_u32 s59, s59, 0x100
	s_addc_u32 s63, s63, 0
	s_add_u32 s72, s72, 0x8000
	s_addc_u32 s73, s73, 0
	s_cmp_gt_u32 s65, 29
	s_cbranch_scc0 .LBB0_1117
	s_and_b64 vcc, exec, s[26:27]
	s_cbranch_vccz .LBB0_1120
	s_barrier

; #define PG8_STAGE(bufoff, gbase, voff) do { _Pragma("unroll") for (int _i = 0; _i < 2; ++_i) \
;         __builtin_amdgcn_global_load_lds((const unsigned*)((const char*)(gbase) + (voff)[_i]), (PG8_LAS unsigned*)(lds + (bufoff) + ldsw + _i * 8192), 16, 0, 0); } while (0)
; #define PG8_LDA(dst, b, h) do { _Pragma("unroll") for (int m = 0; m < 4; ++m) _Pragma("unroll") for (int k = 0; k < 2; ++k) dst[m][k] = *(const PG8_LAS bf16x8*)(lds + PG8_SA(b, h) + aoff + m * 2048 + k * 1024); } while (0)
; #define PG8_LDB(dst, b, h) do { _Pragma("unroll") for (int n = 0; n < 2; ++n) _Pragma("unroll") for (int k = 0; k < 2; ++k) dst[n][k] = *(const PG8_LAS bf16x8*)(lds + PG8_SB(b, h) + boff + n * 2048 + k * 1024); } while (0)
; #define PG8_MMA(ai, bj, At, Bt) do { __builtin_amdgcn_s_setprio(1); _Pragma("unroll") for (int m = 0; m < 4; ++m) _Pragma("unroll") for (int n = 0; n < 2; ++n) _Pragma("unroll") for (int k = 0; k < 2; ++k) \
;         acc[ai][bj][m][n] = __builtin_amdgcn_mfma_f32_16x16x32_bf16(Bt[n][k], At[m][k], acc[ai][bj][m][n], 0, 0, 0); __builtin_amdgcn_s_setprio(0); } while (0)
; #define PG8_WAIT_V(n) asm volatile("s_waitcnt vmcnt(" #n ")" ::: "memory")
; template <class Epi, class Sched, bool ALIGN_EPI = false, bool SP2 = false>
; __device__ __forceinline__ void gemm_phase(PG8_LAS unsigned char* lds, const Gemm g, const Sched& S, const Epi& E) {
;     ...
;         const char* nA = has_next ? (const char*)g.A + (size_t)nxt.pm * tstepA + (size_t)nxt.kofs * kmulA : cA; const char* nB = has_next ? (const char*)g.Bt + (size_t)nxt.pn * tstepB + (size_t)nxt.kofs * 2 : cB;
;         for (int t = 0; t < nt; t += 2) {
;             const bool last = (t == nt - 2);
;             const char* a1 = cA + (size_t)(t + 1) * kstepA;
;             const char* a2 = last ? nA : cA + (size_t)(t + 2) * kstepA; const char* b2 = last ? nB : cB + (size_t)(t + 2) * kstep;
;     ...
;             PG8_LDB(B0, 0, 0); PG8_LDB(B1, 0, 1); PG8_SCHED; PG8_LDA(At, 0, 0); PG8_STAGE(PG8_SA(1, 1), a1 + hstepA, voffA);
;             PG8_WAIT_V(8); PG8_WAIT_L(0); PG8_BAR; PG8_MMA(0, 0, At, B0); PG8_MMA(0, 1, At, B1); PG8_BAR; PG8_SCHED;
;             PG8_LDA(At, 0, 1); PG8_STAGE(PG8_SB(0, 0), b2, voffB); PG8_STAGE(PG8_SB(0, 1), b2 + hstepB, voffB); PG8_STAGE(PG8_SA(0, 0), a2, voffA);
;             PG8_WAIT_V(8); PG8_WAIT_L(0); PG8_BAR; PG8_MMA(1, 0, At, B0); PG8_MMA(1, 1, At, B1); PG8_BAR; PG8_SCHED;
.LBB0_1272:
	ds_read_b128 v[158:161], v154
	ds_read_b128 v[166:169], v154 offset:1024
	ds_read_b128 v[170:173], v154 offset:2048
	ds_read_b128 v[174:177], v154 offset:3072
	ds_read_b128 v[178:181], v155
	ds_read_b128 v[182:185], v155 offset:1024
	ds_read_b128 v[186:189], v155 offset:2048
	ds_read_b128 v[190:193], v155 offset:3072
	s_add_u32 s6, s44, 0xfff80080
	s_addc_u32 s7, s45, -1
	s_cmp_eq_u32 s77, 28
	s_cselect_b32 s55, s3, s7
	s_cselect_b32 s54, s5, s6
	s_cselect_b32 s53, s25, s76
	s_cselect_b32 s52, s27, s75
	v_lshl_add_u64 v[150:151], s[44:45], 0, v[144:145]
	s_add_i32 m0, s59, 0xc000
	ds_read_b128 v[194:197], v156
	ds_read_b128 v[198:201], v156 offset:1024
	ds_read_b128 v[202:205], v156 offset:2048
	ds_read_b128 v[206:209], v156 offset:3072
	ds_read_b128 v[210:213], v156 offset:4096
	ds_read_b128 v[214:217], v156 offset:5120
	ds_read_b128 v[218:221], v156 offset:6144
	ds_read_b128 v[222:225], v156 offset:7168
	global_load_lds_dwordx4 v[150:151], off
	v_lshl_add_u64 v[150:151], s[44:45], 0, v[146:147]
	s_add_i32 m0, s59, 0xe000
	s_nop 0
	global_load_lds_dwordx4 v[150:151], off
	s_waitcnt vmcnt(8)
	s_waitcnt lgkmcnt(0)
	s_barrier
	s_waitcnt lgkmcnt(0)
	v_mfma_f32_16x16x32_bf16 v[124:127], v[158:161], v[194:197], v[124:127]
	v_mfma_f32_16x16x32_bf16 v[120:123], v[170:173], v[194:197], v[120:123]
	v_mfma_f32_16x16x32_bf16 v[116:119], v[158:161], v[202:205], v[116:119]
	v_mfma_f32_16x16x32_bf16 v[112:115], v[170:173], v[202:205], v[112:115]
	v_mfma_f32_16x16x32_bf16 v[108:111], v[158:161], v[210:213], v[108:111]
	v_mfma_f32_16x16x32_bf16 v[104:107], v[170:173], v[210:213], v[104:107]
	v_mfma_f32_16x16x32_bf16 v[100:103], v[158:161], v[218:221], v[100:103]
	v_mfma_f32_16x16x32_bf16 v[96:99], v[170:173], v[218:221], v[96:99]
	v_mfma_f32_16x16x32_bf16 v[124:127], v[166:169], v[198:201], v[124:127]
	v_mfma_f32_16x16x32_bf16 v[120:123], v[174:177], v[198:201], v[120:123]
	v_mfma_f32_16x16x32_bf16 v[116:119], v[166:169], v[206:209], v[116:119]
	v_mfma_f32_16x16x32_bf16 v[112:115], v[174:177], v[206:209], v[112:115]
	v_mfma_f32_16x16x32_bf16 v[108:111], v[166:169], v[214:217], v[108:111]
	v_mfma_f32_16x16x32_bf16 v[104:107], v[174:177], v[214:217], v[104:107]
	v_mfma_f32_16x16x32_bf16 v[100:103], v[166:169], v[222:225], v[100:103]
	v_mfma_f32_16x16x32_bf16 v[96:99], v[174:177], v[222:225], v[96:99]
	v_mfma_f32_16x16x32_bf16 v[60:63], v[178:181], v[194:197], v[60:63]
	v_mfma_f32_16x16x32_bf16 v[56:59], v[186:189], v[194:197], v[56:59]
	v_mfma_f32_16x16x32_bf16 v[52:55], v[178:181], v[202:205], v[52:55]
	v_mfma_f32_16x16x32_bf16 v[48:51], v[186:189], v[202:205], v[48:51]
	v_mfma_f32_16x16x32_bf16 v[44:47], v[178:181], v[210:213], v[44:47]
	v_mfma_f32_16x16x32_bf16 v[40:43], v[186:189], v[210:213], v[40:43]
	v_mfma_f32_16x16x32_bf16 v[36:39], v[178:181], v[218:221], v[36:39]
	v_mfma_f32_16x16x32_bf16 v[32:35], v[186:189], v[218:221], v[32:35]
	v_mfma_f32_16x16x32_bf16 v[60:63], v[182:185], v[198:201], v[60:63]
	v_mfma_f32_16x16x32_bf16 v[56:59], v[190:193], v[198:201], v[56:59]
	v_mfma_f32_16x16x32_bf16 v[52:55], v[182:185], v[206:209], v[52:55]
	v_mfma_f32_16x16x32_bf16 v[48:51], v[190:193], v[206:209], v[48:51]
	v_mfma_f32_16x16x32_bf16 v[44:47], v[182:185], v[214:217], v[44:47]
	v_mfma_f32_16x16x32_bf16 v[40:43], v[190:193], v[214:217], v[40:43]
	v_mfma_f32_16x16x32_bf16 v[36:39], v[182:185], v[222:225], v[36:39]
	v_mfma_f32_16x16x32_bf16 v[32:35], v[190:193], v[222:225], v[32:35]
	s_barrier
	s_add_i32 s6, s72, s58
	v_lshl_add_u64 v[150:151], s[52:53], 0, v[132:133]
	s_mov_b32 m0, s6
	ds_read_b128 v[194:197], v156 offset:16384
	ds_read_b128 v[198:201], v156 offset:17408
	ds_read_b128 v[202:205], v156 offset:18432
	ds_read_b128 v[206:209], v156 offset:19456
	ds_read_b128 v[210:213], v156 offset:20480
	ds_read_b128 v[214:217], v156 offset:21504
	ds_read_b128 v[218:221], v156 offset:22528
	ds_read_b128 v[222:225], v156 offset:23552
	global_load_lds_dwordx4 v[150:151], off
	s_add_i32 m0, s6, 0x2000
	s_add_u32 s6, s52, 0x80000
	v_lshl_add_u64 v[162:163], s[52:53], 0, v[136:137]
	s_addc_u32 s7, s53, 0
	s_add_i32 s9, s73, s58
	global_load_lds_dwordx4 v[162:163], off
	v_lshl_add_u64 v[226:227], s[6:7], 0, v[132:133]
	s_mov_b32 m0, s9
	v_lshl_add_u64 v[228:229], s[54:55], 0, v[134:135]
	global_load_lds_dwordx4 v[226:227], off
	v_lshl_add_u64 v[226:227], s[6:7], 0, v[136:137]
	s_add_i32 m0, s9, 0x2000
	s_nop 0
	global_load_lds_dwordx4 v[226:227], off
	v_lshl_add_u64 v[226:227], s[54:55], 0, v[130:131]
	s_mov_b32 m0, s59
	s_nop 0
	global_load_lds_dwordx4 v[226:227], off
	s_mov_b32 m0, s60
	s_nop 0
	global_load_lds_dwordx4 v[228:229], off
	s_waitcnt vmcnt(8)
	s_waitcnt lgkmcnt(0)
	s_barrier
; #define PG8_STAGE(bufoff, gbase, voff) do { _Pragma("unroll") for (int _i = 0; _i < 2; ++_i) \
;         __builtin_amdgcn_global_load_lds((const unsigned*)((const char*)(gbase) + (voff)[_i]), (PG8_LAS unsigned*)(lds + (bufoff) + ldsw + _i * 8192), 16, 0, 0); } while (0)
; #define PG8_LDA(dst, b, h) do { _Pragma("unroll") for (int m = 0; m < 4; ++m) _Pragma("unroll") for (int k = 0; k < 2; ++k) dst[m][k] = *(const PG8_LAS bf16x8*)(lds + PG8_SA(b, h) + aoff + m * 2048 + k * 1024); } while (0)
; #define PG8_LDB(dst, b, h) do { _Pragma("unroll") for (int n = 0; n < 2; ++n) _Pragma("unroll") for (int k = 0; k < 2; ++k) dst[n][k] = *(const PG8_LAS bf16x8*)(lds + PG8_SB(b, h) + boff + n * 2048 + k * 1024); } while (0)
; #define PG8_MMA(ai, bj, At, Bt) do { __builtin_amdgcn_s_setprio(1); _Pragma("unroll") for (int m = 0; m < 4; ++m) _Pragma("unroll") for (int n = 0; n < 2; ++n) _Pragma("unroll") for (int k = 0; k < 2; ++k) \
;         acc[ai][bj][m][n] = __builtin_amdgcn_mfma_f32_16x16x32_bf16(Bt[n][k], At[m][k], acc[ai][bj][m][n], 0, 0, 0); __builtin_amdgcn_s_setprio(0); } while (0)
; #define PG8_WAIT_V(n) asm volatile("s_waitcnt vmcnt(" #n ")" ::: "memory")
; #define PG8_WAIT_L(n) asm volatile("s_waitcnt lgkmcnt(" #n ")" ::: "memory")
; #define PG8_BAR __builtin_amdgcn_s_barrier()
; #define PG8_SCHED __builtin_amdgcn_sched_barrier(0)
; template <class Epi, class Sched, bool ALIGN_EPI = false, bool SP2 = false>
; __device__ __forceinline__ void gemm_phase(PG8_LAS unsigned char* lds, const Gemm g, const Sched& S, const Epi& E) {
;     ...
;             PG8_WAIT_V(8); PG8_WAIT_L(0); PG8_BAR; PG8_MMA(1, 0, At, B0); PG8_MMA(1, 1, At, B1); PG8_BAR; PG8_SCHED;
;             PG8_LDB(B0, 1, 0); PG8_LDB(B1, 1, 1); PG8_SCHED; PG8_LDA(At, 1, 0); PG8_STAGE(PG8_SA(0, 1), a2 + hstepA, voffA);
;             PG8_WAIT_V(8); PG8_WAIT_L(0); PG8_BAR; PG8_MMA(0, 0, At, B0); PG8_MMA(0, 1, At, B1); PG8_BAR; PG8_SCHED;
	s_waitcnt lgkmcnt(0)
	v_mfma_f32_16x16x32_bf16 v[92:95], v[158:161], v[194:197], v[92:95]
	v_mfma_f32_16x16x32_bf16 v[88:91], v[170:173], v[194:197], v[88:91]
	v_mfma_f32_16x16x32_bf16 v[84:87], v[158:161], v[202:205], v[84:87]
	v_mfma_f32_16x16x32_bf16 v[80:83], v[170:173], v[202:205], v[80:83]
	v_mfma_f32_16x16x32_bf16 v[76:79], v[158:161], v[210:213], v[76:79]
	v_mfma_f32_16x16x32_bf16 v[72:75], v[170:173], v[210:213], v[72:75]
	v_mfma_f32_16x16x32_bf16 v[68:71], v[158:161], v[218:221], v[68:71]
	v_mfma_f32_16x16x32_bf16 v[64:67], v[170:173], v[218:221], v[64:67]
	v_mfma_f32_16x16x32_bf16 v[92:95], v[166:169], v[198:201], v[92:95]
	v_mfma_f32_16x16x32_bf16 v[88:91], v[174:177], v[198:201], v[88:91]
	v_mfma_f32_16x16x32_bf16 v[84:87], v[166:169], v[206:209], v[84:87]
	v_mfma_f32_16x16x32_bf16 v[80:83], v[174:177], v[206:209], v[80:83]
	v_mfma_f32_16x16x32_bf16 v[76:79], v[166:169], v[214:217], v[76:79]
	v_mfma_f32_16x16x32_bf16 v[72:75], v[174:177], v[214:217], v[72:75]
	v_mfma_f32_16x16x32_bf16 v[68:71], v[166:169], v[222:225], v[68:71]
	v_mfma_f32_16x16x32_bf16 v[64:67], v[174:177], v[222:225], v[64:67]
	v_mfma_f32_16x16x32_bf16 v[28:31], v[178:181], v[194:197], v[28:31]
	v_mfma_f32_16x16x32_bf16 v[24:27], v[186:189], v[194:197], v[24:27]
	v_mfma_f32_16x16x32_bf16 v[20:23], v[178:181], v[202:205], v[20:23]
	v_mfma_f32_16x16x32_bf16 v[16:19], v[186:189], v[202:205], v[16:19]
	v_mfma_f32_16x16x32_bf16 v[12:15], v[178:181], v[210:213], v[12:15]
	v_mfma_f32_16x16x32_bf16 v[8:11], v[186:189], v[210:213], v[8:11]
	v_mfma_f32_16x16x32_bf16 v[4:7], v[178:181], v[218:221], v[4:7]
	v_mfma_f32_16x16x32_bf16 v[0:3], v[186:189], v[218:221], v[0:3]
	v_mfma_f32_16x16x32_bf16 v[28:31], v[182:185], v[198:201], v[28:31]
	v_mfma_f32_16x16x32_bf16 v[24:27], v[190:193], v[198:201], v[24:27]
	v_mfma_f32_16x16x32_bf16 v[20:23], v[182:185], v[206:209], v[20:23]
	v_mfma_f32_16x16x32_bf16 v[16:19], v[190:193], v[206:209], v[16:19]
	v_mfma_f32_16x16x32_bf16 v[12:15], v[182:185], v[214:217], v[12:15]
	v_mfma_f32_16x16x32_bf16 v[8:11], v[190:193], v[214:217], v[8:11]
	v_mfma_f32_16x16x32_bf16 v[4:7], v[182:185], v[222:225], v[4:7]
	v_mfma_f32_16x16x32_bf16 v[0:3], v[190:193], v[222:225], v[0:3]
	s_barrier
	s_add_i32 s9, 0, 0x18000
	v_add_u32_e32 v138, s9, v153
	s_add_i32 s34, 0, 0x1c000
	ds_read_b128 v[158:161], v138
	ds_read_b128 v[166:169], v138 offset:1024
	ds_read_b128 v[170:173], v138 offset:2048
	ds_read_b128 v[174:177], v138 offset:3072
	v_add_u32_e32 v138, s34, v153
	ds_read_b128 v[178:181], v138
	ds_read_b128 v[182:185], v138 offset:1024
	ds_read_b128 v[186:189], v138 offset:2048
	ds_read_b128 v[190:193], v138 offset:3072
	s_add_u32 s6, s54, 0x80000
	s_addc_u32 s7, s55, 0
	s_mov_b32 m0, s61
	v_lshl_add_u64 v[230:231], s[6:7], 0, v[130:131]
	ds_read_b128 v[194:197], v156 offset:32768
	ds_read_b128 v[198:201], v156 offset:33792
	ds_read_b128 v[202:205], v156 offset:34816
	ds_read_b128 v[206:209], v156 offset:35840
	ds_read_b128 v[210:213], v156 offset:36864
	ds_read_b128 v[214:217], v156 offset:37888
	ds_read_b128 v[218:221], v156 offset:38912
	ds_read_b128 v[222:225], v156 offset:39936
	global_load_lds_dwordx4 v[230:231], off
	v_lshl_add_u64 v[230:231], s[6:7], 0, v[134:135]
	s_mov_b32 m0, s62
	s_nop 0
	global_load_lds_dwordx4 v[230:231], off
	s_waitcnt vmcnt(8)
	s_waitcnt lgkmcnt(0)
	s_barrier
	s_waitcnt lgkmcnt(0)
	v_mfma_f32_16x16x32_bf16 v[124:127], v[158:161], v[194:197], v[124:127]
	v_mfma_f32_16x16x32_bf16 v[120:123], v[170:173], v[194:197], v[120:123]
	v_mfma_f32_16x16x32_bf16 v[116:119], v[158:161], v[202:205], v[116:119]
	v_mfma_f32_16x16x32_bf16 v[112:115], v[170:173], v[202:205], v[112:115]
	v_mfma_f32_16x16x32_bf16 v[108:111], v[158:161], v[210:213], v[108:111]
	v_mfma_f32_16x16x32_bf16 v[104:107], v[170:173], v[210:213], v[104:107]
	v_mfma_f32_16x16x32_bf16 v[100:103], v[158:161], v[218:221], v[100:103]
	v_mfma_f32_16x16x32_bf16 v[96:99], v[170:173], v[218:221], v[96:99]
	v_mfma_f32_16x16x32_bf16 v[124:127], v[166:169], v[198:201], v[124:127]
	v_mfma_f32_16x16x32_bf16 v[120:123], v[174:177], v[198:201], v[120:123]
	v_mfma_f32_16x16x32_bf16 v[116:119], v[166:169], v[206:209], v[116:119]
	v_mfma_f32_16x16x32_bf16 v[112:115], v[174:177], v[206:209], v[112:115]
	v_mfma_f32_16x16x32_bf16 v[108:111], v[166:169], v[214:217], v[108:111]
	v_mfma_f32_16x16x32_bf16 v[104:107], v[174:177], v[214:217], v[104:107]
	v_mfma_f32_16x16x32_bf16 v[100:103], v[166:169], v[222:225], v[100:103]
	v_mfma_f32_16x16x32_bf16 v[96:99], v[174:177], v[222:225], v[96:99]
	v_mfma_f32_16x16x32_bf16 v[60:63], v[178:181], v[194:197], v[60:63]
	v_mfma_f32_16x16x32_bf16 v[56:59], v[186:189], v[194:197], v[56:59]
	v_mfma_f32_16x16x32_bf16 v[52:55], v[178:181], v[202:205], v[52:55]
	v_mfma_f32_16x16x32_bf16 v[48:51], v[186:189], v[202:205], v[48:51]
	v_mfma_f32_16x16x32_bf16 v[44:47], v[178:181], v[210:213], v[44:47]
	v_mfma_f32_16x16x32_bf16 v[40:43], v[186:189], v[210:213], v[40:43]
	v_mfma_f32_16x16x32_bf16 v[36:39], v[178:181], v[218:221], v[36:39]
	v_mfma_f32_16x16x32_bf16 v[32:35], v[186:189], v[218:221], v[32:35]
	v_mfma_f32_16x16x32_bf16 v[60:63], v[182:185], v[198:201], v[60:63]
	v_mfma_f32_16x16x32_bf16 v[56:59], v[190:193], v[198:201], v[56:59]
	v_mfma_f32_16x16x32_bf16 v[52:55], v[182:185], v[206:209], v[52:55]
	v_mfma_f32_16x16x32_bf16 v[48:51], v[190:193], v[206:209], v[48:51]
	v_mfma_f32_16x16x32_bf16 v[44:47], v[182:185], v[214:217], v[44:47]
	v_mfma_f32_16x16x32_bf16 v[40:43], v[190:193], v[214:217], v[40:43]
	v_mfma_f32_16x16x32_bf16 v[36:39], v[182:185], v[222:225], v[36:39]
	v_mfma_f32_16x16x32_bf16 v[32:35], v[190:193], v[222:225], v[32:35]
	s_barrier
; #define PG8_STAGE(bufoff, gbase, voff) do { _Pragma("unroll") for (int _i = 0; _i < 2; ++_i) \
;         __builtin_amdgcn_global_load_lds((const unsigned*)((const char*)(gbase) + (voff)[_i]), (PG8_LAS unsigned*)(lds + (bufoff) + ldsw + _i * 8192), 16, 0, 0); } while (0)
; #define PG8_LDA(dst, b, h) do { _Pragma("unroll") for (int m = 0; m < 4; ++m) _Pragma("unroll") for (int k = 0; k < 2; ++k) dst[m][k] = *(const PG8_LAS bf16x8*)(lds + PG8_SA(b, h) + aoff + m * 2048 + k * 1024); } while (0)
; #define PG8_MMA(ai, bj, At, Bt) do { __builtin_amdgcn_s_setprio(1); _Pragma("unroll") for (int m = 0; m < 4; ++m) _Pragma("unroll") for (int n = 0; n < 2; ++n) _Pragma("unroll") for (int k = 0; k < 2; ++k) \
;         acc[ai][bj][m][n] = __builtin_amdgcn_mfma_f32_16x16x32_bf16(Bt[n][k], At[m][k], acc[ai][bj][m][n], 0, 0, 0); __builtin_amdgcn_s_setprio(0); } while (0)
; #define PG8_WAIT_V(n) asm volatile("s_waitcnt vmcnt(" #n ")" ::: "memory")
; #define PG8_WAIT_L(n) asm volatile("s_waitcnt lgkmcnt(" #n ")" ::: "memory")
; #define PG8_BAR __builtin_amdgcn_s_barrier()
; #define PG8_SCHED __builtin_amdgcn_sched_barrier(0)
; template <class Epi, class Sched, bool ALIGN_EPI = false, bool SP2 = false>
; __device__ __forceinline__ void gemm_phase(PG8_LAS unsigned char* lds, const Gemm g, const Sched& S, const Epi& E) {
;     ...
;         for (int t = 0; t < nt; t += 2) {
;             const bool last = (t == nt - 2);
;     ...
;             PG8_LDA(At, 1, 1); PG8_STAGE(PG8_SB(1, 0), b3, voffB); PG8_STAGE(PG8_SB(1, 1), b3 + hstepB, voffB); PG8_STAGE(PG8_SA(1, 0), a3, voffA);
;             PG8_WAIT_V(8); PG8_WAIT_L(0); PG8_BAR; PG8_MMA(1, 0, At, B0); PG8_MMA(1, 1, At, B1); PG8_BAR; PG8_SCHED;
	s_add_i32 s6, s9, s58
	v_lshl_add_u64 v[150:151], v[150:151], 0, s[14:15]
	s_mov_b32 m0, s6
	ds_read_b128 v[194:197], v156 offset:49152
	ds_read_b128 v[198:201], v156 offset:50176
	ds_read_b128 v[202:205], v156 offset:51200
	ds_read_b128 v[206:209], v156 offset:52224
	ds_read_b128 v[210:213], v156 offset:53248
	ds_read_b128 v[214:217], v156 offset:54272
	ds_read_b128 v[218:221], v156 offset:55296
	ds_read_b128 v[222:225], v156 offset:56320
	global_load_lds_dwordx4 v[150:151], off
	s_add_i32 m0, s6, 0x2000
	s_add_u32 s6, s52, 0x80080
	v_lshl_add_u64 v[150:151], v[162:163], 0, s[14:15]
	s_addc_u32 s7, s53, 0
	s_add_i32 s9, s34, s58
	global_load_lds_dwordx4 v[150:151], off
	v_lshl_add_u64 v[150:151], s[6:7], 0, v[132:133]
	s_mov_b32 m0, s9
	s_nop 0
	global_load_lds_dwordx4 v[150:151], off
	v_lshl_add_u64 v[150:151], s[6:7], 0, v[136:137]
	s_add_i32 m0, s9, 0x2000
	s_nop 0
	global_load_lds_dwordx4 v[150:151], off
	v_lshl_add_u64 v[150:151], v[226:227], 0, s[14:15]
	s_mov_b32 m0, s69
	s_nop 0
	global_load_lds_dwordx4 v[150:151], off
	v_lshl_add_u64 v[150:151], v[228:229], 0, s[14:15]
	s_mov_b32 m0, s70
	s_nop 0
	global_load_lds_dwordx4 v[150:151], off
	s_waitcnt vmcnt(8)
	s_waitcnt lgkmcnt(0)
	s_barrier
	s_waitcnt lgkmcnt(0)
	v_mfma_f32_16x16x32_bf16 v[92:95], v[158:161], v[194:197], v[92:95]
	v_mfma_f32_16x16x32_bf16 v[88:91], v[170:173], v[194:197], v[88:91]
	v_mfma_f32_16x16x32_bf16 v[84:87], v[158:161], v[202:205], v[84:87]
	v_mfma_f32_16x16x32_bf16 v[80:83], v[170:173], v[202:205], v[80:83]
	v_mfma_f32_16x16x32_bf16 v[76:79], v[158:161], v[210:213], v[76:79]
	v_mfma_f32_16x16x32_bf16 v[72:75], v[170:173], v[210:213], v[72:75]
	v_mfma_f32_16x16x32_bf16 v[68:71], v[158:161], v[218:221], v[68:71]
	v_mfma_f32_16x16x32_bf16 v[64:67], v[170:173], v[218:221], v[64:67]
	v_mfma_f32_16x16x32_bf16 v[92:95], v[166:169], v[198:201], v[92:95]
	v_mfma_f32_16x16x32_bf16 v[88:91], v[174:177], v[198:201], v[88:91]
	v_mfma_f32_16x16x32_bf16 v[84:87], v[166:169], v[206:209], v[84:87]
	v_mfma_f32_16x16x32_bf16 v[80:83], v[174:177], v[206:209], v[80:83]
	v_mfma_f32_16x16x32_bf16 v[76:79], v[166:169], v[214:217], v[76:79]
	v_mfma_f32_16x16x32_bf16 v[72:75], v[174:177], v[214:217], v[72:75]
	v_mfma_f32_16x16x32_bf16 v[68:71], v[166:169], v[222:225], v[68:71]
	v_mfma_f32_16x16x32_bf16 v[64:67], v[174:177], v[222:225], v[64:67]
	v_mfma_f32_16x16x32_bf16 v[28:31], v[178:181], v[194:197], v[28:31]
	v_mfma_f32_16x16x32_bf16 v[24:27], v[186:189], v[194:197], v[24:27]
	v_mfma_f32_16x16x32_bf16 v[20:23], v[178:181], v[202:205], v[20:23]
	v_mfma_f32_16x16x32_bf16 v[16:19], v[186:189], v[202:205], v[16:19]
	v_mfma_f32_16x16x32_bf16 v[12:15], v[178:181], v[210:213], v[12:15]
	v_mfma_f32_16x16x32_bf16 v[8:11], v[186:189], v[210:213], v[8:11]
	v_mfma_f32_16x16x32_bf16 v[4:7], v[178:181], v[218:221], v[4:7]
	v_mfma_f32_16x16x32_bf16 v[0:3], v[186:189], v[218:221], v[0:3]
	v_mfma_f32_16x16x32_bf16 v[28:31], v[182:185], v[198:201], v[28:31]
	v_mfma_f32_16x16x32_bf16 v[24:27], v[190:193], v[198:201], v[24:27]
	v_mfma_f32_16x16x32_bf16 v[20:23], v[182:185], v[206:209], v[20:23]
	v_mfma_f32_16x16x32_bf16 v[16:19], v[190:193], v[206:209], v[16:19]
	v_mfma_f32_16x16x32_bf16 v[12:15], v[182:185], v[214:217], v[12:15]
	v_mfma_f32_16x16x32_bf16 v[8:11], v[190:193], v[214:217], v[8:11]
	v_mfma_f32_16x16x32_bf16 v[4:7], v[182:185], v[222:225], v[4:7]
	v_mfma_f32_16x16x32_bf16 v[0:3], v[190:193], v[222:225], v[0:3]
	s_barrier
	s_add_i32 s77, s77, 2
	s_add_u32 s44, s44, 0x100
	s_addc_u32 s45, s45, 0
	s_add_u32 s75, s75, 0x100
	s_addc_u32 s76, s76, 0
	s_cmp_gt_u32 s77, 29
	s_cbranch_scc0 .LBB0_1272
	s_and_b64 vcc, exec, s[16:17]
	s_cbranch_vccz .LBB0_1275
	s_barrier

; #define PG8_STAGE(bufoff, gbase, voff) do { _Pragma("unroll") for (int _i = 0; _i < 2; ++_i) \
;         __builtin_amdgcn_global_load_lds((const unsigned*)((const char*)(gbase) + (voff)[_i]), (PG8_LAS unsigned*)(lds + (bufoff) + ldsw + _i * 8192), 16, 0, 0); } while (0)
; #define PG8_LDA(dst, b, h) do { _Pragma("unroll") for (int m = 0; m < 4; ++m) _Pragma("unroll") for (int k = 0; k < 2; ++k) dst[m][k] = *(const PG8_LAS bf16x8*)(lds + PG8_SA(b, h) + aoff + m * 2048 + k * 1024); } while (0)
; #define PG8_LDB(dst, b, h) do { _Pragma("unroll") for (int n = 0; n < 2; ++n) _Pragma("unroll") for (int k = 0; k < 2; ++k) dst[n][k] = *(const PG8_LAS bf16x8*)(lds + PG8_SB(b, h) + boff + n * 2048 + k * 1024); } while (0)
; #define PG8_MMA(ai, bj, At, Bt) do { __builtin_amdgcn_s_setprio(1); _Pragma("unroll") for (int m = 0; m < 4; ++m) _Pragma("unroll") for (int n = 0; n < 2; ++n) _Pragma("unroll") for (int k = 0; k < 2; ++k) \
;         acc[ai][bj][m][n] = __builtin_amdgcn_mfma_f32_16x16x32_bf16(Bt[n][k], At[m][k], acc[ai][bj][m][n], 0, 0, 0); __builtin_amdgcn_s_setprio(0); } while (0)
; #define PG8_WAIT_V(n) asm volatile("s_waitcnt vmcnt(" #n ")" ::: "memory")
; template <class Epi, class Sched, bool ALIGN_EPI = false, bool SP2 = false>
; __device__ __forceinline__ void gemm_phase(PG8_LAS unsigned char* lds, const Gemm g, const Sched& S, const Epi& E) {
;     ...
;         const char* nA = has_next ? (const char*)g.A + (size_t)nxt.pm * tstepA + (size_t)nxt.kofs * kmulA : cA; const char* nB = has_next ? (const char*)g.Bt + (size_t)nxt.pn * tstepB + (size_t)nxt.kofs * 2 : cB;
;         for (int t = 0; t < nt; t += 2) {
;             const bool last = (t == nt - 2);
;             const char* a1 = cA + (size_t)(t + 1) * kstepA;
;             const char* a2 = last ? nA : cA + (size_t)(t + 2) * kstepA; const char* b2 = last ? nB : cB + (size_t)(t + 2) * kstep;
;     ...
;             PG8_LDB(B0, 0, 0); PG8_LDB(B1, 0, 1); PG8_SCHED; PG8_LDA(At, 0, 0); PG8_STAGE(PG8_SA(1, 1), a1 + hstepA, voffA);
;             PG8_WAIT_V(8); PG8_WAIT_L(0); PG8_BAR; PG8_MMA(0, 0, At, B0); PG8_MMA(0, 1, At, B1); PG8_BAR; PG8_SCHED;
;             PG8_LDA(At, 0, 1); PG8_STAGE(PG8_SB(0, 0), b2, voffB); PG8_STAGE(PG8_SB(0, 1), b2 + hstepB, voffB); PG8_STAGE(PG8_SA(0, 0), a2, voffA);
;             PG8_WAIT_V(8); PG8_WAIT_L(0); PG8_BAR; PG8_MMA(1, 0, At, B0); PG8_MMA(1, 1, At, B1); PG8_BAR; PG8_SCHED;
.LBB0_1485:
	ds_read_b128 v[88:91], v179
	ds_read_b128 v[96:99], v179 offset:1024
	ds_read_b128 v[108:111], v179 offset:2048
	ds_read_b128 v[112:115], v179 offset:3072
	ds_read_b128 v[158:161], v180
	ds_read_b128 v[166:169], v180 offset:1024
	ds_read_b128 v[170:173], v180 offset:2048
	ds_read_b128 v[182:185], v180 offset:3072
	s_add_u32 s6, s40, 0xfff80080
	s_addc_u32 s7, s41, -1
	s_cmp_eq_u32 s80, 28
	s_cselect_b32 s45, s27, s7
	s_cselect_b32 s44, s74, s6
	s_cselect_b32 s43, s25, s77
	s_cselect_b32 s42, s75, s76
	v_lshl_add_u64 v[162:163], s[40:41], 0, v[150:151]
	s_add_i32 m0, s56, 0xc000
	ds_read_b128 v[186:189], v181
	ds_read_b128 v[190:193], v181 offset:1024
	ds_read_b128 v[194:197], v181 offset:2048
	ds_read_b128 v[198:201], v181 offset:3072
	ds_read_b128 v[202:205], v181 offset:4096
	ds_read_b128 v[206:209], v181 offset:5120
	ds_read_b128 v[210:213], v181 offset:6144
	ds_read_b128 v[214:217], v181 offset:7168
	global_load_lds_dwordx4 v[162:163], off
	v_lshl_add_u64 v[162:163], s[40:41], 0, v[152:153]
	s_add_i32 m0, s56, 0xe000
	s_nop 0
	global_load_lds_dwordx4 v[162:163], off
	s_waitcnt vmcnt(8)
	s_waitcnt lgkmcnt(0)
	s_barrier
	s_waitcnt lgkmcnt(0)
	v_mfma_f32_16x16x32_bf16 v[140:143], v[88:91], v[186:189], v[140:143]
	v_mfma_f32_16x16x32_bf16 v[136:139], v[108:111], v[186:189], v[136:139]
	v_mfma_f32_16x16x32_bf16 v[124:127], v[88:91], v[194:197], v[124:127]
	v_mfma_f32_16x16x32_bf16 v[120:123], v[108:111], v[194:197], v[120:123]
	v_mfma_f32_16x16x32_bf16 v[100:103], v[88:91], v[202:205], v[100:103]
	v_mfma_f32_16x16x32_bf16 v[92:95], v[108:111], v[202:205], v[92:95]
	v_mfma_f32_16x16x32_bf16 v[76:79], v[88:91], v[210:213], v[76:79]
	v_mfma_f32_16x16x32_bf16 v[72:75], v[108:111], v[210:213], v[72:75]
	v_mfma_f32_16x16x32_bf16 v[140:143], v[96:99], v[190:193], v[140:143]
	v_mfma_f32_16x16x32_bf16 v[136:139], v[112:115], v[190:193], v[136:139]
	v_mfma_f32_16x16x32_bf16 v[124:127], v[96:99], v[198:201], v[124:127]
	v_mfma_f32_16x16x32_bf16 v[120:123], v[112:115], v[198:201], v[120:123]
	v_mfma_f32_16x16x32_bf16 v[100:103], v[96:99], v[206:209], v[100:103]
	v_mfma_f32_16x16x32_bf16 v[92:95], v[112:115], v[206:209], v[92:95]
	v_mfma_f32_16x16x32_bf16 v[76:79], v[96:99], v[214:217], v[76:79]
	v_mfma_f32_16x16x32_bf16 v[72:75], v[112:115], v[214:217], v[72:75]
	v_mfma_f32_16x16x32_bf16 v[132:135], v[158:161], v[186:189], v[132:135]
	v_mfma_f32_16x16x32_bf16 v[128:131], v[170:173], v[186:189], v[128:131]
	v_mfma_f32_16x16x32_bf16 v[116:119], v[158:161], v[194:197], v[116:119]
	v_mfma_f32_16x16x32_bf16 v[104:107], v[170:173], v[194:197], v[104:107]
	v_mfma_f32_16x16x32_bf16 v[84:87], v[158:161], v[202:205], v[84:87]
	v_mfma_f32_16x16x32_bf16 v[80:83], v[170:173], v[202:205], v[80:83]
	v_mfma_f32_16x16x32_bf16 v[68:71], v[158:161], v[210:213], v[68:71]
	v_mfma_f32_16x16x32_bf16 v[64:67], v[170:173], v[210:213], v[64:67]
	v_mfma_f32_16x16x32_bf16 v[132:135], v[166:169], v[190:193], v[132:135]
	v_mfma_f32_16x16x32_bf16 v[128:131], v[182:185], v[190:193], v[128:131]
	v_mfma_f32_16x16x32_bf16 v[116:119], v[166:169], v[198:201], v[116:119]
	v_mfma_f32_16x16x32_bf16 v[104:107], v[182:185], v[198:201], v[104:107]
	v_mfma_f32_16x16x32_bf16 v[84:87], v[166:169], v[206:209], v[84:87]
	v_mfma_f32_16x16x32_bf16 v[80:83], v[182:185], v[206:209], v[80:83]
	v_mfma_f32_16x16x32_bf16 v[68:71], v[166:169], v[214:217], v[68:71]
	v_mfma_f32_16x16x32_bf16 v[64:67], v[182:185], v[214:217], v[64:67]
	s_barrier
	s_add_i32 s6, s70, s55
	v_lshl_add_u64 v[162:163], s[42:43], 0, v[144:145]
	s_mov_b32 m0, s6
	ds_read_b128 v[186:189], v181 offset:16384
	ds_read_b128 v[190:193], v181 offset:17408
	ds_read_b128 v[194:197], v181 offset:18432
	ds_read_b128 v[198:201], v181 offset:19456
	ds_read_b128 v[202:205], v181 offset:20480
	ds_read_b128 v[206:209], v181 offset:21504
	ds_read_b128 v[210:213], v181 offset:22528
	ds_read_b128 v[214:217], v181 offset:23552
	global_load_lds_dwordx4 v[162:163], off
	s_add_i32 m0, s6, 0x2000
	s_add_u32 s6, s42, 0x80000
	v_lshl_add_u64 v[174:175], s[42:43], 0, v[146:147]
	s_addc_u32 s7, s43, 0
	s_add_i32 s9, s71, s55
	global_load_lds_dwordx4 v[174:175], off
	v_lshl_add_u64 v[218:219], s[6:7], 0, v[144:145]
	s_mov_b32 m0, s9
	v_lshl_add_u64 v[220:221], s[44:45], 0, v[146:147]
	global_load_lds_dwordx4 v[218:219], off
	v_lshl_add_u64 v[218:219], s[6:7], 0, v[146:147]
	s_add_i32 m0, s9, 0x2000
	s_nop 0
	global_load_lds_dwordx4 v[218:219], off
	v_lshl_add_u64 v[218:219], s[44:45], 0, v[144:145]
	s_mov_b32 m0, s56
	s_nop 0
	global_load_lds_dwordx4 v[218:219], off
	s_mov_b32 m0, s57
	s_nop 0
	global_load_lds_dwordx4 v[220:221], off
	s_waitcnt vmcnt(8)
	s_waitcnt lgkmcnt(0)
	s_barrier
; #define PG8_STAGE(bufoff, gbase, voff) do { _Pragma("unroll") for (int _i = 0; _i < 2; ++_i) \
;         __builtin_amdgcn_global_load_lds((const unsigned*)((const char*)(gbase) + (voff)[_i]), (PG8_LAS unsigned*)(lds + (bufoff) + ldsw + _i * 8192), 16, 0, 0); } while (0)
; #define PG8_LDA(dst, b, h) do { _Pragma("unroll") for (int m = 0; m < 4; ++m) _Pragma("unroll") for (int k = 0; k < 2; ++k) dst[m][k] = *(const PG8_LAS bf16x8*)(lds + PG8_SA(b, h) + aoff + m * 2048 + k * 1024); } while (0)
; #define PG8_LDB(dst, b, h) do { _Pragma("unroll") for (int n = 0; n < 2; ++n) _Pragma("unroll") for (int k = 0; k < 2; ++k) dst[n][k] = *(const PG8_LAS bf16x8*)(lds + PG8_SB(b, h) + boff + n * 2048 + k * 1024); } while (0)
; #define PG8_MMA(ai, bj, At, Bt) do { __builtin_amdgcn_s_setprio(1); _Pragma("unroll") for (int m = 0; m < 4; ++m) _Pragma("unroll") for (int n = 0; n < 2; ++n) _Pragma("unroll") for (int k = 0; k < 2; ++k) \
;         acc[ai][bj][m][n] = __builtin_amdgcn_mfma_f32_16x16x32_bf16(Bt[n][k], At[m][k], acc[ai][bj][m][n], 0, 0, 0); __builtin_amdgcn_s_setprio(0); } while (0)
; #define PG8_WAIT_V(n) asm volatile("s_waitcnt vmcnt(" #n ")" ::: "memory")
; #define PG8_WAIT_L(n) asm volatile("s_waitcnt lgkmcnt(" #n ")" ::: "memory")
; #define PG8_BAR __builtin_amdgcn_s_barrier()
; #define PG8_SCHED __builtin_amdgcn_sched_barrier(0)
; template <class Epi, class Sched, bool ALIGN_EPI = false, bool SP2 = false>
; __device__ __forceinline__ void gemm_phase(PG8_LAS unsigned char* lds, const Gemm g, const Sched& S, const Epi& E) {
;     ...
;             PG8_WAIT_V(8); PG8_WAIT_L(0); PG8_BAR; PG8_MMA(1, 0, At, B0); PG8_MMA(1, 1, At, B1); PG8_BAR; PG8_SCHED;
;             PG8_LDB(B0, 1, 0); PG8_LDB(B1, 1, 1); PG8_SCHED; PG8_LDA(At, 1, 0); PG8_STAGE(PG8_SA(0, 1), a2 + hstepA, voffA);
;             PG8_WAIT_V(8); PG8_WAIT_L(0); PG8_BAR; PG8_MMA(0, 0, At, B0); PG8_MMA(0, 1, At, B1); PG8_BAR; PG8_SCHED;
	s_waitcnt lgkmcnt(0)
	v_mfma_f32_16x16x32_bf16 v[60:63], v[88:91], v[186:189], v[60:63]
	v_mfma_f32_16x16x32_bf16 v[56:59], v[108:111], v[186:189], v[56:59]
	v_mfma_f32_16x16x32_bf16 v[44:47], v[88:91], v[194:197], v[44:47]
	v_mfma_f32_16x16x32_bf16 v[40:43], v[108:111], v[194:197], v[40:43]
	v_mfma_f32_16x16x32_bf16 v[28:31], v[88:91], v[202:205], v[28:31]
	v_mfma_f32_16x16x32_bf16 v[24:27], v[108:111], v[202:205], v[24:27]
	v_mfma_f32_16x16x32_bf16 v[12:15], v[88:91], v[210:213], v[12:15]
	v_mfma_f32_16x16x32_bf16 v[8:11], v[108:111], v[210:213], v[8:11]
	v_mfma_f32_16x16x32_bf16 v[60:63], v[96:99], v[190:193], v[60:63]
	v_mfma_f32_16x16x32_bf16 v[56:59], v[112:115], v[190:193], v[56:59]
	v_mfma_f32_16x16x32_bf16 v[44:47], v[96:99], v[198:201], v[44:47]
	v_mfma_f32_16x16x32_bf16 v[40:43], v[112:115], v[198:201], v[40:43]
	v_mfma_f32_16x16x32_bf16 v[28:31], v[96:99], v[206:209], v[28:31]
	v_mfma_f32_16x16x32_bf16 v[24:27], v[112:115], v[206:209], v[24:27]
	v_mfma_f32_16x16x32_bf16 v[12:15], v[96:99], v[214:217], v[12:15]
	v_mfma_f32_16x16x32_bf16 v[8:11], v[112:115], v[214:217], v[8:11]
	v_mfma_f32_16x16x32_bf16 v[52:55], v[158:161], v[186:189], v[52:55]
	v_mfma_f32_16x16x32_bf16 v[48:51], v[170:173], v[186:189], v[48:51]
	v_mfma_f32_16x16x32_bf16 v[36:39], v[158:161], v[194:197], v[36:39]
	v_mfma_f32_16x16x32_bf16 v[32:35], v[170:173], v[194:197], v[32:35]
	v_mfma_f32_16x16x32_bf16 v[20:23], v[158:161], v[202:205], v[20:23]
	v_mfma_f32_16x16x32_bf16 v[16:19], v[170:173], v[202:205], v[16:19]
	v_mfma_f32_16x16x32_bf16 v[4:7], v[158:161], v[210:213], v[4:7]
	v_mfma_f32_16x16x32_bf16 v[0:3], v[170:173], v[210:213], v[0:3]
	v_mfma_f32_16x16x32_bf16 v[52:55], v[166:169], v[190:193], v[52:55]
	v_mfma_f32_16x16x32_bf16 v[48:51], v[182:185], v[190:193], v[48:51]
	v_mfma_f32_16x16x32_bf16 v[36:39], v[166:169], v[198:201], v[36:39]
	v_mfma_f32_16x16x32_bf16 v[32:35], v[182:185], v[198:201], v[32:35]
	v_mfma_f32_16x16x32_bf16 v[20:23], v[166:169], v[206:209], v[20:23]
	v_mfma_f32_16x16x32_bf16 v[16:19], v[182:185], v[206:209], v[16:19]
	v_mfma_f32_16x16x32_bf16 v[4:7], v[166:169], v[214:217], v[4:7]
	v_mfma_f32_16x16x32_bf16 v[0:3], v[182:185], v[214:217], v[0:3]
	s_barrier
	s_add_i32 s9, 0, 0x18000
	s_add_i32 s34, 0, 0x1c000
	v_add_u32_e32 v112, s9, v177
	v_add_u32_e32 v148, s34, v177
	ds_read_b128 v[88:91], v112
	ds_read_b128 v[96:99], v112 offset:1024
	ds_read_b128 v[108:111], v112 offset:2048
	ds_read_b128 v[112:115], v112 offset:3072
	ds_read_b128 v[158:161], v148
	ds_read_b128 v[166:169], v148 offset:1024
	ds_read_b128 v[170:173], v148 offset:2048
	ds_read_b128 v[182:185], v148 offset:3072
	s_add_u32 s6, s44, 0x80000
	s_addc_u32 s7, s45, 0
	s_mov_b32 m0, s58
	v_lshl_add_u64 v[222:223], s[6:7], 0, v[144:145]
	ds_read_b128 v[186:189], v181 offset:32768
	ds_read_b128 v[190:193], v181 offset:33792
	ds_read_b128 v[194:197], v181 offset:34816
	ds_read_b128 v[198:201], v181 offset:35840
	ds_read_b128 v[202:205], v181 offset:36864
	ds_read_b128 v[206:209], v181 offset:37888
	ds_read_b128 v[210:213], v181 offset:38912
	ds_read_b128 v[214:217], v181 offset:39936
	global_load_lds_dwordx4 v[222:223], off
	v_lshl_add_u64 v[222:223], s[6:7], 0, v[146:147]
	s_mov_b32 m0, s59
	s_nop 0
	global_load_lds_dwordx4 v[222:223], off
	s_waitcnt vmcnt(8)
	s_waitcnt lgkmcnt(0)
	s_barrier
	s_waitcnt lgkmcnt(0)
	v_mfma_f32_16x16x32_bf16 v[140:143], v[88:91], v[186:189], v[140:143]
	v_mfma_f32_16x16x32_bf16 v[136:139], v[108:111], v[186:189], v[136:139]
	v_mfma_f32_16x16x32_bf16 v[124:127], v[88:91], v[194:197], v[124:127]
	v_mfma_f32_16x16x32_bf16 v[120:123], v[108:111], v[194:197], v[120:123]
	v_mfma_f32_16x16x32_bf16 v[100:103], v[88:91], v[202:205], v[100:103]
	v_mfma_f32_16x16x32_bf16 v[92:95], v[108:111], v[202:205], v[92:95]
	v_mfma_f32_16x16x32_bf16 v[76:79], v[88:91], v[210:213], v[76:79]
	v_mfma_f32_16x16x32_bf16 v[72:75], v[108:111], v[210:213], v[72:75]
	v_mfma_f32_16x16x32_bf16 v[140:143], v[96:99], v[190:193], v[140:143]
	v_mfma_f32_16x16x32_bf16 v[136:139], v[112:115], v[190:193], v[136:139]
	v_mfma_f32_16x16x32_bf16 v[124:127], v[96:99], v[198:201], v[124:127]
	v_mfma_f32_16x16x32_bf16 v[120:123], v[112:115], v[198:201], v[120:123]
	v_mfma_f32_16x16x32_bf16 v[100:103], v[96:99], v[206:209], v[100:103]
	v_mfma_f32_16x16x32_bf16 v[92:95], v[112:115], v[206:209], v[92:95]
	v_mfma_f32_16x16x32_bf16 v[76:79], v[96:99], v[214:217], v[76:79]
	v_mfma_f32_16x16x32_bf16 v[72:75], v[112:115], v[214:217], v[72:75]
	v_mfma_f32_16x16x32_bf16 v[132:135], v[158:161], v[186:189], v[132:135]
	v_mfma_f32_16x16x32_bf16 v[128:131], v[170:173], v[186:189], v[128:131]
	v_mfma_f32_16x16x32_bf16 v[116:119], v[158:161], v[194:197], v[116:119]
	v_mfma_f32_16x16x32_bf16 v[104:107], v[170:173], v[194:197], v[104:107]
	v_mfma_f32_16x16x32_bf16 v[84:87], v[158:161], v[202:205], v[84:87]
	v_mfma_f32_16x16x32_bf16 v[80:83], v[170:173], v[202:205], v[80:83]
	v_mfma_f32_16x16x32_bf16 v[68:71], v[158:161], v[210:213], v[68:71]
	v_mfma_f32_16x16x32_bf16 v[64:67], v[170:173], v[210:213], v[64:67]
	v_mfma_f32_16x16x32_bf16 v[132:135], v[166:169], v[190:193], v[132:135]
	v_mfma_f32_16x16x32_bf16 v[128:131], v[182:185], v[190:193], v[128:131]
	v_mfma_f32_16x16x32_bf16 v[116:119], v[166:169], v[198:201], v[116:119]
	v_mfma_f32_16x16x32_bf16 v[104:107], v[182:185], v[198:201], v[104:107]
	v_mfma_f32_16x16x32_bf16 v[84:87], v[166:169], v[206:209], v[84:87]
	v_mfma_f32_16x16x32_bf16 v[80:83], v[182:185], v[206:209], v[80:83]
	v_mfma_f32_16x16x32_bf16 v[68:71], v[166:169], v[214:217], v[68:71]
	v_mfma_f32_16x16x32_bf16 v[64:67], v[182:185], v[214:217], v[64:67]
	s_barrier
; #define PG8_STAGE(bufoff, gbase, voff) do { _Pragma("unroll") for (int _i = 0; _i < 2; ++_i) \
;         __builtin_amdgcn_global_load_lds((const unsigned*)((const char*)(gbase) + (voff)[_i]), (PG8_LAS unsigned*)(lds + (bufoff) + ldsw + _i * 8192), 16, 0, 0); } while (0)
; #define PG8_LDA(dst, b, h) do { _Pragma("unroll") for (int m = 0; m < 4; ++m) _Pragma("unroll") for (int k = 0; k < 2; ++k) dst[m][k] = *(const PG8_LAS bf16x8*)(lds + PG8_SA(b, h) + aoff + m * 2048 + k * 1024); } while (0)
; #define PG8_MMA(ai, bj, At, Bt) do { __builtin_amdgcn_s_setprio(1); _Pragma("unroll") for (int m = 0; m < 4; ++m) _Pragma("unroll") for (int n = 0; n < 2; ++n) _Pragma("unroll") for (int k = 0; k < 2; ++k) \
;         acc[ai][bj][m][n] = __builtin_amdgcn_mfma_f32_16x16x32_bf16(Bt[n][k], At[m][k], acc[ai][bj][m][n], 0, 0, 0); __builtin_amdgcn_s_setprio(0); } while (0)
; #define PG8_WAIT_V(n) asm volatile("s_waitcnt vmcnt(" #n ")" ::: "memory")
; #define PG8_WAIT_L(n) asm volatile("s_waitcnt lgkmcnt(" #n ")" ::: "memory")
; #define PG8_BAR __builtin_amdgcn_s_barrier()
; #define PG8_SCHED __builtin_amdgcn_sched_barrier(0)
; template <class Epi, class Sched, bool ALIGN_EPI = false, bool SP2 = false>
; __device__ __forceinline__ void gemm_phase(PG8_LAS unsigned char* lds, const Gemm g, const Sched& S, const Epi& E) {
;     ...
;         for (int t = 0; t < nt; t += 2) {
;             const bool last = (t == nt - 2);
;     ...
;             PG8_LDA(At, 1, 1); PG8_STAGE(PG8_SB(1, 0), b3, voffB); PG8_STAGE(PG8_SB(1, 1), b3 + hstepB, voffB); PG8_STAGE(PG8_SA(1, 0), a3, voffA);
;             PG8_WAIT_V(8); PG8_WAIT_L(0); PG8_BAR; PG8_MMA(1, 0, At, B0); PG8_MMA(1, 1, At, B1); PG8_BAR; PG8_SCHED;
	s_add_i32 s6, s9, s55
	v_lshl_add_u64 v[162:163], v[162:163], 0, s[14:15]
	s_mov_b32 m0, s6
	ds_read_b128 v[186:189], v181 offset:49152
	ds_read_b128 v[190:193], v181 offset:50176
	ds_read_b128 v[194:197], v181 offset:51200
	ds_read_b128 v[198:201], v181 offset:52224
	ds_read_b128 v[202:205], v181 offset:53248
	ds_read_b128 v[206:209], v181 offset:54272
	ds_read_b128 v[210:213], v181 offset:55296
	ds_read_b128 v[214:217], v181 offset:56320
	global_load_lds_dwordx4 v[162:163], off
	s_add_i32 m0, s6, 0x2000
	s_add_u32 s6, s42, 0x80080
	v_lshl_add_u64 v[162:163], v[174:175], 0, s[14:15]
	s_addc_u32 s7, s43, 0
	s_add_i32 s9, s34, s55
	global_load_lds_dwordx4 v[162:163], off
	v_lshl_add_u64 v[162:163], s[6:7], 0, v[144:145]
	s_mov_b32 m0, s9
	s_nop 0
	global_load_lds_dwordx4 v[162:163], off
	v_lshl_add_u64 v[162:163], s[6:7], 0, v[146:147]
	s_add_i32 m0, s9, 0x2000
	s_nop 0
	global_load_lds_dwordx4 v[162:163], off
	v_lshl_add_u64 v[162:163], v[218:219], 0, s[14:15]
	s_mov_b32 m0, s63
	s_nop 0
	global_load_lds_dwordx4 v[162:163], off
	v_lshl_add_u64 v[162:163], v[220:221], 0, s[14:15]
	s_mov_b32 m0, s64
	s_nop 0
	global_load_lds_dwordx4 v[162:163], off
	s_waitcnt vmcnt(8)
	s_waitcnt lgkmcnt(0)
	s_barrier
	s_waitcnt lgkmcnt(0)
	v_mfma_f32_16x16x32_bf16 v[60:63], v[88:91], v[186:189], v[60:63]
	v_mfma_f32_16x16x32_bf16 v[56:59], v[108:111], v[186:189], v[56:59]
	v_mfma_f32_16x16x32_bf16 v[44:47], v[88:91], v[194:197], v[44:47]
	v_mfma_f32_16x16x32_bf16 v[40:43], v[108:111], v[194:197], v[40:43]
	v_mfma_f32_16x16x32_bf16 v[28:31], v[88:91], v[202:205], v[28:31]
	v_mfma_f32_16x16x32_bf16 v[24:27], v[108:111], v[202:205], v[24:27]
	v_mfma_f32_16x16x32_bf16 v[12:15], v[88:91], v[210:213], v[12:15]
	v_mfma_f32_16x16x32_bf16 v[8:11], v[108:111], v[210:213], v[8:11]
	v_mfma_f32_16x16x32_bf16 v[60:63], v[96:99], v[190:193], v[60:63]
	v_mfma_f32_16x16x32_bf16 v[56:59], v[112:115], v[190:193], v[56:59]
	v_mfma_f32_16x16x32_bf16 v[44:47], v[96:99], v[198:201], v[44:47]
	v_mfma_f32_16x16x32_bf16 v[40:43], v[112:115], v[198:201], v[40:43]
	v_mfma_f32_16x16x32_bf16 v[28:31], v[96:99], v[206:209], v[28:31]
	v_mfma_f32_16x16x32_bf16 v[24:27], v[112:115], v[206:209], v[24:27]
	v_mfma_f32_16x16x32_bf16 v[12:15], v[96:99], v[214:217], v[12:15]
	v_mfma_f32_16x16x32_bf16 v[8:11], v[112:115], v[214:217], v[8:11]
	v_mfma_f32_16x16x32_bf16 v[52:55], v[158:161], v[186:189], v[52:55]
	v_mfma_f32_16x16x32_bf16 v[48:51], v[170:173], v[186:189], v[48:51]
	v_mfma_f32_16x16x32_bf16 v[36:39], v[158:161], v[194:197], v[36:39]
	v_mfma_f32_16x16x32_bf16 v[32:35], v[170:173], v[194:197], v[32:35]
	v_mfma_f32_16x16x32_bf16 v[20:23], v[158:161], v[202:205], v[20:23]
	v_mfma_f32_16x16x32_bf16 v[16:19], v[170:173], v[202:205], v[16:19]
	v_mfma_f32_16x16x32_bf16 v[4:7], v[158:161], v[210:213], v[4:7]
	v_mfma_f32_16x16x32_bf16 v[0:3], v[170:173], v[210:213], v[0:3]
	v_mfma_f32_16x16x32_bf16 v[52:55], v[166:169], v[190:193], v[52:55]
	v_mfma_f32_16x16x32_bf16 v[48:51], v[182:185], v[190:193], v[48:51]
	v_mfma_f32_16x16x32_bf16 v[36:39], v[166:169], v[198:201], v[36:39]
	v_mfma_f32_16x16x32_bf16 v[32:35], v[182:185], v[198:201], v[32:35]
	v_mfma_f32_16x16x32_bf16 v[20:23], v[166:169], v[206:209], v[20:23]
	v_mfma_f32_16x16x32_bf16 v[16:19], v[182:185], v[206:209], v[16:19]
	v_mfma_f32_16x16x32_bf16 v[4:7], v[166:169], v[214:217], v[4:7]
	v_mfma_f32_16x16x32_bf16 v[0:3], v[182:185], v[214:217], v[0:3]
	s_barrier
	s_add_i32 s80, s80, 2
	s_add_u32 s40, s40, 0x100
	s_addc_u32 s41, s41, 0
	s_add_u32 s76, s76, 0x100
	s_addc_u32 s77, s77, 0
	s_cmp_gt_u32 s80, 29
	s_cbranch_scc0 .LBB0_1485
	s_and_b64 vcc, exec, s[16:17]
	s_cbranch_vccz .LBB0_1488
	s_barrier

; #define PG8_STAGE(bufoff, gbase, voff) do { _Pragma("unroll") for (int _i = 0; _i < 2; ++_i) \
;         __builtin_amdgcn_global_load_lds((const unsigned*)((const char*)(gbase) + (voff)[_i]), (PG8_LAS unsigned*)(lds + (bufoff) + ldsw + _i * 8192), 16, 0, 0); } while (0)
; #define PG8_LDA(dst, b, h) do { _Pragma("unroll") for (int m = 0; m < 4; ++m) _Pragma("unroll") for (int k = 0; k < 2; ++k) dst[m][k] = *(const PG8_LAS bf16x8*)(lds + PG8_SA(b, h) + aoff + m * 2048 + k * 1024); } while (0)
; #define PG8_LDB(dst, b, h) do { _Pragma("unroll") for (int n = 0; n < 2; ++n) _Pragma("unroll") for (int k = 0; k < 2; ++k) dst[n][k] = *(const PG8_LAS bf16x8*)(lds + PG8_SB(b, h) + boff + n * 2048 + k * 1024); } while (0)
; #define PG8_MMA(ai, bj, At, Bt) do { __builtin_amdgcn_s_setprio(1); _Pragma("unroll") for (int m = 0; m < 4; ++m) _Pragma("unroll") for (int n = 0; n < 2; ++n) _Pragma("unroll") for (int k = 0; k < 2; ++k) \
;         acc[ai][bj][m][n] = __builtin_amdgcn_mfma_f32_16x16x32_bf16(Bt[n][k], At[m][k], acc[ai][bj][m][n], 0, 0, 0); __builtin_amdgcn_s_setprio(0); } while (0)
; #define PG8_WAIT_V(n) asm volatile("s_waitcnt vmcnt(" #n ")" ::: "memory")
; template <class Epi, class Sched, bool ALIGN_EPI = false, bool SP2 = false>
; __device__ __forceinline__ void gemm_phase(PG8_LAS unsigned char* lds, const Gemm g, const Sched& S, const Epi& E) {
;     ...
;         const char* nA = has_next ? (const char*)g.A + (size_t)nxt.pm * tstepA + (size_t)nxt.kofs * kmulA : cA; const char* nB = has_next ? (const char*)g.Bt + (size_t)nxt.pn * tstepB + (size_t)nxt.kofs * 2 : cB;
;         for (int t = 0; t < nt; t += 2) {
;             const bool last = (t == nt - 2);
;             const char* a1 = cA + (size_t)(t + 1) * kstepA;
;             const char* a2 = last ? nA : cA + (size_t)(t + 2) * kstepA; const char* b2 = last ? nB : cB + (size_t)(t + 2) * kstep;
;     ...
;             PG8_LDB(B0, 0, 0); PG8_LDB(B1, 0, 1); PG8_SCHED; PG8_LDA(At, 0, 0); PG8_STAGE(PG8_SA(1, 1), a1 + hstepA, voffA);
;             PG8_WAIT_V(8); PG8_WAIT_L(0); PG8_BAR; PG8_MMA(0, 0, At, B0); PG8_MMA(0, 1, At, B1); PG8_BAR; PG8_SCHED;
;             PG8_LDA(At, 0, 1); PG8_STAGE(PG8_SB(0, 0), b2, voffB); PG8_STAGE(PG8_SB(0, 1), b2 + hstepB, voffB); PG8_STAGE(PG8_SA(0, 0), a2, voffA);
;             PG8_WAIT_V(8); PG8_WAIT_L(0); PG8_BAR; PG8_MMA(1, 0, At, B0); PG8_MMA(1, 1, At, B1); PG8_BAR; PG8_SCHED;
.LBB0_1626:
	ds_read_b128 v[156:159], v153
	ds_read_b128 v[160:163], v153 offset:1024
	ds_read_b128 v[166:169], v153 offset:2048
	ds_read_b128 v[170:173], v153 offset:3072
	ds_read_b128 v[174:177], v154
	ds_read_b128 v[178:181], v154 offset:1024
	ds_read_b128 v[182:185], v154 offset:2048
	ds_read_b128 v[186:189], v154 offset:3072
	s_add_u32 s6, s38, 0xfff80080
	s_addc_u32 s7, s39, -1
	s_cmp_eq_u32 s70, 28
	s_cselect_b32 s43, s23, s7
	s_cselect_b32 s42, s44, s6
	s_cselect_b32 s41, s17, s69
	s_cselect_b32 s40, s45, s68
	v_lshl_add_u64 v[222:223], s[38:39], 0, v[144:145]
	s_add_i32 m0, s56, 0xc000
	ds_read_b128 v[190:193], v155
	ds_read_b128 v[194:197], v155 offset:1024
	ds_read_b128 v[198:201], v155 offset:2048
	ds_read_b128 v[202:205], v155 offset:3072
	ds_read_b128 v[206:209], v155 offset:4096
	ds_read_b128 v[210:213], v155 offset:5120
	ds_read_b128 v[214:217], v155 offset:6144
	ds_read_b128 v[218:221], v155 offset:7168
	global_load_lds_dwordx4 v[222:223], off
	v_lshl_add_u64 v[222:223], s[38:39], 0, v[146:147]
	s_add_i32 m0, s56, 0xe000
	s_nop 0
	global_load_lds_dwordx4 v[222:223], off
	s_waitcnt vmcnt(8)
	s_waitcnt lgkmcnt(0)
	s_barrier
	s_waitcnt lgkmcnt(0)
	v_mfma_f32_16x16x32_bf16 v[124:127], v[156:159], v[190:193], v[124:127]
	v_mfma_f32_16x16x32_bf16 v[120:123], v[166:169], v[190:193], v[120:123]
	v_mfma_f32_16x16x32_bf16 v[108:111], v[156:159], v[198:201], v[108:111]
	v_mfma_f32_16x16x32_bf16 v[104:107], v[166:169], v[198:201], v[104:107]
	v_mfma_f32_16x16x32_bf16 v[92:95], v[156:159], v[206:209], v[92:95]
	v_mfma_f32_16x16x32_bf16 v[88:91], v[166:169], v[206:209], v[88:91]
	v_mfma_f32_16x16x32_bf16 v[76:79], v[156:159], v[214:217], v[76:79]
	v_mfma_f32_16x16x32_bf16 v[72:75], v[166:169], v[214:217], v[72:75]
	v_mfma_f32_16x16x32_bf16 v[124:127], v[160:163], v[194:197], v[124:127]
	v_mfma_f32_16x16x32_bf16 v[120:123], v[170:173], v[194:197], v[120:123]
	v_mfma_f32_16x16x32_bf16 v[108:111], v[160:163], v[202:205], v[108:111]
	v_mfma_f32_16x16x32_bf16 v[104:107], v[170:173], v[202:205], v[104:107]
	v_mfma_f32_16x16x32_bf16 v[92:95], v[160:163], v[210:213], v[92:95]
	v_mfma_f32_16x16x32_bf16 v[88:91], v[170:173], v[210:213], v[88:91]
	v_mfma_f32_16x16x32_bf16 v[76:79], v[160:163], v[218:221], v[76:79]
	v_mfma_f32_16x16x32_bf16 v[72:75], v[170:173], v[218:221], v[72:75]
	v_mfma_f32_16x16x32_bf16 v[116:119], v[174:177], v[190:193], v[116:119]
	v_mfma_f32_16x16x32_bf16 v[112:115], v[182:185], v[190:193], v[112:115]
	v_mfma_f32_16x16x32_bf16 v[100:103], v[174:177], v[198:201], v[100:103]
	v_mfma_f32_16x16x32_bf16 v[96:99], v[182:185], v[198:201], v[96:99]
	v_mfma_f32_16x16x32_bf16 v[84:87], v[174:177], v[206:209], v[84:87]
	v_mfma_f32_16x16x32_bf16 v[80:83], v[182:185], v[206:209], v[80:83]
	v_mfma_f32_16x16x32_bf16 v[68:71], v[174:177], v[214:217], v[68:71]
	v_mfma_f32_16x16x32_bf16 v[64:67], v[182:185], v[214:217], v[64:67]
	v_mfma_f32_16x16x32_bf16 v[116:119], v[178:181], v[194:197], v[116:119]
	v_mfma_f32_16x16x32_bf16 v[112:115], v[186:189], v[194:197], v[112:115]
	v_mfma_f32_16x16x32_bf16 v[100:103], v[178:181], v[202:205], v[100:103]
	v_mfma_f32_16x16x32_bf16 v[96:99], v[186:189], v[202:205], v[96:99]
	v_mfma_f32_16x16x32_bf16 v[84:87], v[178:181], v[210:213], v[84:87]
	v_mfma_f32_16x16x32_bf16 v[80:83], v[186:189], v[210:213], v[80:83]
	v_mfma_f32_16x16x32_bf16 v[68:71], v[178:181], v[218:221], v[68:71]
	v_mfma_f32_16x16x32_bf16 v[64:67], v[186:189], v[218:221], v[64:67]
	s_barrier
	s_add_i32 s6, s66, s55
	v_lshl_add_u64 v[222:223], s[40:41], 0, v[130:131]
	s_mov_b32 m0, s6
	ds_read_b128 v[190:193], v155 offset:16384
	ds_read_b128 v[194:197], v155 offset:17408
	ds_read_b128 v[198:201], v155 offset:18432
	ds_read_b128 v[202:205], v155 offset:19456
	ds_read_b128 v[206:209], v155 offset:20480
	ds_read_b128 v[210:213], v155 offset:21504
	ds_read_b128 v[214:217], v155 offset:22528
	ds_read_b128 v[218:221], v155 offset:23552
	global_load_lds_dwordx4 v[222:223], off
	s_add_i32 m0, s6, 0x2000
	s_add_u32 s6, s40, 0x80000
	v_lshl_add_u64 v[224:225], s[40:41], 0, v[134:135]
	s_addc_u32 s7, s41, 0
	s_add_i32 s9, s67, s55
	global_load_lds_dwordx4 v[224:225], off
	v_lshl_add_u64 v[226:227], s[6:7], 0, v[130:131]
	s_mov_b32 m0, s9
	v_lshl_add_u64 v[228:229], s[42:43], 0, v[132:133]
	global_load_lds_dwordx4 v[226:227], off
	v_lshl_add_u64 v[226:227], s[6:7], 0, v[134:135]
	s_add_i32 m0, s9, 0x2000
	s_nop 0
	global_load_lds_dwordx4 v[226:227], off
	v_lshl_add_u64 v[226:227], s[42:43], 0, v[128:129]
	s_mov_b32 m0, s56
	s_nop 0
	global_load_lds_dwordx4 v[226:227], off
	s_mov_b32 m0, s57
	s_nop 0
	global_load_lds_dwordx4 v[228:229], off
	s_waitcnt vmcnt(8)
	s_waitcnt lgkmcnt(0)
	s_barrier
; #define PG8_STAGE(bufoff, gbase, voff) do { _Pragma("unroll") for (int _i = 0; _i < 2; ++_i) \
;         __builtin_amdgcn_global_load_lds((const unsigned*)((const char*)(gbase) + (voff)[_i]), (PG8_LAS unsigned*)(lds + (bufoff) + ldsw + _i * 8192), 16, 0, 0); } while (0)
; #define PG8_LDA(dst, b, h) do { _Pragma("unroll") for (int m = 0; m < 4; ++m) _Pragma("unroll") for (int k = 0; k < 2; ++k) dst[m][k] = *(const PG8_LAS bf16x8*)(lds + PG8_SA(b, h) + aoff + m * 2048 + k * 1024); } while (0)
; #define PG8_LDB(dst, b, h) do { _Pragma("unroll") for (int n = 0; n < 2; ++n) _Pragma("unroll") for (int k = 0; k < 2; ++k) dst[n][k] = *(const PG8_LAS bf16x8*)(lds + PG8_SB(b, h) + boff + n * 2048 + k * 1024); } while (0)
; #define PG8_MMA(ai, bj, At, Bt) do { __builtin_amdgcn_s_setprio(1); _Pragma("unroll") for (int m = 0; m < 4; ++m) _Pragma("unroll") for (int n = 0; n < 2; ++n) _Pragma("unroll") for (int k = 0; k < 2; ++k) \
;         acc[ai][bj][m][n] = __builtin_amdgcn_mfma_f32_16x16x32_bf16(Bt[n][k], At[m][k], acc[ai][bj][m][n], 0, 0, 0); __builtin_amdgcn_s_setprio(0); } while (0)
; #define PG8_WAIT_V(n) asm volatile("s_waitcnt vmcnt(" #n ")" ::: "memory")
; #define PG8_WAIT_L(n) asm volatile("s_waitcnt lgkmcnt(" #n ")" ::: "memory")
; #define PG8_BAR __builtin_amdgcn_s_barrier()
; #define PG8_SCHED __builtin_amdgcn_sched_barrier(0)
; template <class Epi, class Sched, bool ALIGN_EPI = false, bool SP2 = false>
; __device__ __forceinline__ void gemm_phase(PG8_LAS unsigned char* lds, const Gemm g, const Sched& S, const Epi& E) {
;     ...
;             PG8_WAIT_V(8); PG8_WAIT_L(0); PG8_BAR; PG8_MMA(1, 0, At, B0); PG8_MMA(1, 1, At, B1); PG8_BAR; PG8_SCHED;
;             PG8_LDB(B0, 1, 0); PG8_LDB(B1, 1, 1); PG8_SCHED; PG8_LDA(At, 1, 0); PG8_STAGE(PG8_SA(0, 1), a2 + hstepA, voffA);
;             PG8_WAIT_V(8); PG8_WAIT_L(0); PG8_BAR; PG8_MMA(0, 0, At, B0); PG8_MMA(0, 1, At, B1); PG8_BAR; PG8_SCHED;
	s_waitcnt lgkmcnt(0)
	v_mfma_f32_16x16x32_bf16 v[60:63], v[156:159], v[190:193], v[60:63]
	v_mfma_f32_16x16x32_bf16 v[56:59], v[166:169], v[190:193], v[56:59]
	v_mfma_f32_16x16x32_bf16 v[44:47], v[156:159], v[198:201], v[44:47]
	v_mfma_f32_16x16x32_bf16 v[40:43], v[166:169], v[198:201], v[40:43]
	v_mfma_f32_16x16x32_bf16 v[28:31], v[156:159], v[206:209], v[28:31]
	v_mfma_f32_16x16x32_bf16 v[24:27], v[166:169], v[206:209], v[24:27]
	v_mfma_f32_16x16x32_bf16 v[12:15], v[156:159], v[214:217], v[12:15]
	v_mfma_f32_16x16x32_bf16 v[8:11], v[166:169], v[214:217], v[8:11]
	v_mfma_f32_16x16x32_bf16 v[60:63], v[160:163], v[194:197], v[60:63]
	v_mfma_f32_16x16x32_bf16 v[56:59], v[170:173], v[194:197], v[56:59]
	v_mfma_f32_16x16x32_bf16 v[44:47], v[160:163], v[202:205], v[44:47]
	v_mfma_f32_16x16x32_bf16 v[40:43], v[170:173], v[202:205], v[40:43]
	v_mfma_f32_16x16x32_bf16 v[28:31], v[160:163], v[210:213], v[28:31]
	v_mfma_f32_16x16x32_bf16 v[24:27], v[170:173], v[210:213], v[24:27]
	v_mfma_f32_16x16x32_bf16 v[12:15], v[160:163], v[218:221], v[12:15]
	v_mfma_f32_16x16x32_bf16 v[8:11], v[170:173], v[218:221], v[8:11]
	v_mfma_f32_16x16x32_bf16 v[52:55], v[174:177], v[190:193], v[52:55]
	v_mfma_f32_16x16x32_bf16 v[48:51], v[182:185], v[190:193], v[48:51]
	v_mfma_f32_16x16x32_bf16 v[36:39], v[174:177], v[198:201], v[36:39]
	v_mfma_f32_16x16x32_bf16 v[32:35], v[182:185], v[198:201], v[32:35]
	v_mfma_f32_16x16x32_bf16 v[20:23], v[174:177], v[206:209], v[20:23]
	v_mfma_f32_16x16x32_bf16 v[16:19], v[182:185], v[206:209], v[16:19]
	v_mfma_f32_16x16x32_bf16 v[4:7], v[174:177], v[214:217], v[4:7]
	v_mfma_f32_16x16x32_bf16 v[0:3], v[182:185], v[214:217], v[0:3]
	v_mfma_f32_16x16x32_bf16 v[52:55], v[178:181], v[194:197], v[52:55]
	v_mfma_f32_16x16x32_bf16 v[48:51], v[186:189], v[194:197], v[48:51]
	v_mfma_f32_16x16x32_bf16 v[36:39], v[178:181], v[202:205], v[36:39]
	v_mfma_f32_16x16x32_bf16 v[32:35], v[186:189], v[202:205], v[32:35]
	v_mfma_f32_16x16x32_bf16 v[20:23], v[178:181], v[210:213], v[20:23]
	v_mfma_f32_16x16x32_bf16 v[16:19], v[186:189], v[210:213], v[16:19]
	v_mfma_f32_16x16x32_bf16 v[4:7], v[178:181], v[218:221], v[4:7]
	v_mfma_f32_16x16x32_bf16 v[0:3], v[186:189], v[218:221], v[0:3]
	s_barrier
	s_add_i32 s9, 0, 0x18000
	s_add_i32 s34, 0, 0x1c000
	v_add_u32_e32 v170, s9, v152
	v_add_u32_e32 v186, s34, v152
	ds_read_b128 v[156:159], v170
	ds_read_b128 v[160:163], v170 offset:1024
	ds_read_b128 v[166:169], v170 offset:2048
	ds_read_b128 v[170:173], v170 offset:3072
	ds_read_b128 v[174:177], v186
	ds_read_b128 v[178:181], v186 offset:1024
	ds_read_b128 v[182:185], v186 offset:2048
	ds_read_b128 v[186:189], v186 offset:3072
	s_add_u32 s6, s42, 0x80000
	s_addc_u32 s7, s43, 0
	s_mov_b32 m0, s58
	v_lshl_add_u64 v[230:231], s[6:7], 0, v[128:129]
	ds_read_b128 v[190:193], v155 offset:32768
	ds_read_b128 v[194:197], v155 offset:33792
	ds_read_b128 v[198:201], v155 offset:34816
	ds_read_b128 v[202:205], v155 offset:35840
	ds_read_b128 v[206:209], v155 offset:36864
	ds_read_b128 v[210:213], v155 offset:37888
	ds_read_b128 v[214:217], v155 offset:38912
	ds_read_b128 v[218:221], v155 offset:39936
	global_load_lds_dwordx4 v[230:231], off
	v_lshl_add_u64 v[230:231], s[6:7], 0, v[132:133]
	s_mov_b32 m0, s59
	s_nop 0
	global_load_lds_dwordx4 v[230:231], off
	s_waitcnt vmcnt(8)
	s_waitcnt lgkmcnt(0)
	s_barrier
	s_waitcnt lgkmcnt(0)
	v_mfma_f32_16x16x32_bf16 v[124:127], v[156:159], v[190:193], v[124:127]
	v_mfma_f32_16x16x32_bf16 v[120:123], v[166:169], v[190:193], v[120:123]
	v_mfma_f32_16x16x32_bf16 v[108:111], v[156:159], v[198:201], v[108:111]
	v_mfma_f32_16x16x32_bf16 v[104:107], v[166:169], v[198:201], v[104:107]
	v_mfma_f32_16x16x32_bf16 v[92:95], v[156:159], v[206:209], v[92:95]
	v_mfma_f32_16x16x32_bf16 v[88:91], v[166:169], v[206:209], v[88:91]
	v_mfma_f32_16x16x32_bf16 v[76:79], v[156:159], v[214:217], v[76:79]
	v_mfma_f32_16x16x32_bf16 v[72:75], v[166:169], v[214:217], v[72:75]
	v_mfma_f32_16x16x32_bf16 v[124:127], v[160:163], v[194:197], v[124:127]
	v_mfma_f32_16x16x32_bf16 v[120:123], v[170:173], v[194:197], v[120:123]
	v_mfma_f32_16x16x32_bf16 v[108:111], v[160:163], v[202:205], v[108:111]
	v_mfma_f32_16x16x32_bf16 v[104:107], v[170:173], v[202:205], v[104:107]
	v_mfma_f32_16x16x32_bf16 v[92:95], v[160:163], v[210:213], v[92:95]
	v_mfma_f32_16x16x32_bf16 v[88:91], v[170:173], v[210:213], v[88:91]
	v_mfma_f32_16x16x32_bf16 v[76:79], v[160:163], v[218:221], v[76:79]
	v_mfma_f32_16x16x32_bf16 v[72:75], v[170:173], v[218:221], v[72:75]
	v_mfma_f32_16x16x32_bf16 v[116:119], v[174:177], v[190:193], v[116:119]
	v_mfma_f32_16x16x32_bf16 v[112:115], v[182:185], v[190:193], v[112:115]
	v_mfma_f32_16x16x32_bf16 v[100:103], v[174:177], v[198:201], v[100:103]
	v_mfma_f32_16x16x32_bf16 v[96:99], v[182:185], v[198:201], v[96:99]
	v_mfma_f32_16x16x32_bf16 v[84:87], v[174:177], v[206:209], v[84:87]
	v_mfma_f32_16x16x32_bf16 v[80:83], v[182:185], v[206:209], v[80:83]
	v_mfma_f32_16x16x32_bf16 v[68:71], v[174:177], v[214:217], v[68:71]
	v_mfma_f32_16x16x32_bf16 v[64:67], v[182:185], v[214:217], v[64:67]
	v_mfma_f32_16x16x32_bf16 v[116:119], v[178:181], v[194:197], v[116:119]
	v_mfma_f32_16x16x32_bf16 v[112:115], v[186:189], v[194:197], v[112:115]
	v_mfma_f32_16x16x32_bf16 v[100:103], v[178:181], v[202:205], v[100:103]
	v_mfma_f32_16x16x32_bf16 v[96:99], v[186:189], v[202:205], v[96:99]
	v_mfma_f32_16x16x32_bf16 v[84:87], v[178:181], v[210:213], v[84:87]
	v_mfma_f32_16x16x32_bf16 v[80:83], v[186:189], v[210:213], v[80:83]
	v_mfma_f32_16x16x32_bf16 v[68:71], v[178:181], v[218:221], v[68:71]
	v_mfma_f32_16x16x32_bf16 v[64:67], v[186:189], v[218:221], v[64:67]
	s_barrier
; #define PG8_STAGE(bufoff, gbase, voff) do { _Pragma("unroll") for (int _i = 0; _i < 2; ++_i) \
;         __builtin_amdgcn_global_load_lds((const unsigned*)((const char*)(gbase) + (voff)[_i]), (PG8_LAS unsigned*)(lds + (bufoff) + ldsw + _i * 8192), 16, 0, 0); } while (0)
; #define PG8_LDA(dst, b, h) do { _Pragma("unroll") for (int m = 0; m < 4; ++m) _Pragma("unroll") for (int k = 0; k < 2; ++k) dst[m][k] = *(const PG8_LAS bf16x8*)(lds + PG8_SA(b, h) + aoff + m * 2048 + k * 1024); } while (0)
; #define PG8_MMA(ai, bj, At, Bt) do { __builtin_amdgcn_s_setprio(1); _Pragma("unroll") for (int m = 0; m < 4; ++m) _Pragma("unroll") for (int n = 0; n < 2; ++n) _Pragma("unroll") for (int k = 0; k < 2; ++k) \
;         acc[ai][bj][m][n] = __builtin_amdgcn_mfma_f32_16x16x32_bf16(Bt[n][k], At[m][k], acc[ai][bj][m][n], 0, 0, 0); __builtin_amdgcn_s_setprio(0); } while (0)
; #define PG8_WAIT_V(n) asm volatile("s_waitcnt vmcnt(" #n ")" ::: "memory")
; #define PG8_WAIT_L(n) asm volatile("s_waitcnt lgkmcnt(" #n ")" ::: "memory")
; #define PG8_BAR __builtin_amdgcn_s_barrier()
; #define PG8_SCHED __builtin_amdgcn_sched_barrier(0)
; template <class Epi, class Sched, bool ALIGN_EPI = false, bool SP2 = false>
; __device__ __forceinline__ void gemm_phase(PG8_LAS unsigned char* lds, const Gemm g, const Sched& S, const Epi& E) {
;     ...
;         for (int t = 0; t < nt; t += 2) {
;             const bool last = (t == nt - 2);
;     ...
;             PG8_LDA(At, 1, 1); PG8_STAGE(PG8_SB(1, 0), b3, voffB); PG8_STAGE(PG8_SB(1, 1), b3 + hstepB, voffB); PG8_STAGE(PG8_SA(1, 0), a3, voffA);
;             PG8_WAIT_V(8); PG8_WAIT_L(0); PG8_BAR; PG8_MMA(1, 0, At, B0); PG8_MMA(1, 1, At, B1); PG8_BAR; PG8_SCHED;
	s_add_i32 s6, s9, s55
	v_lshl_add_u64 v[222:223], v[222:223], 0, s[12:13]
	s_mov_b32 m0, s6
	ds_read_b128 v[190:193], v155 offset:49152
	ds_read_b128 v[194:197], v155 offset:50176
	ds_read_b128 v[198:201], v155 offset:51200
	ds_read_b128 v[202:205], v155 offset:52224
	ds_read_b128 v[206:209], v155 offset:53248
	ds_read_b128 v[210:213], v155 offset:54272
	ds_read_b128 v[214:217], v155 offset:55296
	ds_read_b128 v[218:221], v155 offset:56320
	global_load_lds_dwordx4 v[222:223], off
	s_add_i32 m0, s6, 0x2000
	s_add_u32 s6, s40, 0x80080
	v_lshl_add_u64 v[222:223], v[224:225], 0, s[12:13]
	s_addc_u32 s7, s41, 0
	s_add_i32 s9, s34, s55
	global_load_lds_dwordx4 v[222:223], off
	v_lshl_add_u64 v[222:223], s[6:7], 0, v[130:131]
	s_mov_b32 m0, s9
	s_nop 0
	global_load_lds_dwordx4 v[222:223], off
	v_lshl_add_u64 v[222:223], s[6:7], 0, v[134:135]
	s_add_i32 m0, s9, 0x2000
	s_nop 0
	global_load_lds_dwordx4 v[222:223], off
	v_lshl_add_u64 v[222:223], v[226:227], 0, s[12:13]
	s_mov_b32 m0, s61
	s_nop 0
	global_load_lds_dwordx4 v[222:223], off
	v_lshl_add_u64 v[222:223], v[228:229], 0, s[12:13]
	s_mov_b32 m0, s62
	s_nop 0
	global_load_lds_dwordx4 v[222:223], off
	s_waitcnt vmcnt(8)
	s_waitcnt lgkmcnt(0)
	s_barrier
	s_waitcnt lgkmcnt(0)
	v_mfma_f32_16x16x32_bf16 v[60:63], v[156:159], v[190:193], v[60:63]
	v_mfma_f32_16x16x32_bf16 v[56:59], v[166:169], v[190:193], v[56:59]
	v_mfma_f32_16x16x32_bf16 v[44:47], v[156:159], v[198:201], v[44:47]
	v_mfma_f32_16x16x32_bf16 v[40:43], v[166:169], v[198:201], v[40:43]
	v_mfma_f32_16x16x32_bf16 v[28:31], v[156:159], v[206:209], v[28:31]
	v_mfma_f32_16x16x32_bf16 v[24:27], v[166:169], v[206:209], v[24:27]
	v_mfma_f32_16x16x32_bf16 v[12:15], v[156:159], v[214:217], v[12:15]
	v_mfma_f32_16x16x32_bf16 v[8:11], v[166:169], v[214:217], v[8:11]
	v_mfma_f32_16x16x32_bf16 v[60:63], v[160:163], v[194:197], v[60:63]
	v_mfma_f32_16x16x32_bf16 v[56:59], v[170:173], v[194:197], v[56:59]
	v_mfma_f32_16x16x32_bf16 v[44:47], v[160:163], v[202:205], v[44:47]
	v_mfma_f32_16x16x32_bf16 v[40:43], v[170:173], v[202:205], v[40:43]
	v_mfma_f32_16x16x32_bf16 v[28:31], v[160:163], v[210:213], v[28:31]
	v_mfma_f32_16x16x32_bf16 v[24:27], v[170:173], v[210:213], v[24:27]
	v_mfma_f32_16x16x32_bf16 v[12:15], v[160:163], v[218:221], v[12:15]
	v_mfma_f32_16x16x32_bf16 v[8:11], v[170:173], v[218:221], v[8:11]
	v_mfma_f32_16x16x32_bf16 v[52:55], v[174:177], v[190:193], v[52:55]
	v_mfma_f32_16x16x32_bf16 v[48:51], v[182:185], v[190:193], v[48:51]
	v_mfma_f32_16x16x32_bf16 v[36:39], v[174:177], v[198:201], v[36:39]
	v_mfma_f32_16x16x32_bf16 v[32:35], v[182:185], v[198:201], v[32:35]
	v_mfma_f32_16x16x32_bf16 v[20:23], v[174:177], v[206:209], v[20:23]
	v_mfma_f32_16x16x32_bf16 v[16:19], v[182:185], v[206:209], v[16:19]
	v_mfma_f32_16x16x32_bf16 v[4:7], v[174:177], v[214:217], v[4:7]
	v_mfma_f32_16x16x32_bf16 v[0:3], v[182:185], v[214:217], v[0:3]
	v_mfma_f32_16x16x32_bf16 v[52:55], v[178:181], v[194:197], v[52:55]
	v_mfma_f32_16x16x32_bf16 v[48:51], v[186:189], v[194:197], v[48:51]
	v_mfma_f32_16x16x32_bf16 v[36:39], v[178:181], v[202:205], v[36:39]
	v_mfma_f32_16x16x32_bf16 v[32:35], v[186:189], v[202:205], v[32:35]
	v_mfma_f32_16x16x32_bf16 v[20:23], v[178:181], v[210:213], v[20:23]
	v_mfma_f32_16x16x32_bf16 v[16:19], v[186:189], v[210:213], v[16:19]
	v_mfma_f32_16x16x32_bf16 v[4:7], v[178:181], v[218:221], v[4:7]
	v_mfma_f32_16x16x32_bf16 v[0:3], v[186:189], v[218:221], v[0:3]
	s_barrier
	s_add_i32 s70, s70, 2
	s_add_u32 s38, s38, 0x100
	s_addc_u32 s39, s39, 0
	s_add_u32 s68, s68, 0x100
	s_addc_u32 s69, s69, 0
	s_cmp_gt_u32 s70, 29
	s_cbranch_scc0 .LBB0_1626
	s_and_b64 vcc, exec, s[14:15]
	s_cbranch_vccz .LBB0_1629
	s_barrier

; #define PG8_STAGE(bufoff, gbase, voff) do { _Pragma("unroll") for (int _i = 0; _i < 2; ++_i) \
;         __builtin_amdgcn_global_load_lds((const unsigned*)((const char*)(gbase) + (voff)[_i]), (PG8_LAS unsigned*)(lds + (bufoff) + ldsw + _i * 8192), 16, 0, 0); } while (0)
; #define PG8_LDA(dst, b, h) do { _Pragma("unroll") for (int m = 0; m < 4; ++m) _Pragma("unroll") for (int k = 0; k < 2; ++k) dst[m][k] = *(const PG8_LAS bf16x8*)(lds + PG8_SA(b, h) + aoff + m * 2048 + k * 1024); } while (0)
; #define PG8_LDB(dst, b, h) do { _Pragma("unroll") for (int n = 0; n < 2; ++n) _Pragma("unroll") for (int k = 0; k < 2; ++k) dst[n][k] = *(const PG8_LAS bf16x8*)(lds + PG8_SB(b, h) + boff + n * 2048 + k * 1024); } while (0)
; #define PG8_MMA(ai, bj, At, Bt) do { __builtin_amdgcn_s_setprio(1); _Pragma("unroll") for (int m = 0; m < 4; ++m) _Pragma("unroll") for (int n = 0; n < 2; ++n) _Pragma("unroll") for (int k = 0; k < 2; ++k) \
;         acc[ai][bj][m][n] = __builtin_amdgcn_mfma_f32_16x16x32_bf16(Bt[n][k], At[m][k], acc[ai][bj][m][n], 0, 0, 0); __builtin_amdgcn_s_setprio(0); } while (0)
; #define PG8_WAIT_V(n) asm volatile("s_waitcnt vmcnt(" #n ")" ::: "memory")
; template <class Epi, class Sched, bool ALIGN_EPI = false, bool SP2 = false>
; __device__ __forceinline__ void gemm_phase(PG8_LAS unsigned char* lds, const Gemm g, const Sched& S, const Epi& E) {
;     ...
;         const char* nA = has_next ? (const char*)g.A + (size_t)nxt.pm * tstepA + (size_t)nxt.kofs * kmulA : cA; const char* nB = has_next ? (const char*)g.Bt + (size_t)nxt.pn * tstepB + (size_t)nxt.kofs * 2 : cB;
;         for (int t = 0; t < nt; t += 2) {
;             const bool last = (t == nt - 2);
;             const char* a1 = cA + (size_t)(t + 1) * kstepA;
;             const char* a2 = last ? nA : cA + (size_t)(t + 2) * kstepA; const char* b2 = last ? nB : cB + (size_t)(t + 2) * kstep;
;     ...
;             PG8_LDB(B0, 0, 0); PG8_LDB(B1, 0, 1); PG8_SCHED; PG8_LDA(At, 0, 0); PG8_STAGE(PG8_SA(1, 1), a1 + hstepA, voffA);
;             PG8_WAIT_V(8); PG8_WAIT_L(0); PG8_BAR; PG8_MMA(0, 0, At, B0); PG8_MMA(0, 1, At, B1); PG8_BAR; PG8_SCHED;
;             PG8_LDA(At, 0, 1); PG8_STAGE(PG8_SB(0, 0), b2, voffB); PG8_STAGE(PG8_SB(0, 1), b2 + hstepB, voffB); PG8_STAGE(PG8_SA(0, 0), a2, voffA);
;             PG8_WAIT_V(8); PG8_WAIT_L(0); PG8_BAR; PG8_MMA(1, 0, At, B0); PG8_MMA(1, 1, At, B1); PG8_BAR; PG8_SCHED;
.LBB0_1705:
	ds_read_b128 v[88:91], v177
	ds_read_b128 v[96:99], v177 offset:1024
	ds_read_b128 v[108:111], v177 offset:2048
	ds_read_b128 v[112:115], v177 offset:3072
	ds_read_b128 v[156:159], v178
	ds_read_b128 v[160:163], v178 offset:1024
	ds_read_b128 v[166:169], v178 offset:2048
	ds_read_b128 v[170:173], v178 offset:3072
	s_add_u32 s6, s54, 0xffe04000
	s_addc_u32 s7, s55, -1
	s_cmpk_eq_i32 s9, 0x7c
	s_cselect_b32 s7, s43, s7
	s_cselect_b32 s6, s78, s6
	s_cselect_b32 s57, s41, s81
	s_cselect_b32 s56, s79, s80
	v_lshl_add_u64 v[212:213], s[54:55], 0, v[144:145]
	s_add_i32 m0, s62, 0xc000
	ds_read_b128 v[180:183], v179
	ds_read_b128 v[184:187], v179 offset:1024
	ds_read_b128 v[188:191], v179 offset:2048
	ds_read_b128 v[192:195], v179 offset:3072
	ds_read_b128 v[196:199], v179 offset:4096
	ds_read_b128 v[200:203], v179 offset:5120
	ds_read_b128 v[204:207], v179 offset:6144
	ds_read_b128 v[208:211], v179 offset:7168
	global_load_lds_dwordx4 v[212:213], off
	v_lshl_add_u64 v[212:213], v[212:213], 0, s[26:27]
	s_add_i32 m0, s62, 0xe000
	s_nop 0
	global_load_lds_dwordx4 v[212:213], off
	s_waitcnt vmcnt(8)
	s_waitcnt lgkmcnt(0)
	s_barrier
	s_waitcnt lgkmcnt(0)
	v_mfma_f32_16x16x32_bf16 v[140:143], v[88:91], v[180:183], v[140:143]
	v_mfma_f32_16x16x32_bf16 v[136:139], v[108:111], v[180:183], v[136:139]
	v_mfma_f32_16x16x32_bf16 v[124:127], v[88:91], v[188:191], v[124:127]
	v_mfma_f32_16x16x32_bf16 v[120:123], v[108:111], v[188:191], v[120:123]
	v_mfma_f32_16x16x32_bf16 v[100:103], v[88:91], v[196:199], v[100:103]
	v_mfma_f32_16x16x32_bf16 v[92:95], v[108:111], v[196:199], v[92:95]
	v_mfma_f32_16x16x32_bf16 v[76:79], v[88:91], v[204:207], v[76:79]
	v_mfma_f32_16x16x32_bf16 v[72:75], v[108:111], v[204:207], v[72:75]
	v_mfma_f32_16x16x32_bf16 v[140:143], v[96:99], v[184:187], v[140:143]
	v_mfma_f32_16x16x32_bf16 v[136:139], v[112:115], v[184:187], v[136:139]
	v_mfma_f32_16x16x32_bf16 v[124:127], v[96:99], v[192:195], v[124:127]
	v_mfma_f32_16x16x32_bf16 v[120:123], v[112:115], v[192:195], v[120:123]
	v_mfma_f32_16x16x32_bf16 v[100:103], v[96:99], v[200:203], v[100:103]
	v_mfma_f32_16x16x32_bf16 v[92:95], v[112:115], v[200:203], v[92:95]
	v_mfma_f32_16x16x32_bf16 v[76:79], v[96:99], v[208:211], v[76:79]
	v_mfma_f32_16x16x32_bf16 v[72:75], v[112:115], v[208:211], v[72:75]
	v_mfma_f32_16x16x32_bf16 v[132:135], v[156:159], v[180:183], v[132:135]
	v_mfma_f32_16x16x32_bf16 v[128:131], v[166:169], v[180:183], v[128:131]
	v_mfma_f32_16x16x32_bf16 v[116:119], v[156:159], v[188:191], v[116:119]
	v_mfma_f32_16x16x32_bf16 v[104:107], v[166:169], v[188:191], v[104:107]
	v_mfma_f32_16x16x32_bf16 v[84:87], v[156:159], v[196:199], v[84:87]
	v_mfma_f32_16x16x32_bf16 v[80:83], v[166:169], v[196:199], v[80:83]
	v_mfma_f32_16x16x32_bf16 v[68:71], v[156:159], v[204:207], v[68:71]
	v_mfma_f32_16x16x32_bf16 v[64:67], v[166:169], v[204:207], v[64:67]
	v_mfma_f32_16x16x32_bf16 v[132:135], v[160:163], v[184:187], v[132:135]
	v_mfma_f32_16x16x32_bf16 v[128:131], v[170:173], v[184:187], v[128:131]
	v_mfma_f32_16x16x32_bf16 v[116:119], v[160:163], v[192:195], v[116:119]
	v_mfma_f32_16x16x32_bf16 v[104:107], v[170:173], v[192:195], v[104:107]
	v_mfma_f32_16x16x32_bf16 v[84:87], v[160:163], v[200:203], v[84:87]
	v_mfma_f32_16x16x32_bf16 v[80:83], v[170:173], v[200:203], v[80:83]
	v_mfma_f32_16x16x32_bf16 v[68:71], v[160:163], v[208:211], v[68:71]
	v_mfma_f32_16x16x32_bf16 v[64:67], v[170:173], v[208:211], v[64:67]
	s_barrier
	s_add_i32 s34, s74, s61
	v_lshl_add_u64 v[212:213], s[56:57], 0, v[146:147]
	s_mov_b32 m0, s34
	ds_read_b128 v[180:183], v179 offset:16384
	ds_read_b128 v[184:187], v179 offset:17408
	ds_read_b128 v[188:191], v179 offset:18432
	ds_read_b128 v[192:195], v179 offset:19456
	ds_read_b128 v[196:199], v179 offset:20480
	ds_read_b128 v[200:203], v179 offset:21504
	ds_read_b128 v[204:207], v179 offset:22528
	ds_read_b128 v[208:211], v179 offset:23552
	global_load_lds_dwordx4 v[212:213], off
	s_add_i32 m0, s34, 0x2000
	s_add_u32 s34, s56, 0x200000
	v_lshl_add_u64 v[214:215], s[56:57], 0, v[150:151]
	s_addc_u32 s35, s57, 0
	s_add_i32 s82, s75, s61
	global_load_lds_dwordx4 v[214:215], off
	v_lshl_add_u64 v[216:217], s[34:35], 0, v[146:147]
	s_mov_b32 m0, s82
	s_nop 0
	global_load_lds_dwordx4 v[216:217], off
	v_lshl_add_u64 v[216:217], s[34:35], 0, v[150:151]
	s_add_i32 m0, s82, 0x2000
	s_nop 0
	global_load_lds_dwordx4 v[216:217], off
	v_lshl_add_u64 v[216:217], s[6:7], 0, v[144:145]
	s_mov_b32 m0, s62
	v_lshl_add_u64 v[218:219], v[216:217], 0, s[26:27]
	global_load_lds_dwordx4 v[216:217], off
	s_mov_b32 m0, s63
	s_nop 0
	global_load_lds_dwordx4 v[218:219], off
	s_waitcnt vmcnt(8)
	s_waitcnt lgkmcnt(0)
	s_barrier
; #define PG8_STAGE(bufoff, gbase, voff) do { _Pragma("unroll") for (int _i = 0; _i < 2; ++_i) \
;         __builtin_amdgcn_global_load_lds((const unsigned*)((const char*)(gbase) + (voff)[_i]), (PG8_LAS unsigned*)(lds + (bufoff) + ldsw + _i * 8192), 16, 0, 0); } while (0)
; #define PG8_LDA(dst, b, h) do { _Pragma("unroll") for (int m = 0; m < 4; ++m) _Pragma("unroll") for (int k = 0; k < 2; ++k) dst[m][k] = *(const PG8_LAS bf16x8*)(lds + PG8_SA(b, h) + aoff + m * 2048 + k * 1024); } while (0)
; #define PG8_LDB(dst, b, h) do { _Pragma("unroll") for (int n = 0; n < 2; ++n) _Pragma("unroll") for (int k = 0; k < 2; ++k) dst[n][k] = *(const PG8_LAS bf16x8*)(lds + PG8_SB(b, h) + boff + n * 2048 + k * 1024); } while (0)
; #define PG8_MMA(ai, bj, At, Bt) do { __builtin_amdgcn_s_setprio(1); _Pragma("unroll") for (int m = 0; m < 4; ++m) _Pragma("unroll") for (int n = 0; n < 2; ++n) _Pragma("unroll") for (int k = 0; k < 2; ++k) \
;         acc[ai][bj][m][n] = __builtin_amdgcn_mfma_f32_16x16x32_bf16(Bt[n][k], At[m][k], acc[ai][bj][m][n], 0, 0, 0); __builtin_amdgcn_s_setprio(0); } while (0)
; #define PG8_WAIT_V(n) asm volatile("s_waitcnt vmcnt(" #n ")" ::: "memory")
; #define PG8_WAIT_L(n) asm volatile("s_waitcnt lgkmcnt(" #n ")" ::: "memory")
; #define PG8_BAR __builtin_amdgcn_s_barrier()
; #define PG8_SCHED __builtin_amdgcn_sched_barrier(0)
; template <class Epi, class Sched, bool ALIGN_EPI = false, bool SP2 = false>
; __device__ __forceinline__ void gemm_phase(PG8_LAS unsigned char* lds, const Gemm g, const Sched& S, const Epi& E) {
;     ...
;             PG8_WAIT_V(8); PG8_WAIT_L(0); PG8_BAR; PG8_MMA(1, 0, At, B0); PG8_MMA(1, 1, At, B1); PG8_BAR; PG8_SCHED;
;             PG8_LDB(B0, 1, 0); PG8_LDB(B1, 1, 1); PG8_SCHED; PG8_LDA(At, 1, 0); PG8_STAGE(PG8_SA(0, 1), a2 + hstepA, voffA);
;             PG8_WAIT_V(8); PG8_WAIT_L(0); PG8_BAR; PG8_MMA(0, 0, At, B0); PG8_MMA(0, 1, At, B1); PG8_BAR; PG8_SCHED;
	s_waitcnt lgkmcnt(0)
	v_mfma_f32_16x16x32_bf16 v[60:63], v[88:91], v[180:183], v[60:63]
	v_mfma_f32_16x16x32_bf16 v[56:59], v[108:111], v[180:183], v[56:59]
	v_mfma_f32_16x16x32_bf16 v[44:47], v[88:91], v[188:191], v[44:47]
	v_mfma_f32_16x16x32_bf16 v[40:43], v[108:111], v[188:191], v[40:43]
	v_mfma_f32_16x16x32_bf16 v[28:31], v[88:91], v[196:199], v[28:31]
	v_mfma_f32_16x16x32_bf16 v[24:27], v[108:111], v[196:199], v[24:27]
	v_mfma_f32_16x16x32_bf16 v[12:15], v[88:91], v[204:207], v[12:15]
	v_mfma_f32_16x16x32_bf16 v[8:11], v[108:111], v[204:207], v[8:11]
	v_mfma_f32_16x16x32_bf16 v[60:63], v[96:99], v[184:187], v[60:63]
	v_mfma_f32_16x16x32_bf16 v[56:59], v[112:115], v[184:187], v[56:59]
	v_mfma_f32_16x16x32_bf16 v[44:47], v[96:99], v[192:195], v[44:47]
	v_mfma_f32_16x16x32_bf16 v[40:43], v[112:115], v[192:195], v[40:43]
	v_mfma_f32_16x16x32_bf16 v[28:31], v[96:99], v[200:203], v[28:31]
	v_mfma_f32_16x16x32_bf16 v[24:27], v[112:115], v[200:203], v[24:27]
	v_mfma_f32_16x16x32_bf16 v[12:15], v[96:99], v[208:211], v[12:15]
	v_mfma_f32_16x16x32_bf16 v[8:11], v[112:115], v[208:211], v[8:11]
	v_mfma_f32_16x16x32_bf16 v[52:55], v[156:159], v[180:183], v[52:55]
	v_mfma_f32_16x16x32_bf16 v[48:51], v[166:169], v[180:183], v[48:51]
	v_mfma_f32_16x16x32_bf16 v[36:39], v[156:159], v[188:191], v[36:39]
	v_mfma_f32_16x16x32_bf16 v[32:35], v[166:169], v[188:191], v[32:35]
	v_mfma_f32_16x16x32_bf16 v[20:23], v[156:159], v[196:199], v[20:23]
	v_mfma_f32_16x16x32_bf16 v[16:19], v[166:169], v[196:199], v[16:19]
	v_mfma_f32_16x16x32_bf16 v[4:7], v[156:159], v[204:207], v[4:7]
	v_mfma_f32_16x16x32_bf16 v[0:3], v[166:169], v[204:207], v[0:3]
	v_mfma_f32_16x16x32_bf16 v[52:55], v[160:163], v[184:187], v[52:55]
	v_mfma_f32_16x16x32_bf16 v[48:51], v[170:173], v[184:187], v[48:51]
	v_mfma_f32_16x16x32_bf16 v[36:39], v[160:163], v[192:195], v[36:39]
	v_mfma_f32_16x16x32_bf16 v[32:35], v[170:173], v[192:195], v[32:35]
	v_mfma_f32_16x16x32_bf16 v[20:23], v[160:163], v[200:203], v[20:23]
	v_mfma_f32_16x16x32_bf16 v[16:19], v[170:173], v[200:203], v[16:19]
	v_mfma_f32_16x16x32_bf16 v[4:7], v[160:163], v[208:211], v[4:7]
	v_mfma_f32_16x16x32_bf16 v[0:3], v[170:173], v[208:211], v[0:3]
	s_barrier
	s_add_i32 s6, 0, 0x18000
	s_add_i32 s34, 0, 0x1c000
	v_add_u32_e32 v112, s6, v175
	v_add_u32_e32 v148, s34, v175
	ds_read_b128 v[88:91], v112
	ds_read_b128 v[96:99], v112 offset:1024
	ds_read_b128 v[108:111], v112 offset:2048
	ds_read_b128 v[112:115], v112 offset:3072
	ds_read_b128 v[156:159], v148
	ds_read_b128 v[160:163], v148 offset:1024
	ds_read_b128 v[166:169], v148 offset:2048
	ds_read_b128 v[170:173], v148 offset:3072
	s_mov_b32 m0, s64
	v_lshl_add_u64 v[218:219], v[216:217], 0, s[12:13]
	ds_read_b128 v[180:183], v179 offset:32768
	ds_read_b128 v[184:187], v179 offset:33792
	ds_read_b128 v[188:191], v179 offset:34816
	ds_read_b128 v[192:195], v179 offset:35840
	ds_read_b128 v[196:199], v179 offset:36864
	ds_read_b128 v[200:203], v179 offset:37888
	ds_read_b128 v[204:207], v179 offset:38912
	ds_read_b128 v[208:211], v179 offset:39936
	global_load_lds_dwordx4 v[218:219], off
	v_lshl_add_u64 v[218:219], v[216:217], 0, s[36:37]
	s_mov_b32 m0, s65
	s_nop 0
	global_load_lds_dwordx4 v[218:219], off
	s_waitcnt vmcnt(8)
	s_waitcnt lgkmcnt(0)
	s_barrier
	s_waitcnt lgkmcnt(0)
	v_mfma_f32_16x16x32_bf16 v[140:143], v[88:91], v[180:183], v[140:143]
	v_mfma_f32_16x16x32_bf16 v[136:139], v[108:111], v[180:183], v[136:139]
	v_mfma_f32_16x16x32_bf16 v[124:127], v[88:91], v[188:191], v[124:127]
	v_mfma_f32_16x16x32_bf16 v[120:123], v[108:111], v[188:191], v[120:123]
	v_mfma_f32_16x16x32_bf16 v[100:103], v[88:91], v[196:199], v[100:103]
	v_mfma_f32_16x16x32_bf16 v[92:95], v[108:111], v[196:199], v[92:95]
	v_mfma_f32_16x16x32_bf16 v[76:79], v[88:91], v[204:207], v[76:79]
	v_mfma_f32_16x16x32_bf16 v[72:75], v[108:111], v[204:207], v[72:75]
	v_mfma_f32_16x16x32_bf16 v[140:143], v[96:99], v[184:187], v[140:143]
	v_mfma_f32_16x16x32_bf16 v[136:139], v[112:115], v[184:187], v[136:139]
	v_mfma_f32_16x16x32_bf16 v[124:127], v[96:99], v[192:195], v[124:127]
	v_mfma_f32_16x16x32_bf16 v[120:123], v[112:115], v[192:195], v[120:123]
	v_mfma_f32_16x16x32_bf16 v[100:103], v[96:99], v[200:203], v[100:103]
	v_mfma_f32_16x16x32_bf16 v[92:95], v[112:115], v[200:203], v[92:95]
	v_mfma_f32_16x16x32_bf16 v[76:79], v[96:99], v[208:211], v[76:79]
	v_mfma_f32_16x16x32_bf16 v[72:75], v[112:115], v[208:211], v[72:75]
	v_mfma_f32_16x16x32_bf16 v[132:135], v[156:159], v[180:183], v[132:135]
	v_mfma_f32_16x16x32_bf16 v[128:131], v[166:169], v[180:183], v[128:131]
	v_mfma_f32_16x16x32_bf16 v[116:119], v[156:159], v[188:191], v[116:119]
	v_mfma_f32_16x16x32_bf16 v[104:107], v[166:169], v[188:191], v[104:107]
	v_mfma_f32_16x16x32_bf16 v[84:87], v[156:159], v[196:199], v[84:87]
	v_mfma_f32_16x16x32_bf16 v[80:83], v[166:169], v[196:199], v[80:83]
	v_mfma_f32_16x16x32_bf16 v[68:71], v[156:159], v[204:207], v[68:71]
	v_mfma_f32_16x16x32_bf16 v[64:67], v[166:169], v[204:207], v[64:67]
	v_mfma_f32_16x16x32_bf16 v[132:135], v[160:163], v[184:187], v[132:135]
	v_mfma_f32_16x16x32_bf16 v[128:131], v[170:173], v[184:187], v[128:131]
	v_mfma_f32_16x16x32_bf16 v[116:119], v[160:163], v[192:195], v[116:119]
	v_mfma_f32_16x16x32_bf16 v[104:107], v[170:173], v[192:195], v[104:107]
	v_mfma_f32_16x16x32_bf16 v[84:87], v[160:163], v[200:203], v[84:87]
	v_mfma_f32_16x16x32_bf16 v[80:83], v[170:173], v[200:203], v[80:83]
	v_mfma_f32_16x16x32_bf16 v[68:71], v[160:163], v[208:211], v[68:71]
	v_mfma_f32_16x16x32_bf16 v[64:67], v[170:173], v[208:211], v[64:67]
	s_barrier
; #define PG8_STAGE(bufoff, gbase, voff) do { _Pragma("unroll") for (int _i = 0; _i < 2; ++_i) \
;         __builtin_amdgcn_global_load_lds((const unsigned*)((const char*)(gbase) + (voff)[_i]), (PG8_LAS unsigned*)(lds + (bufoff) + ldsw + _i * 8192), 16, 0, 0); } while (0)
; #define PG8_LDA(dst, b, h) do { _Pragma("unroll") for (int m = 0; m < 4; ++m) _Pragma("unroll") for (int k = 0; k < 2; ++k) dst[m][k] = *(const PG8_LAS bf16x8*)(lds + PG8_SA(b, h) + aoff + m * 2048 + k * 1024); } while (0)
; #define PG8_MMA(ai, bj, At, Bt) do { __builtin_amdgcn_s_setprio(1); _Pragma("unroll") for (int m = 0; m < 4; ++m) _Pragma("unroll") for (int n = 0; n < 2; ++n) _Pragma("unroll") for (int k = 0; k < 2; ++k) \
;         acc[ai][bj][m][n] = __builtin_amdgcn_mfma_f32_16x16x32_bf16(Bt[n][k], At[m][k], acc[ai][bj][m][n], 0, 0, 0); __builtin_amdgcn_s_setprio(0); } while (0)
; #define PG8_WAIT_V(n) asm volatile("s_waitcnt vmcnt(" #n ")" ::: "memory")
; #define PG8_WAIT_L(n) asm volatile("s_waitcnt lgkmcnt(" #n ")" ::: "memory")
; #define PG8_BAR __builtin_amdgcn_s_barrier()
; #define PG8_SCHED __builtin_amdgcn_sched_barrier(0)
; template <class Epi, class Sched, bool ALIGN_EPI = false, bool SP2 = false>
; __device__ __forceinline__ void gemm_phase(PG8_LAS unsigned char* lds, const Gemm g, const Sched& S, const Epi& E) {
;     ...
;         for (int t = 0; t < nt; t += 2) {
;             const bool last = (t == nt - 2);
;     ...
;             PG8_LDA(At, 1, 1); PG8_STAGE(PG8_SB(1, 0), b3, voffB); PG8_STAGE(PG8_SB(1, 1), b3 + hstepB, voffB); PG8_STAGE(PG8_SA(1, 0), a3, voffA);
;             PG8_WAIT_V(8); PG8_WAIT_L(0); PG8_BAR; PG8_MMA(1, 0, At, B0); PG8_MMA(1, 1, At, B1); PG8_BAR; PG8_SCHED;
	s_add_i32 s6, s6, s61
	v_lshl_add_u64 v[212:213], v[212:213], 0, s[16:17]
	s_mov_b32 m0, s6
	ds_read_b128 v[180:183], v179 offset:49152
	ds_read_b128 v[184:187], v179 offset:50176
	ds_read_b128 v[188:191], v179 offset:51200
	ds_read_b128 v[192:195], v179 offset:52224
	ds_read_b128 v[196:199], v179 offset:53248
	ds_read_b128 v[200:203], v179 offset:54272
	ds_read_b128 v[204:207], v179 offset:55296
	ds_read_b128 v[208:211], v179 offset:56320
	global_load_lds_dwordx4 v[212:213], off
	s_add_i32 m0, s6, 0x2000
	s_add_u32 s6, s56, 0x200080
	v_lshl_add_u64 v[212:213], v[214:215], 0, s[16:17]
	s_addc_u32 s7, s57, 0
	s_add_i32 s34, s34, s61
	global_load_lds_dwordx4 v[212:213], off
	v_lshl_add_u64 v[212:213], s[6:7], 0, v[146:147]
	s_mov_b32 m0, s34
	s_nop 0
	global_load_lds_dwordx4 v[212:213], off
	v_lshl_add_u64 v[212:213], s[6:7], 0, v[150:151]
	s_add_i32 m0, s34, 0x2000
	s_nop 0
	global_load_lds_dwordx4 v[212:213], off
	v_lshl_add_u64 v[212:213], v[216:217], 0, s[18:19]
	s_mov_b32 m0, s69
	s_nop 0
	global_load_lds_dwordx4 v[212:213], off
	v_lshl_add_u64 v[212:213], v[216:217], 0, s[38:39]
	s_mov_b32 m0, s70
	s_nop 0
	global_load_lds_dwordx4 v[212:213], off
	s_waitcnt vmcnt(8)
	s_waitcnt lgkmcnt(0)
	s_barrier
	s_waitcnt lgkmcnt(0)
	v_mfma_f32_16x16x32_bf16 v[60:63], v[88:91], v[180:183], v[60:63]
	v_mfma_f32_16x16x32_bf16 v[56:59], v[108:111], v[180:183], v[56:59]
	v_mfma_f32_16x16x32_bf16 v[44:47], v[88:91], v[188:191], v[44:47]
	v_mfma_f32_16x16x32_bf16 v[40:43], v[108:111], v[188:191], v[40:43]
	v_mfma_f32_16x16x32_bf16 v[28:31], v[88:91], v[196:199], v[28:31]
	v_mfma_f32_16x16x32_bf16 v[24:27], v[108:111], v[196:199], v[24:27]
	v_mfma_f32_16x16x32_bf16 v[12:15], v[88:91], v[204:207], v[12:15]
	v_mfma_f32_16x16x32_bf16 v[8:11], v[108:111], v[204:207], v[8:11]
	v_mfma_f32_16x16x32_bf16 v[60:63], v[96:99], v[184:187], v[60:63]
	v_mfma_f32_16x16x32_bf16 v[56:59], v[112:115], v[184:187], v[56:59]
	v_mfma_f32_16x16x32_bf16 v[44:47], v[96:99], v[192:195], v[44:47]
	v_mfma_f32_16x16x32_bf16 v[40:43], v[112:115], v[192:195], v[40:43]
	v_mfma_f32_16x16x32_bf16 v[28:31], v[96:99], v[200:203], v[28:31]
	v_mfma_f32_16x16x32_bf16 v[24:27], v[112:115], v[200:203], v[24:27]
	v_mfma_f32_16x16x32_bf16 v[12:15], v[96:99], v[208:211], v[12:15]
	v_mfma_f32_16x16x32_bf16 v[8:11], v[112:115], v[208:211], v[8:11]
	v_mfma_f32_16x16x32_bf16 v[52:55], v[156:159], v[180:183], v[52:55]
	v_mfma_f32_16x16x32_bf16 v[48:51], v[166:169], v[180:183], v[48:51]
	v_mfma_f32_16x16x32_bf16 v[36:39], v[156:159], v[188:191], v[36:39]
	v_mfma_f32_16x16x32_bf16 v[32:35], v[166:169], v[188:191], v[32:35]
	v_mfma_f32_16x16x32_bf16 v[20:23], v[156:159], v[196:199], v[20:23]
	v_mfma_f32_16x16x32_bf16 v[16:19], v[166:169], v[196:199], v[16:19]
	v_mfma_f32_16x16x32_bf16 v[4:7], v[156:159], v[204:207], v[4:7]
	v_mfma_f32_16x16x32_bf16 v[0:3], v[166:169], v[204:207], v[0:3]
	v_mfma_f32_16x16x32_bf16 v[52:55], v[160:163], v[184:187], v[52:55]
	v_mfma_f32_16x16x32_bf16 v[48:51], v[170:173], v[184:187], v[48:51]
	v_mfma_f32_16x16x32_bf16 v[36:39], v[160:163], v[192:195], v[36:39]
	v_mfma_f32_16x16x32_bf16 v[32:35], v[170:173], v[192:195], v[32:35]
	v_mfma_f32_16x16x32_bf16 v[20:23], v[160:163], v[200:203], v[20:23]
	v_mfma_f32_16x16x32_bf16 v[16:19], v[170:173], v[200:203], v[16:19]
	v_mfma_f32_16x16x32_bf16 v[4:7], v[160:163], v[208:211], v[4:7]
	v_mfma_f32_16x16x32_bf16 v[0:3], v[170:173], v[208:211], v[0:3]
	s_barrier
	s_add_i32 s9, s9, 2
	s_add_u32 s80, s80, 0x100
	s_addc_u32 s81, s81, 0
	s_add_u32 s54, s54, 0x8000
	s_addc_u32 s55, s55, 0
	s_cmpk_gt_u32 s9, 0x7d
	s_cbranch_scc0 .LBB0_1705
	s_and_b64 vcc, exec, s[22:23]
	s_cbranch_vccz .LBB0_1708
	s_barrier
